# accumulator zeroing with 64-bit moves in all GEMM instances; tile-boundary wave-group re-sync also in STEP1, STEP2, QKV GEMMs
# speedup vs baseline: 1.0177x; 1.0177x over previous
; template <class Epi, class Sched>
; __device__ __forceinline__ void gemm_phase(LAS unsigned char* lds, const int K, const int lda, const int ldb, const Sched& S, const Epi& E) {
;     ...
;     f32x4 acc[2][2][4][2];
; #pragma unroll
;     for (int a = 0; a < 2; ++a)
; #pragma unroll
;         for (int b = 0; b < 2; ++b)
; #pragma unroll
;             for (int m = 0; m < 4; ++m)
; #pragma unroll
;                 for (int n = 0; n < 2; ++n) acc[a][b][m][n] = (f32x4){0.f, 0.f, 0.f, 0.f};
.LBB0_201:
	s_mov_b64 s[46:47], 0x100
	v_lshl_add_u64 v[138:139], v[2:3], 0, s[46:47]
	v_mov_b32_e32 v2, 0
	s_mov_b32 s39, -2
	v_mov_b32_e32 v3, v2
	v_mov_b32_e32 v4, v2
	v_mov_b32_e32 v5, v2
	v_mov_b32_e32 v6, v2
	v_mov_b32_e32 v7, v2
	v_mov_b32_e32 v8, v2
	v_mov_b32_e32 v9, v2
	v_mov_b32_e32 v10, v2
	v_mov_b32_e32 v11, v2
	v_mov_b32_e32 v12, v2
	v_mov_b32_e32 v13, v2
	v_mov_b32_e32 v14, v2
	v_mov_b32_e32 v15, v2
	v_mov_b32_e32 v16, v2
	v_mov_b32_e32 v17, v2
	v_mov_b32_e32 v26, v2
	v_mov_b32_e32 v27, v2
	v_mov_b32_e32 v28, v2
	v_mov_b32_e32 v29, v2
	v_mov_b32_e32 v30, v2
	v_mov_b32_e32 v31, v2
	v_mov_b32_e32 v32, v2
	v_mov_b32_e32 v33, v2
	s_waitcnt vmcnt(0)
	v_mov_b64_e32 v[42:43], 0
	v_mov_b64_e32 v[44:45], 0
	v_mov_b64_e32 v[46:47], 0
	v_mov_b64_e32 v[48:49], 0
	v_mov_b64_e32 v[18:19], 0
	v_mov_b64_e32 v[20:21], 0
	v_mov_b64_e32 v[22:23], 0
	v_mov_b64_e32 v[24:25], 0
	v_mov_b64_e32 v[34:35], 0
	v_mov_b64_e32 v[36:37], 0
	v_mov_b64_e32 v[38:39], 0
	v_mov_b64_e32 v[40:41], 0
	v_mov_b64_e32 v[50:51], 0
	v_mov_b64_e32 v[52:53], 0
	v_mov_b64_e32 v[54:55], 0
	v_mov_b64_e32 v[56:57], 0
	v_mov_b64_e32 v[58:59], 0
	v_mov_b64_e32 v[60:61], 0
	v_mov_b64_e32 v[62:63], 0
	v_mov_b64_e32 v[64:65], 0
	v_mov_b64_e32 v[66:67], 0
	v_mov_b64_e32 v[68:69], 0
	v_mov_b64_e32 v[70:71], 0
	v_mov_b64_e32 v[72:73], 0
	v_mov_b64_e32 v[74:75], 0
	v_mov_b64_e32 v[76:77], 0
	v_mov_b64_e32 v[78:79], 0
	v_mov_b64_e32 v[80:81], 0
	v_mov_b64_e32 v[86:87], 0
	v_mov_b64_e32 v[88:89], 0
	v_mov_b64_e32 v[94:95], 0
	v_mov_b64_e32 v[96:97], 0
	v_mov_b64_e32 v[102:103], 0
	v_mov_b64_e32 v[104:105], 0
	v_mov_b64_e32 v[110:111], 0
	v_mov_b64_e32 v[112:113], 0
	v_mov_b64_e32 v[82:83], 0
	v_mov_b64_e32 v[84:85], 0
	v_mov_b64_e32 v[90:91], 0
	v_mov_b64_e32 v[92:93], 0
	v_mov_b64_e32 v[98:99], 0
	v_mov_b64_e32 v[100:101], 0
	v_mov_b64_e32 v[106:107], 0
	v_mov_b64_e32 v[108:109], 0
	v_mov_b64_e32 v[114:115], 0
	v_mov_b64_e32 v[116:117], 0
	v_mov_b64_e32 v[118:119], 0
	v_mov_b64_e32 v[120:121], 0
	v_mov_b64_e32 v[122:123], 0
	v_mov_b64_e32 v[124:125], 0
	v_mov_b64_e32 v[126:127], 0
	v_mov_b64_e32 v[128:129], 0
	s_mov_b64 s[40:41], 0xe0000
	s_mov_b64 s[42:43], 0xe0080

; template <class Epi, class Sched>
; __device__ __forceinline__ void gemm_phase(LAS unsigned char* lds, const int K, const int lda, const int ldb, const Sched& S, const Epi& E) {
;     ...
;     f32x4 acc[2][2][4][2];
; #pragma unroll
;     for (int a = 0; a < 2; ++a)
; #pragma unroll
;         for (int b = 0; b < 2; ++b)
; #pragma unroll
;             for (int m = 0; m < 4; ++m)
; #pragma unroll
;                 for (int n = 0; n < 2; ++n) acc[a][b][m][n] = (f32x4){0.f, 0.f, 0.f, 0.f};
.LBB0_255:
	v_mov_b32_e32 v2, 0
	s_mov_b64 s[34:35], 0
	s_mov_b64 s[14:15], -1
	s_mov_b64 s[16:17], 0
	v_mov_b32_e32 v3, v2
	v_mov_b32_e32 v4, v2
	v_mov_b32_e32 v5, v2
	v_mov_b32_e32 v6, v2
	v_mov_b32_e32 v7, v2
	v_mov_b32_e32 v8, v2
	v_mov_b32_e32 v9, v2
	v_mov_b32_e32 v10, v2
	v_mov_b32_e32 v11, v2
	v_mov_b32_e32 v12, v2
	v_mov_b32_e32 v13, v2
	v_mov_b32_e32 v18, v2
	v_mov_b32_e32 v19, v2
	v_mov_b32_e32 v20, v2
	v_mov_b32_e32 v21, v2
	v_mov_b32_e32 v26, v2
	v_mov_b32_e32 v27, v2
	v_mov_b32_e32 v28, v2
	v_mov_b32_e32 v29, v2
	s_waitcnt vmcnt(0)
	v_mov_b64_e32 v[34:35], 0
	v_mov_b64_e32 v[36:37], 0
	v_mov_b64_e32 v[42:43], 0
	v_mov_b64_e32 v[44:45], 0
	v_mov_b64_e32 v[50:51], 0
	v_mov_b64_e32 v[52:53], 0
	v_mov_b64_e32 v[14:15], 0
	v_mov_b64_e32 v[16:17], 0
	v_mov_b64_e32 v[22:23], 0
	v_mov_b64_e32 v[24:25], 0
	v_mov_b64_e32 v[30:31], 0
	v_mov_b64_e32 v[32:33], 0
	v_mov_b64_e32 v[38:39], 0
	v_mov_b64_e32 v[40:41], 0
	v_mov_b64_e32 v[46:47], 0
	v_mov_b64_e32 v[48:49], 0
	v_mov_b64_e32 v[54:55], 0
	v_mov_b64_e32 v[56:57], 0
	v_mov_b64_e32 v[58:59], 0
	v_mov_b64_e32 v[60:61], 0
	v_mov_b64_e32 v[62:63], 0
	v_mov_b64_e32 v[64:65], 0
	v_mov_b64_e32 v[66:67], 0
	v_mov_b64_e32 v[68:69], 0
	v_mov_b64_e32 v[70:71], 0
	v_mov_b64_e32 v[72:73], 0
	v_mov_b64_e32 v[74:75], 0
	v_mov_b64_e32 v[76:77], 0
	v_mov_b64_e32 v[82:83], 0
	v_mov_b64_e32 v[84:85], 0
	v_mov_b64_e32 v[90:91], 0
	v_mov_b64_e32 v[92:93], 0
	v_mov_b64_e32 v[98:99], 0
	v_mov_b64_e32 v[100:101], 0
	v_mov_b64_e32 v[106:107], 0
	v_mov_b64_e32 v[108:109], 0
	v_mov_b64_e32 v[114:115], 0
	v_mov_b64_e32 v[116:117], 0
	v_mov_b64_e32 v[78:79], 0
	v_mov_b64_e32 v[80:81], 0
	v_mov_b64_e32 v[86:87], 0
	v_mov_b64_e32 v[88:89], 0
	v_mov_b64_e32 v[94:95], 0
	v_mov_b64_e32 v[96:97], 0
	v_mov_b64_e32 v[102:103], 0
	v_mov_b64_e32 v[104:105], 0
	v_mov_b64_e32 v[110:111], 0
	v_mov_b64_e32 v[112:113], 0
	v_mov_b64_e32 v[118:119], 0
	v_mov_b64_e32 v[120:121], 0
	v_mov_b64_e32 v[122:123], 0
	v_mov_b64_e32 v[124:125], 0
	v_mov_b64_e32 v[126:127], 0
	v_mov_b64_e32 v[128:129], 0

; template <class Epi, class Sched>
; __device__ __forceinline__ void gemm_phase(LAS unsigned char* lds, const int K, const int lda, const int ldb, const Sched& S, const Epi& E) {
;     ...
;     f32x4 acc[2][2][4][2];
; #pragma unroll
;     for (int a = 0; a < 2; ++a)
; #pragma unroll
;         for (int b = 0; b < 2; ++b)
; #pragma unroll
;             for (int m = 0; m < 4; ++m)
; #pragma unroll
;                 for (int n = 0; n < 2; ++n) acc[a][b][m][n] = (f32x4){0.f, 0.f, 0.f, 0.f};
.LBB0_269:
	s_add_u32 s10, s10, 0x20080
	s_addc_u32 s11, s11, 0
	s_add_u32 s41, s12, 0x100
	v_mov_b32_e32 v2, 0
	s_addc_u32 s42, s13, 0
	s_mov_b32 s43, -2
	v_mov_b32_e32 v3, v2
	v_mov_b32_e32 v4, v2
	v_mov_b32_e32 v5, v2
	v_mov_b32_e32 v30, v2
	v_mov_b32_e32 v31, v2
	v_mov_b32_e32 v32, v2
	v_mov_b32_e32 v33, v2
	v_mov_b32_e32 v6, v2
	v_mov_b32_e32 v7, v2
	v_mov_b32_e32 v8, v2
	v_mov_b32_e32 v9, v2
	s_waitcnt vmcnt(0)
	v_mov_b64_e32 v[38:39], 0
	v_mov_b64_e32 v[40:41], 0
	v_mov_b64_e32 v[10:11], 0
	v_mov_b64_e32 v[12:13], 0
	v_mov_b64_e32 v[42:43], 0
	v_mov_b64_e32 v[44:45], 0
	v_mov_b64_e32 v[14:15], 0
	v_mov_b64_e32 v[16:17], 0
	v_mov_b64_e32 v[46:47], 0
	v_mov_b64_e32 v[48:49], 0
	v_mov_b64_e32 v[62:63], 0
	v_mov_b64_e32 v[64:65], 0
	v_mov_b64_e32 v[94:95], 0
	v_mov_b64_e32 v[96:97], 0
	v_mov_b64_e32 v[70:71], 0
	v_mov_b64_e32 v[72:73], 0
	v_mov_b64_e32 v[102:103], 0
	v_mov_b64_e32 v[104:105], 0
	v_mov_b64_e32 v[74:75], 0
	v_mov_b64_e32 v[76:77], 0
	v_mov_b64_e32 v[106:107], 0
	v_mov_b64_e32 v[108:109], 0
	v_mov_b64_e32 v[78:79], 0
	v_mov_b64_e32 v[80:81], 0
	v_mov_b64_e32 v[110:111], 0
	v_mov_b64_e32 v[112:113], 0
	v_mov_b64_e32 v[18:19], 0
	v_mov_b64_e32 v[20:21], 0
	v_mov_b64_e32 v[50:51], 0
	v_mov_b64_e32 v[52:53], 0
	v_mov_b64_e32 v[22:23], 0
	v_mov_b64_e32 v[24:25], 0
	v_mov_b64_e32 v[54:55], 0
	v_mov_b64_e32 v[56:57], 0
	v_mov_b64_e32 v[26:27], 0
	v_mov_b64_e32 v[28:29], 0
	v_mov_b64_e32 v[58:59], 0
	v_mov_b64_e32 v[60:61], 0
	v_mov_b64_e32 v[34:35], 0
	v_mov_b64_e32 v[36:37], 0
	v_mov_b64_e32 v[66:67], 0
	v_mov_b64_e32 v[68:69], 0
	v_mov_b64_e32 v[82:83], 0
	v_mov_b64_e32 v[84:85], 0
	v_mov_b64_e32 v[114:115], 0
	v_mov_b64_e32 v[116:117], 0
	v_mov_b64_e32 v[86:87], 0
	v_mov_b64_e32 v[88:89], 0
	v_mov_b64_e32 v[118:119], 0
	v_mov_b64_e32 v[120:121], 0
	v_mov_b64_e32 v[90:91], 0
	v_mov_b64_e32 v[92:93], 0
	v_mov_b64_e32 v[122:123], 0
	v_mov_b64_e32 v[124:125], 0
	v_mov_b64_e32 v[98:99], 0
	v_mov_b64_e32 v[100:101], 0
	v_mov_b64_e32 v[126:127], 0
	v_mov_b64_e32 v[128:129], 0

; #define PG8_STAGE(bufoff, gbase, voff) do { _Pragma("unroll") for (int _i = 0; _i < 2; ++_i) \
;         __builtin_amdgcn_global_load_lds((const unsigned*)((const char*)(gbase) + (voff)[_i]), (LAS unsigned*)(lds + (bufoff) + ldsw + _i * 8192), 16, 0, 0); } while (0)
; #define PG8_STAGE_A(bufoff, gbase, h, vv) do { if constexpr (GATHER) { _Pragma("unroll") for (int _i = 0; _i < 2; ++_i) \
;         __builtin_amdgcn_global_load_lds((const unsigned*)((const char*)(gbase) + (vv)[h][_i]), (LAS unsigned*)(lds + (bufoff) + ldsw + _i * 8192), 16, 0, 0); } \
;         else { PG8_STAGE(bufoff, (gbase) + (h) * hstepA, voffA); } } while (0)
; #define PG8_LDA(dst, b, h) do { _Pragma("unroll") for (int m = 0; m < 4; ++m) _Pragma("unroll") for (int k = 0; k < 2; ++k) dst[m][k] = *(const LAS bf16x8*)(lds + PG8_SA(b, h) + aoff + m * 2048 + k * 1024); } while (0)
; #define PG8_WAIT_V(n) asm volatile("s_waitcnt vmcnt(" #n ")" ::: "memory")
; #define PG8_WAIT_L(n) asm volatile("s_waitcnt lgkmcnt(" #n ")" ::: "memory")
; template <class Epi, class Sched>
; __device__ __forceinline__ void gemm_phase(LAS unsigned char* lds, const int K, const int lda, const int ldb, const Sched& S, const Epi& E) {
;     ...
;         for (int t = 0; t < nt; t += 2) {
;             const bool last = (t == nt - 2);
;             const char* a1 = cA + (size_t)(t + 1) * kstep;
;             const char* a2 = last ? nA : cA + (size_t)(t + 2) * kstep; const char* b2 = last ? nB : cB + (size_t)(t + 2) * kstep;
;             const char* a3 = a2 + kstep; const char* b3 = b2 + kstep;
;             PG8_LDB(B0, 0, 0); PG8_SCHED; PG8_LDA(At, 0, 0); PG8_STAGE_A(PG8_SA(1, 1), a1, 1, vcur);
;             if constexpr (GATHER) { if (last) {
; #pragma unroll
;                 for (int h = 0; h < 2; ++h)
; #pragma unroll
;                     for (int i = 0; i < 2; ++i) vcur[h][i] = vnxt[h][i]; } }
;             PG8_WAIT_L(8); PG8_BAR; PG8_WAIT_L(0); PG8_MMA(0, 0, At, B0); PG8_BAR; PG8_SCHED;
;             PG8_LDB(B1, 0, 1); PG8_STAGE(PG8_SB(0, 0), b2, voffB);
;             PG8_BAR; PG8_WAIT_L(0); PG8_MMA(0, 1, At, B1); PG8_BAR;
;             PG8_LDA(At, 0, 1); PG8_STAGE_A(PG8_SA(0, 0), a2, 0, vcur);
;             PG8_BAR; PG8_WAIT_L(0); PG8_MMA(1, 0, At, B0); PG8_BAR; PG8_SCHED;
;             PG8_STAGE(PG8_SB(0, 1), b2 + hstepB, voffB);
;             PG8_WAIT_V(6); PG8_BAR; PG8_MMA(1, 1, At, B1); PG8_BAR;
.LBB0_286:
	s_add_u32 s11, s6, s42
	s_addc_u32 s13, s7, s43
	s_add_u32 s20, s11, 0x100
	s_addc_u32 s21, s13, 0
	s_and_b64 s[2:3], s[40:41], exec
	s_cselect_b32 s49, s35, s21
	s_cselect_b32 s48, s34, s20
	s_add_u32 s2, s8, s42
	s_addc_u32 s3, s9, s43
	s_add_u32 s20, s2, 0x100
	s_addc_u32 s21, s3, 0
	s_add_i32 s50, 0, 0x10000
	s_and_b64 s[2:3], s[40:41], exec
	s_cselect_b32 s3, s37, s21
	s_cselect_b32 s2, s36, s20
	s_add_u32 s20, s11, 0x10080
	s_addc_u32 s21, s13, 0
	s_add_i32 s57, s50, s19
	s_add_i32 m0, s30, 0xc000
	s_add_i32 s51, s30, 0xe000
	s_add_i32 s56, 0, 0x14000
	s_add_i32 s66, s57, 0x2000
	s_add_u32 s46, s2, 0x10000
	v_add_u32_e32 v146, s50, v132
	s_addc_u32 s47, s3, 0
	s_add_i32 s67, s56, s19
	ds_read_b128 v[134:137], v146
	ds_read_b128 v[138:141], v146 offset:1024
	ds_read_b128 v[142:145], v146 offset:2048
	ds_read_b128 v[150:153], v146 offset:3072
	s_add_i32 s68, s67, 0x2000
	s_add_i32 s69, 0, 0x18000
	s_add_u32 s42, s48, 0x10000
	s_addc_u32 s43, s49, 0
	s_add_i32 s70, s69, s19
	s_add_i32 s63, 0, 0x1c000
	s_add_i32 s62, s70, 0x2000
	s_add_u32 s40, s2, 0x10080
	s_addc_u32 s41, s3, 0
	s_add_i32 s13, s63, s19
	s_add_i32 s11, s13, 0x2000
	v_lshl_add_u64 v[146:147], s[20:21], 0, v[0:1]
	ds_read_b128 v[154:157], v133
	ds_read_b128 v[158:161], v133 offset:1024
	ds_read_b128 v[162:165], v133 offset:2048
	ds_read_b128 v[166:169], v133 offset:3072
	ds_read_b128 v[170:173], v133 offset:4096
	ds_read_b128 v[174:177], v133 offset:5120
	ds_read_b128 v[178:181], v133 offset:6144
	ds_read_b128 v[186:189], v133 offset:7168
	global_load_lds_dwordx4 v[146:147], off
	v_lshl_add_u64 v[146:147], s[20:21], 0, v[130:131]
	s_mov_b32 m0, s51
	s_nop 0
	global_load_lds_dwordx4 v[146:147], off
	s_waitcnt lgkmcnt(8)
	s_barrier
	s_waitcnt lgkmcnt(0)
	s_setprio 1
	s_waitcnt lgkmcnt(0)
	v_mfma_f32_16x16x32_bf16 v[126:129], v[134:137], v[154:157], v[126:129]
	v_mfma_f32_16x16x32_bf16 v[98:101], v[142:145], v[154:157], v[98:101]
	v_mfma_f32_16x16x32_bf16 v[122:125], v[134:137], v[162:165], v[122:125]
	v_mfma_f32_16x16x32_bf16 v[94:97], v[142:145], v[162:165], v[94:97]
	v_mfma_f32_16x16x32_bf16 v[118:121], v[134:137], v[170:173], v[118:121]
	v_mfma_f32_16x16x32_bf16 v[78:81], v[142:145], v[170:173], v[78:81]
	v_mfma_f32_16x16x32_bf16 v[106:109], v[134:137], v[178:181], v[106:109]
	v_mfma_f32_16x16x32_bf16 v[74:77], v[142:145], v[178:181], v[74:77]
	v_mfma_f32_16x16x32_bf16 v[126:129], v[138:141], v[158:161], v[126:129]
	v_mfma_f32_16x16x32_bf16 v[98:101], v[150:153], v[158:161], v[98:101]
	v_mfma_f32_16x16x32_bf16 v[122:125], v[138:141], v[166:169], v[122:125]
	v_mfma_f32_16x16x32_bf16 v[94:97], v[150:153], v[166:169], v[94:97]
	v_mfma_f32_16x16x32_bf16 v[118:121], v[138:141], v[174:177], v[118:121]
	v_mfma_f32_16x16x32_bf16 v[78:81], v[150:153], v[174:177], v[78:81]
	v_mfma_f32_16x16x32_bf16 v[106:109], v[138:141], v[186:189], v[106:109]
	v_mfma_f32_16x16x32_bf16 v[74:77], v[150:153], v[186:189], v[74:77]
	s_setprio 0
	s_barrier
	v_add_u32_e32 v146, s56, v132
	s_mov_b32 m0, s57
	ds_read_b128 v[190:193], v146
	ds_read_b128 v[216:219], v146 offset:1024
	ds_read_b128 v[220:223], v146 offset:2048
	ds_read_b128 v[224:227], v146 offset:3072
	v_lshl_add_u64 v[146:147], s[2:3], 0, v[0:1]
	global_load_lds_dwordx4 v[146:147], off
	v_lshl_add_u64 v[182:183], s[2:3], 0, v[130:131]
	s_mov_b32 m0, s66
	s_nop 0
	global_load_lds_dwordx4 v[182:183], off
	s_barrier
	s_waitcnt lgkmcnt(0)
	s_setprio 1
	s_waitcnt lgkmcnt(0)
	v_mfma_f32_16x16x32_bf16 v[62:65], v[190:193], v[154:157], v[62:65]
	v_mfma_f32_16x16x32_bf16 v[114:117], v[220:223], v[154:157], v[114:117]
	v_mfma_f32_16x16x32_bf16 v[54:57], v[190:193], v[162:165], v[54:57]
	v_mfma_f32_16x16x32_bf16 v[30:33], v[220:223], v[162:165], v[30:33]
	v_mfma_f32_16x16x32_bf16 v[46:49], v[190:193], v[170:173], v[46:49]
	v_mfma_f32_16x16x32_bf16 v[110:113], v[220:223], v[170:173], v[110:113]
	v_mfma_f32_16x16x32_bf16 v[42:45], v[190:193], v[178:181], v[42:45]
	v_mfma_f32_16x16x32_bf16 v[22:25], v[220:223], v[178:181], v[22:25]
	v_mfma_f32_16x16x32_bf16 v[62:65], v[216:219], v[158:161], v[62:65]
	v_mfma_f32_16x16x32_bf16 v[114:117], v[224:227], v[158:161], v[114:117]
	v_mfma_f32_16x16x32_bf16 v[54:57], v[216:219], v[166:169], v[54:57]
	v_mfma_f32_16x16x32_bf16 v[30:33], v[224:227], v[166:169], v[30:33]
	v_mfma_f32_16x16x32_bf16 v[46:49], v[216:219], v[174:177], v[46:49]
	v_mfma_f32_16x16x32_bf16 v[110:113], v[224:227], v[174:177], v[110:113]
	v_mfma_f32_16x16x32_bf16 v[42:45], v[216:219], v[186:189], v[42:45]
	v_mfma_f32_16x16x32_bf16 v[22:25], v[224:227], v[186:189], v[22:25]
	s_setprio 0
	s_mov_b32 m0, s30
	v_lshl_add_u64 v[194:195], s[48:49], 0, v[0:1]
	s_barrier
	ds_read_b128 v[154:157], v133 offset:16384
	ds_read_b128 v[158:161], v133 offset:17408
	ds_read_b128 v[162:165], v133 offset:18432
	ds_read_b128 v[166:169], v133 offset:19456
	ds_read_b128 v[170:173], v133 offset:20480
	ds_read_b128 v[174:177], v133 offset:21504
	ds_read_b128 v[178:181], v133 offset:22528
	ds_read_b128 v[186:189], v133 offset:23552
	global_load_lds_dwordx4 v[194:195], off
	v_lshl_add_u64 v[214:215], s[48:49], 0, v[130:131]
	s_mov_b32 m0, s44
	s_nop 0
	global_load_lds_dwordx4 v[214:215], off
	s_barrier
; #define PG8_STAGE(bufoff, gbase, voff) do { _Pragma("unroll") for (int _i = 0; _i < 2; ++_i) \
;         __builtin_amdgcn_global_load_lds((const unsigned*)((const char*)(gbase) + (voff)[_i]), (LAS unsigned*)(lds + (bufoff) + ldsw + _i * 8192), 16, 0, 0); } while (0)
; #define PG8_STAGE_A(bufoff, gbase, h, vv) do { if constexpr (GATHER) { _Pragma("unroll") for (int _i = 0; _i < 2; ++_i) \
;         __builtin_amdgcn_global_load_lds((const unsigned*)((const char*)(gbase) + (vv)[h][_i]), (LAS unsigned*)(lds + (bufoff) + ldsw + _i * 8192), 16, 0, 0); } \
;         else { PG8_STAGE(bufoff, (gbase) + (h) * hstepA, voffA); } } while (0)
; #define PG8_LDA(dst, b, h) do { _Pragma("unroll") for (int m = 0; m < 4; ++m) _Pragma("unroll") for (int k = 0; k < 2; ++k) dst[m][k] = *(const LAS bf16x8*)(lds + PG8_SA(b, h) + aoff + m * 2048 + k * 1024); } while (0)
; #define PG8_LDB(dst, b, h) do { _Pragma("unroll") for (int n = 0; n < 2; ++n) _Pragma("unroll") for (int k = 0; k < 2; ++k) dst[n][k] = *(const LAS bf16x8*)(lds + PG8_SB(b, h) + boff + n * 2048 + k * 1024); } while (0)
; #define PG8_MMA(ai, bj, At, Bt) do { __builtin_amdgcn_s_setprio(1); _Pragma("unroll") for (int m = 0; m < 4; ++m) _Pragma("unroll") for (int n = 0; n < 2; ++n) _Pragma("unroll") for (int k = 0; k < 2; ++k) \
;         acc[ai][bj][m][n] = __builtin_amdgcn_mfma_f32_16x16x32_bf16(Bt[n][k], At[m][k], acc[ai][bj][m][n], 0, 0, 0); __builtin_amdgcn_s_setprio(0); } while (0)
; #define PG8_BAR __builtin_amdgcn_s_barrier()
; template <class Epi, class Sched>
; __device__ __forceinline__ void gemm_phase(LAS unsigned char* lds, const int K, const int lda, const int ldb, const Sched& S, const Epi& E) {
;     ...
;             PG8_WAIT_V(6); PG8_BAR; PG8_MMA(1, 1, At, B1); PG8_BAR;
;             PG8_LDB(B0, 1, 0); PG8_SCHED; PG8_LDA(At, 1, 0); PG8_STAGE_A(PG8_SA(0, 1), a2, 1, vcur);
;             PG8_WAIT_L(8); PG8_BAR; PG8_WAIT_L(0); PG8_MMA(0, 0, At, B0); PG8_BAR; PG8_SCHED;
;             PG8_LDB(B1, 1, 1); PG8_STAGE(PG8_SB(1, 0), b3, voffB);
;             PG8_BAR; PG8_WAIT_L(0); PG8_MMA(0, 1, At, B1); PG8_BAR;
;             PG8_LDA(At, 1, 1); PG8_STAGE_A(PG8_SA(1, 0), a3, 0, vcur);
;             PG8_BAR; PG8_WAIT_L(0); PG8_MMA(1, 0, At, B0); PG8_BAR; PG8_SCHED;
;             PG8_STAGE(PG8_SB(1, 1), b3 + hstepB, voffB);
;             PG8_WAIT_V(6); PG8_BAR; PG8_MMA(1, 1, At, B1); PG8_BAR;
	s_waitcnt lgkmcnt(0)
	s_setprio 1
	s_waitcnt lgkmcnt(0)
	v_mfma_f32_16x16x32_bf16 v[102:105], v[134:137], v[154:157], v[102:105]
	v_mfma_f32_16x16x32_bf16 v[70:73], v[142:145], v[154:157], v[70:73]
	v_mfma_f32_16x16x32_bf16 v[90:93], v[134:137], v[162:165], v[90:93]
	v_mfma_f32_16x16x32_bf16 v[66:69], v[142:145], v[162:165], v[66:69]
	v_mfma_f32_16x16x32_bf16 v[82:85], v[134:137], v[170:173], v[82:85]
	v_mfma_f32_16x16x32_bf16 v[58:61], v[142:145], v[170:173], v[58:61]
	v_mfma_f32_16x16x32_bf16 v[86:89], v[134:137], v[178:181], v[86:89]
	v_mfma_f32_16x16x32_bf16 v[50:53], v[142:145], v[178:181], v[50:53]
	v_mfma_f32_16x16x32_bf16 v[102:105], v[138:141], v[158:161], v[102:105]
	v_mfma_f32_16x16x32_bf16 v[70:73], v[150:153], v[158:161], v[70:73]
	v_mfma_f32_16x16x32_bf16 v[90:93], v[138:141], v[166:169], v[90:93]
	v_mfma_f32_16x16x32_bf16 v[66:69], v[150:153], v[166:169], v[66:69]
	v_mfma_f32_16x16x32_bf16 v[82:85], v[138:141], v[174:177], v[82:85]
	v_mfma_f32_16x16x32_bf16 v[58:61], v[150:153], v[174:177], v[58:61]
	v_mfma_f32_16x16x32_bf16 v[86:89], v[138:141], v[186:189], v[86:89]
	v_mfma_f32_16x16x32_bf16 v[50:53], v[150:153], v[186:189], v[50:53]
	s_setprio 0
	s_barrier
	s_mov_b32 m0, s67
	v_lshl_add_u64 v[134:135], s[46:47], 0, v[0:1]
	global_load_lds_dwordx4 v[134:135], off
	v_lshl_add_u64 v[134:135], s[46:47], 0, v[130:131]
	s_mov_b32 m0, s68
	s_nop 0
	global_load_lds_dwordx4 v[134:135], off
	s_waitcnt vmcnt(6)
	s_barrier
	s_setprio 1
	v_mfma_f32_16x16x32_bf16 v[38:41], v[190:193], v[154:157], v[38:41]
	v_mfma_f32_16x16x32_bf16 v[10:13], v[220:223], v[154:157], v[10:13]
	v_mfma_f32_16x16x32_bf16 v[34:37], v[190:193], v[162:165], v[34:37]
	v_mfma_f32_16x16x32_bf16 v[14:17], v[220:223], v[162:165], v[14:17]
	v_mfma_f32_16x16x32_bf16 v[26:29], v[190:193], v[170:173], v[26:29]
	v_mfma_f32_16x16x32_bf16 v[6:9], v[220:223], v[170:173], v[6:9]
	v_mfma_f32_16x16x32_bf16 v[18:21], v[190:193], v[178:181], v[18:21]
	v_mfma_f32_16x16x32_bf16 v[2:5], v[220:223], v[178:181], v[2:5]
	v_mfma_f32_16x16x32_bf16 v[38:41], v[216:219], v[158:161], v[38:41]
	v_mfma_f32_16x16x32_bf16 v[10:13], v[224:227], v[158:161], v[10:13]
	v_mfma_f32_16x16x32_bf16 v[34:37], v[216:219], v[166:169], v[34:37]
	v_mfma_f32_16x16x32_bf16 v[14:17], v[224:227], v[166:169], v[14:17]
	v_mfma_f32_16x16x32_bf16 v[26:29], v[216:219], v[174:177], v[26:29]
	v_mfma_f32_16x16x32_bf16 v[6:9], v[224:227], v[174:177], v[6:9]
	v_mfma_f32_16x16x32_bf16 v[18:21], v[216:219], v[186:189], v[18:21]
	v_mfma_f32_16x16x32_bf16 v[2:5], v[224:227], v[186:189], v[2:5]
	s_setprio 0
	v_add_u32_e32 v148, s69, v132
	s_barrier
	ds_read_b128 v[134:137], v148
	ds_read_b128 v[138:141], v148 offset:1024
	ds_read_b128 v[142:145], v148 offset:2048
	ds_read_b128 v[150:153], v148 offset:3072
	s_mov_b32 m0, s45
	v_lshl_add_u64 v[190:191], s[42:43], 0, v[0:1]
	ds_read_b128 v[154:157], v133 offset:32768
	ds_read_b128 v[158:161], v133 offset:33792
	ds_read_b128 v[162:165], v133 offset:34816
	ds_read_b128 v[166:169], v133 offset:35840
	ds_read_b128 v[170:173], v133 offset:36864
	ds_read_b128 v[174:177], v133 offset:37888
	ds_read_b128 v[178:181], v133 offset:38912
	ds_read_b128 v[186:189], v133 offset:39936
	global_load_lds_dwordx4 v[190:191], off
	v_lshl_add_u64 v[190:191], s[42:43], 0, v[130:131]
	s_mov_b32 m0, s52
	s_nop 0
	global_load_lds_dwordx4 v[190:191], off
	s_waitcnt lgkmcnt(8)
	s_barrier
	s_waitcnt lgkmcnt(0)
	s_setprio 1
	s_waitcnt lgkmcnt(0)
	v_mfma_f32_16x16x32_bf16 v[126:129], v[134:137], v[154:157], v[126:129]
	v_mfma_f32_16x16x32_bf16 v[98:101], v[142:145], v[154:157], v[98:101]
	v_mfma_f32_16x16x32_bf16 v[122:125], v[134:137], v[162:165], v[122:125]
	v_mfma_f32_16x16x32_bf16 v[94:97], v[142:145], v[162:165], v[94:97]
	v_mfma_f32_16x16x32_bf16 v[118:121], v[134:137], v[170:173], v[118:121]
	v_mfma_f32_16x16x32_bf16 v[78:81], v[142:145], v[170:173], v[78:81]
	v_mfma_f32_16x16x32_bf16 v[106:109], v[134:137], v[178:181], v[106:109]
	v_mfma_f32_16x16x32_bf16 v[74:77], v[142:145], v[178:181], v[74:77]
	v_mfma_f32_16x16x32_bf16 v[126:129], v[138:141], v[158:161], v[126:129]
	v_mfma_f32_16x16x32_bf16 v[98:101], v[150:153], v[158:161], v[98:101]
	v_mfma_f32_16x16x32_bf16 v[122:125], v[138:141], v[166:169], v[122:125]
	v_mfma_f32_16x16x32_bf16 v[94:97], v[150:153], v[166:169], v[94:97]
	v_mfma_f32_16x16x32_bf16 v[118:121], v[138:141], v[174:177], v[118:121]
	v_mfma_f32_16x16x32_bf16 v[78:81], v[150:153], v[174:177], v[78:81]
	v_mfma_f32_16x16x32_bf16 v[106:109], v[138:141], v[186:189], v[106:109]
	v_mfma_f32_16x16x32_bf16 v[74:77], v[150:153], v[186:189], v[74:77]
	s_setprio 0
	s_barrier
	s_mov_b32 m0, s70
	v_add_u32_e32 v148, s63, v132
	v_lshl_add_u64 v[146:147], v[146:147], 0, s[64:65]
	ds_read_b128 v[190:193], v148
	ds_read_b128 v[216:219], v148 offset:1024
	ds_read_b128 v[220:223], v148 offset:2048
	ds_read_b128 v[224:227], v148 offset:3072
	global_load_lds_dwordx4 v[146:147], off
	v_lshl_add_u64 v[146:147], v[182:183], 0, s[64:65]
	s_mov_b32 m0, s62
	s_nop 0
	global_load_lds_dwordx4 v[146:147], off
	s_barrier
; #define PG8_MMA(ai, bj, At, Bt) do { __builtin_amdgcn_s_setprio(1); _Pragma("unroll") for (int m = 0; m < 4; ++m) _Pragma("unroll") for (int n = 0; n < 2; ++n) _Pragma("unroll") for (int k = 0; k < 2; ++k) \
;         acc[ai][bj][m][n] = __builtin_amdgcn_mfma_f32_16x16x32_bf16(Bt[n][k], At[m][k], acc[ai][bj][m][n], 0, 0, 0); __builtin_amdgcn_s_setprio(0); } while (0)
; #define PG8_WAIT_V(n) asm volatile("s_waitcnt vmcnt(" #n ")" ::: "memory")
; #define PG8_BAR __builtin_amdgcn_s_barrier()
; template <class Epi, class Sched>
; __device__ __forceinline__ void gemm_phase(LAS unsigned char* lds, const int K, const int lda, const int ldb, const Sched& S, const Epi& E) {
;     ...
;             PG8_WAIT_V(6); PG8_BAR; PG8_MMA(1, 1, At, B1); PG8_BAR;
;     ...
;         if (!has_next) break;
; #pragma unroll
;         for (int a = 0; a < 2; ++a)
; #pragma unroll
;             for (int b = 0; b < 2; ++b)
; #pragma unroll
;                 for (int m = 0; m < 4; ++m)
; #pragma unroll
;                     for (int n = 0; n < 2; ++n) acc[a][b][m][n] = (f32x4){0.f, 0.f, 0.f, 0.f};
;         cur = nxt; cA = nA; cB = nB; ++ui;
	s_waitcnt lgkmcnt(0)
	s_setprio 1
	s_waitcnt lgkmcnt(0)
	v_mfma_f32_16x16x32_bf16 v[62:65], v[190:193], v[154:157], v[62:65]
	v_mfma_f32_16x16x32_bf16 v[114:117], v[220:223], v[154:157], v[114:117]
	v_mfma_f32_16x16x32_bf16 v[54:57], v[190:193], v[162:165], v[54:57]
	v_mfma_f32_16x16x32_bf16 v[30:33], v[220:223], v[162:165], v[30:33]
	v_mfma_f32_16x16x32_bf16 v[46:49], v[190:193], v[170:173], v[46:49]
	v_mfma_f32_16x16x32_bf16 v[110:113], v[220:223], v[170:173], v[110:113]
	v_mfma_f32_16x16x32_bf16 v[42:45], v[190:193], v[178:181], v[42:45]
	v_mfma_f32_16x16x32_bf16 v[22:25], v[220:223], v[178:181], v[22:25]
	v_mfma_f32_16x16x32_bf16 v[62:65], v[216:219], v[158:161], v[62:65]
	v_mfma_f32_16x16x32_bf16 v[114:117], v[224:227], v[158:161], v[114:117]
	v_mfma_f32_16x16x32_bf16 v[54:57], v[216:219], v[166:169], v[54:57]
	v_mfma_f32_16x16x32_bf16 v[30:33], v[224:227], v[166:169], v[30:33]
	v_mfma_f32_16x16x32_bf16 v[46:49], v[216:219], v[174:177], v[46:49]
	v_mfma_f32_16x16x32_bf16 v[110:113], v[224:227], v[174:177], v[110:113]
	v_mfma_f32_16x16x32_bf16 v[42:45], v[216:219], v[186:189], v[42:45]
	v_mfma_f32_16x16x32_bf16 v[22:25], v[224:227], v[186:189], v[22:25]
	s_setprio 0
	s_mov_b32 m0, s53
	v_lshl_add_u64 v[146:147], v[194:195], 0, s[64:65]
	s_barrier
	ds_read_b128 v[154:157], v133 offset:49152
	ds_read_b128 v[158:161], v133 offset:50176
	ds_read_b128 v[162:165], v133 offset:51200
	ds_read_b128 v[166:169], v133 offset:52224
	ds_read_b128 v[170:173], v133 offset:53248
	ds_read_b128 v[174:177], v133 offset:54272
	ds_read_b128 v[178:181], v133 offset:55296
	ds_read_b128 v[186:189], v133 offset:56320
	global_load_lds_dwordx4 v[146:147], off
	v_lshl_add_u64 v[146:147], v[214:215], 0, s[64:65]
	s_mov_b32 m0, s54
	s_nop 0
	global_load_lds_dwordx4 v[146:147], off
	s_barrier
	s_waitcnt lgkmcnt(0)
	s_setprio 1
	s_waitcnt lgkmcnt(0)
	v_mfma_f32_16x16x32_bf16 v[102:105], v[134:137], v[154:157], v[102:105]
	v_mfma_f32_16x16x32_bf16 v[70:73], v[142:145], v[154:157], v[70:73]
	v_mfma_f32_16x16x32_bf16 v[90:93], v[134:137], v[162:165], v[90:93]
	v_mfma_f32_16x16x32_bf16 v[66:69], v[142:145], v[162:165], v[66:69]
	v_mfma_f32_16x16x32_bf16 v[82:85], v[134:137], v[170:173], v[82:85]
	v_mfma_f32_16x16x32_bf16 v[58:61], v[142:145], v[170:173], v[58:61]
	v_mfma_f32_16x16x32_bf16 v[86:89], v[134:137], v[178:181], v[86:89]
	v_mfma_f32_16x16x32_bf16 v[50:53], v[142:145], v[178:181], v[50:53]
	v_mfma_f32_16x16x32_bf16 v[102:105], v[138:141], v[158:161], v[102:105]
	v_mfma_f32_16x16x32_bf16 v[70:73], v[150:153], v[158:161], v[70:73]
	v_mfma_f32_16x16x32_bf16 v[90:93], v[138:141], v[166:169], v[90:93]
	v_mfma_f32_16x16x32_bf16 v[66:69], v[150:153], v[166:169], v[66:69]
	v_mfma_f32_16x16x32_bf16 v[82:85], v[138:141], v[174:177], v[82:85]
	v_mfma_f32_16x16x32_bf16 v[58:61], v[150:153], v[174:177], v[58:61]
	v_mfma_f32_16x16x32_bf16 v[86:89], v[138:141], v[186:189], v[86:89]
	v_mfma_f32_16x16x32_bf16 v[50:53], v[150:153], v[186:189], v[50:53]
	s_setprio 0
	s_barrier
	s_mov_b32 m0, s13
	v_lshl_add_u64 v[134:135], s[40:41], 0, v[0:1]
	global_load_lds_dwordx4 v[134:135], off
	v_lshl_add_u64 v[134:135], s[40:41], 0, v[130:131]
	s_mov_b32 m0, s11
	s_nop 0
	global_load_lds_dwordx4 v[134:135], off
	s_waitcnt vmcnt(6)
	s_barrier
	s_setprio 1
	v_mfma_f32_16x16x32_bf16 v[38:41], v[190:193], v[154:157], v[38:41]
	v_mfma_f32_16x16x32_bf16 v[10:13], v[220:223], v[154:157], v[10:13]
	v_mfma_f32_16x16x32_bf16 v[34:37], v[190:193], v[162:165], v[34:37]
	v_mfma_f32_16x16x32_bf16 v[14:17], v[220:223], v[162:165], v[14:17]
	v_mfma_f32_16x16x32_bf16 v[26:29], v[190:193], v[170:173], v[26:29]
	v_mfma_f32_16x16x32_bf16 v[6:9], v[220:223], v[170:173], v[6:9]
	v_mfma_f32_16x16x32_bf16 v[18:21], v[190:193], v[178:181], v[18:21]
	v_mfma_f32_16x16x32_bf16 v[2:5], v[220:223], v[178:181], v[2:5]
	v_mfma_f32_16x16x32_bf16 v[38:41], v[216:219], v[158:161], v[38:41]
	v_mfma_f32_16x16x32_bf16 v[10:13], v[224:227], v[158:161], v[10:13]
	v_mfma_f32_16x16x32_bf16 v[34:37], v[216:219], v[166:169], v[34:37]
	v_mfma_f32_16x16x32_bf16 v[14:17], v[224:227], v[166:169], v[14:17]
	v_mfma_f32_16x16x32_bf16 v[26:29], v[216:219], v[174:177], v[26:29]
	v_mfma_f32_16x16x32_bf16 v[6:9], v[224:227], v[174:177], v[6:9]
	v_mfma_f32_16x16x32_bf16 v[18:21], v[216:219], v[186:189], v[18:21]
	v_mfma_f32_16x16x32_bf16 v[2:5], v[224:227], v[186:189], v[2:5]
	s_setprio 0
	s_andn2_b64 vcc, exec, s[38:39]
	s_mov_b64 s[40:41], -1
	s_mov_b64 s[38:39], 0
	s_mov_b64 s[42:43], 0x100
	s_barrier
	s_cbranch_vccz .LBB0_286
	s_andn2_b64 vcc, exec, s[16:17]
	s_cbranch_vccnz .LBB0_282
	v_mov_b32_e32 v2, 0
	s_mov_b32 s4, s12
	s_mov_b32 s0, s10
	s_mov_b64 s[8:9], s[36:37]
	s_mov_b64 s[6:7], s[34:35]
	s_mov_b32 s55, s60
	v_mov_b32_e32 v3, v2
	v_mov_b64_e32 v[4:5], 0
	v_mov_b64_e32 v[18:19], 0
	v_mov_b64_e32 v[20:21], 0
	v_mov_b64_e32 v[6:7], 0
	v_mov_b64_e32 v[8:9], 0
	v_mov_b64_e32 v[26:27], 0
	v_mov_b64_e32 v[28:29], 0
	v_mov_b64_e32 v[14:15], 0
	v_mov_b64_e32 v[16:17], 0
	v_mov_b64_e32 v[34:35], 0
	v_mov_b64_e32 v[36:37], 0
	v_mov_b64_e32 v[10:11], 0
	v_mov_b64_e32 v[12:13], 0
	v_mov_b64_e32 v[38:39], 0
	v_mov_b64_e32 v[40:41], 0
	v_mov_b64_e32 v[50:51], 0
	v_mov_b64_e32 v[52:53], 0
	v_mov_b64_e32 v[86:87], 0
	v_mov_b64_e32 v[88:89], 0
	v_mov_b64_e32 v[58:59], 0
	v_mov_b64_e32 v[60:61], 0
	v_mov_b64_e32 v[82:83], 0
	v_mov_b64_e32 v[84:85], 0
	v_mov_b64_e32 v[66:67], 0
	v_mov_b64_e32 v[68:69], 0
	v_mov_b64_e32 v[90:91], 0
	v_mov_b64_e32 v[92:93], 0
	v_mov_b64_e32 v[70:71], 0
	v_mov_b64_e32 v[72:73], 0
	v_mov_b64_e32 v[102:103], 0
	v_mov_b64_e32 v[104:105], 0
	v_mov_b64_e32 v[22:23], 0
	v_mov_b64_e32 v[24:25], 0
	v_mov_b64_e32 v[42:43], 0
	v_mov_b64_e32 v[44:45], 0
	v_mov_b64_e32 v[110:111], 0
	v_mov_b64_e32 v[112:113], 0
	v_mov_b64_e32 v[46:47], 0
	v_mov_b64_e32 v[48:49], 0
	v_mov_b64_e32 v[30:31], 0
	v_mov_b64_e32 v[32:33], 0
	v_mov_b64_e32 v[54:55], 0
	v_mov_b64_e32 v[56:57], 0
	v_mov_b64_e32 v[114:115], 0
	v_mov_b64_e32 v[116:117], 0
	v_mov_b64_e32 v[62:63], 0
	v_mov_b64_e32 v[64:65], 0
	v_mov_b64_e32 v[74:75], 0
	v_mov_b64_e32 v[76:77], 0
	v_mov_b64_e32 v[106:107], 0
	v_mov_b64_e32 v[108:109], 0
	v_mov_b64_e32 v[78:79], 0
	v_mov_b64_e32 v[80:81], 0
	v_mov_b64_e32 v[118:119], 0
	v_mov_b64_e32 v[120:121], 0
	v_mov_b64_e32 v[94:95], 0
	v_mov_b64_e32 v[96:97], 0
	v_mov_b64_e32 v[122:123], 0
	v_mov_b64_e32 v[124:125], 0
	v_mov_b64_e32 v[98:99], 0
	v_mov_b64_e32 v[100:101], 0
	v_mov_b64_e32 v[126:127], 0
	v_mov_b64_e32 v[128:129], 0
	s_branch .LBB0_282

; #define PG8_STAGE(bufoff, gbase, voff) do { _Pragma("unroll") for (int _i = 0; _i < 2; ++_i) \
;         __builtin_amdgcn_global_load_lds((const unsigned*)((const char*)(gbase) + (voff)[_i]), (LAS unsigned*)(lds + (bufoff) + ldsw + _i * 8192), 16, 0, 0); } while (0)
; #define PG8_STAGE_A(bufoff, gbase, h, vv) do { if constexpr (GATHER) { _Pragma("unroll") for (int _i = 0; _i < 2; ++_i) \
;         __builtin_amdgcn_global_load_lds((const unsigned*)((const char*)(gbase) + (vv)[h][_i]), (LAS unsigned*)(lds + (bufoff) + ldsw + _i * 8192), 16, 0, 0); } \
;         else { PG8_STAGE(bufoff, (gbase) + (h) * hstepA, voffA); } } while (0)
; #define PG8_WAIT_V(n) asm volatile("s_waitcnt vmcnt(" #n ")" ::: "memory")
; #define PG8_BAR __builtin_amdgcn_s_barrier()
; template <class Epi, class Sched>
; __device__ __forceinline__ void gemm_phase(LAS unsigned char* lds, const int K, const int lda, const int ldb, const Sched& S, const Epi& E) {
;     ...
;     f32x4 acc[2][2][4][2];
; #pragma unroll
;     for (int a = 0; a < 2; ++a)
; #pragma unroll
;         for (int b = 0; b < 2; ++b)
; #pragma unroll
;             for (int m = 0; m < 4; ++m)
; #pragma unroll
;                 for (int n = 0; n < 2; ++n) acc[a][b][m][n] = (f32x4){0.f, 0.f, 0.f, 0.f};
;     ...
;     PG8_STAGE(PG8_SB(0, 0), cB, voffB); PG8_STAGE_A(PG8_SA(0, 0), cA, 0, vcur); PG8_STAGE(PG8_SB(0, 1), cB + hstepB, voffB); PG8_STAGE_A(PG8_SA(0, 1), cA, 1, vcur);
;     if (wr == 1) PG8_BAR;
;     PG8_WAIT_V(4); PG8_BAR;
;     PG8_STAGE(PG8_SB(1, 0), cB + kstep, voffB); PG8_STAGE_A(PG8_SA(1, 0), cA + kstep, 0, vcur); PG8_STAGE(PG8_SB(1, 1), cB + hstepB + kstep, voffB);
;     PG8_WAIT_V(6); PG8_BAR;
.LBB0_382:
	v_lshrrev_b32_e32 v20, 1, v2
	v_and_b32_e32 v20, 24, v20
	v_and_b32_e32 v11, 15, v2
	v_lshlrev_b32_e32 v21, 1, v20
	v_lshlrev_b32_e32 v2, 2, v2
	v_lshl_or_b32 v144, s4, 6, v11
	v_lshl_or_b32 v11, v11, 6, v21
	s_lshl_b32 s2, s4, 13
	v_and_b32_e32 v2, 32, v2
	v_lshl_add_u64 v[12:13], s[12:13], 0, v[0:1]
	v_mov_b32_e32 v135, v1
	v_bitop3_b32 v21, v11, s2, v2 bitop3:0xde
	s_lshl_b32 s2, s5, 5
	v_lshl_add_u64 v[14:15], s[12:13], 0, v[134:135]
	v_mov_b32_e32 v131, v1
	s_and_b32 s2, s2, 0x60
	s_add_i32 m0, s54, 0x18000
	v_lshl_add_u64 v[12:13], v[12:13], 0, s[64:65]
	v_lshl_add_u64 v[16:17], s[0:1], 0, v[130:131]
	v_mov_b32_e32 v133, v1
	s_lshl_b32 s3, s2, 7
	s_waitcnt vmcnt(4)
	s_barrier
	global_load_lds_dwordx4 v[12:13], off
	v_lshl_add_u64 v[12:13], v[14:15], 0, s[64:65]
	s_add_i32 m0, s54, 0x1a000
	s_add_i32 s71, s54, 0x8000
	s_add_i32 s72, s54, 0xa000
	v_lshl_add_u64 v[18:19], s[0:1], 0, v[132:133]
	global_load_lds_dwordx4 v[12:13], off
	v_lshl_add_u64 v[12:13], v[16:17], 0, s[64:65]
	s_mov_b32 m0, s71
	s_add_u32 s4, s12, 0xe0080
	global_load_lds_dwordx4 v[12:13], off
	v_lshl_add_u64 v[12:13], v[18:19], 0, s[64:65]
	s_mov_b32 m0, s72
	s_addc_u32 s5, s13, 0
	global_load_lds_dwordx4 v[12:13], off
	s_add_i32 m0, s54, 0x1c000
	v_lshl_add_u64 v[12:13], s[4:5], 0, v[0:1]
	global_load_lds_dwordx4 v[12:13], off
	v_lshl_add_u64 v[12:13], s[4:5], 0, v[134:135]
	s_add_i32 m0, s54, 0x1e000
	v_or_b32_e32 v146, s2, v20
	global_load_lds_dwordx4 v[12:13], off
	s_movk_i32 s2, 0xe00
	v_bitop3_b32 v145, v11, s3, v2 bitop3:0xde
	v_lshrrev_b32_e32 v3, 1, v3
	v_mul_lo_u32 v2, v5, s2
	s_mov_b32 s3, 0xe000
	v_mad_u64_u32 v[2:3], s[4:5], v3, s3, v[2:3]
	v_or_b32_e32 v2, v2, v4
	v_add_lshl_u32 v136, v2, v6, 1
	v_lshrrev_b32_e32 v3, 1, v7
	v_mul_lo_u32 v2, v9, s2
	v_mad_u64_u32 v[2:3], s[4:5], v3, s3, v[2:3]
	s_waitcnt vmcnt(6)
	v_or_b32_e32 v2, v2, v8
	v_add_lshl_u32 v138, v2, v10, 1
	v_mov_b32_e32 v2, 0
	v_mov_b32_e32 v137, v1
	v_mov_b32_e32 v139, v1
	s_mov_b32 s73, 0
	v_add_u32_e32 v147, 0, v21
	v_mov_b32_e32 v3, v2
	v_mov_b64_e32 v[4:5], 0
	v_mov_b64_e32 v[6:7], 0
	v_mov_b64_e32 v[8:9], 0
	v_mov_b64_e32 v[10:11], 0
	v_mov_b64_e32 v[12:13], 0
	v_mov_b64_e32 v[14:15], 0
	v_mov_b64_e32 v[16:17], 0
	v_mov_b64_e32 v[18:19], 0
	v_mov_b64_e32 v[20:21], 0
	v_mov_b64_e32 v[22:23], 0
	v_mov_b64_e32 v[24:25], 0
	v_mov_b64_e32 v[26:27], 0
	v_mov_b64_e32 v[28:29], 0
	v_mov_b64_e32 v[30:31], 0
	v_mov_b64_e32 v[32:33], 0
	v_mov_b64_e32 v[34:35], 0
	v_mov_b64_e32 v[36:37], 0
	v_mov_b64_e32 v[38:39], 0
	v_mov_b64_e32 v[40:41], 0
	v_mov_b64_e32 v[42:43], 0
	v_mov_b64_e32 v[44:45], 0
	v_mov_b64_e32 v[46:47], 0
	v_mov_b64_e32 v[48:49], 0
	v_mov_b64_e32 v[50:51], 0
	v_mov_b64_e32 v[52:53], 0
	v_mov_b64_e32 v[54:55], 0
	v_mov_b64_e32 v[56:57], 0
	v_mov_b64_e32 v[58:59], 0
	v_mov_b64_e32 v[60:61], 0
	v_mov_b64_e32 v[62:63], 0
	v_mov_b64_e32 v[64:65], 0
	v_mov_b64_e32 v[66:67], 0
	v_mov_b64_e32 v[68:69], 0
	v_mov_b64_e32 v[70:71], 0
	v_mov_b64_e32 v[72:73], 0
	v_mov_b64_e32 v[74:75], 0
	v_mov_b64_e32 v[76:77], 0
	v_mov_b64_e32 v[78:79], 0
	v_mov_b64_e32 v[80:81], 0
	v_mov_b64_e32 v[82:83], 0
	v_mov_b64_e32 v[84:85], 0
	v_mov_b64_e32 v[86:87], 0
	v_mov_b64_e32 v[88:89], 0
	v_mov_b64_e32 v[90:91], 0
	v_mov_b64_e32 v[92:93], 0
	v_mov_b64_e32 v[94:95], 0
	v_mov_b64_e32 v[96:97], 0
	v_mov_b64_e32 v[98:99], 0
	v_mov_b64_e32 v[100:101], 0
	v_mov_b64_e32 v[102:103], 0
	v_mov_b64_e32 v[104:105], 0
	v_mov_b64_e32 v[106:107], 0
	v_mov_b64_e32 v[108:109], 0
	v_mov_b64_e32 v[110:111], 0
	v_mov_b64_e32 v[112:113], 0
	v_mov_b64_e32 v[114:115], 0
	v_mov_b64_e32 v[116:117], 0
	v_mov_b64_e32 v[118:119], 0
	v_mov_b64_e32 v[120:121], 0
	v_mov_b64_e32 v[122:123], 0
	v_mov_b64_e32 v[124:125], 0
	v_mov_b64_e32 v[126:127], 0
	v_mov_b64_e32 v[128:129], 0
	s_mov_b64 s[4:5], s[12:13]
	s_mov_b32 s57, 0x7f800000
	s_brev_b32 s56, 1
	s_barrier
	s_branch .LBB0_385

; #define PG8_STAGE(bufoff, gbase, voff) do { _Pragma("unroll") for (int _i = 0; _i < 2; ++_i) \
;         __builtin_amdgcn_global_load_lds((const unsigned*)((const char*)(gbase) + (voff)[_i]), (LAS unsigned*)(lds + (bufoff) + ldsw + _i * 8192), 16, 0, 0); } while (0)
; #define PG8_STAGE_A(bufoff, gbase, h, vv) do { if constexpr (GATHER) { _Pragma("unroll") for (int _i = 0; _i < 2; ++_i) \
;         __builtin_amdgcn_global_load_lds((const unsigned*)((const char*)(gbase) + (vv)[h][_i]), (LAS unsigned*)(lds + (bufoff) + ldsw + _i * 8192), 16, 0, 0); } \
;         else { PG8_STAGE(bufoff, (gbase) + (h) * hstepA, voffA); } } while (0)
; #define PG8_LDA(dst, b, h) do { _Pragma("unroll") for (int m = 0; m < 4; ++m) _Pragma("unroll") for (int k = 0; k < 2; ++k) dst[m][k] = *(const LAS bf16x8*)(lds + PG8_SA(b, h) + aoff + m * 2048 + k * 1024); } while (0)
; #define PG8_WAIT_V(n) asm volatile("s_waitcnt vmcnt(" #n ")" ::: "memory")
; #define PG8_WAIT_L(n) asm volatile("s_waitcnt lgkmcnt(" #n ")" ::: "memory")
; template <class Epi, class Sched>
; __device__ __forceinline__ void gemm_phase(LAS unsigned char* lds, const int K, const int lda, const int ldb, const Sched& S, const Epi& E) {
;     ...
;         for (int t = 0; t < nt; t += 2) {
;             const bool last = (t == nt - 2);
;             const char* a1 = cA + (size_t)(t + 1) * kstep;
;             const char* a2 = last ? nA : cA + (size_t)(t + 2) * kstep; const char* b2 = last ? nB : cB + (size_t)(t + 2) * kstep;
;             const char* a3 = a2 + kstep; const char* b3 = b2 + kstep;
;             PG8_LDB(B0, 0, 0); PG8_SCHED; PG8_LDA(At, 0, 0); PG8_STAGE_A(PG8_SA(1, 1), a1, 1, vcur);
;             if constexpr (GATHER) { if (last) {
; #pragma unroll
;                 for (int h = 0; h < 2; ++h)
; #pragma unroll
;                     for (int i = 0; i < 2; ++i) vcur[h][i] = vnxt[h][i]; } }
;             PG8_WAIT_L(8); PG8_BAR; PG8_WAIT_L(0); PG8_MMA(0, 0, At, B0); PG8_BAR; PG8_SCHED;
;             PG8_LDB(B1, 0, 1); PG8_STAGE(PG8_SB(0, 0), b2, voffB);
;             PG8_BAR; PG8_WAIT_L(0); PG8_MMA(0, 1, At, B1); PG8_BAR;
;             PG8_LDA(At, 0, 1); PG8_STAGE_A(PG8_SA(0, 0), a2, 0, vcur);
;             PG8_BAR; PG8_WAIT_L(0); PG8_MMA(1, 0, At, B0); PG8_BAR; PG8_SCHED;
;             PG8_STAGE(PG8_SB(0, 1), b2 + hstepB, voffB);
;             PG8_WAIT_V(6); PG8_BAR; PG8_MMA(1, 1, At, B1); PG8_BAR;
.LBB0_392:
	s_add_u32 s2, s0, s12
	s_addc_u32 s3, s1, s13
	s_add_u32 s2, s2, 0x100
	s_addc_u32 s3, s3, 0
	s_add_u32 s14, s78, s12
	s_addc_u32 s15, s79, s13
	s_add_i32 s20, 0, 0x10000
	v_add_u32_e32 v160, s20, v145
	ds_read_b128 v[148:151], v160
	ds_read_b128 v[152:155], v160 offset:1024
	ds_read_b128 v[156:159], v160 offset:2048
	ds_read_b128 v[160:163], v160 offset:3072
	s_cmpk_eq_i32 s12, 0x1b00
	s_cselect_b32 s17, s11, s3
	s_cselect_b32 s16, s10, s2
	s_cselect_b32 s15, s5, s15
	s_cselect_b32 s14, s4, s14
	v_lshl_add_u64 v[214:215], v[140:141], 0, s[12:13]
	s_add_i32 m0, s54, 0xc000
	ds_read_b128 v[164:167], v147
	ds_read_b128 v[168:171], v147 offset:1024
	ds_read_b128 v[172:175], v147 offset:2048
	ds_read_b128 v[176:179], v147 offset:3072
	ds_read_b128 v[180:183], v147 offset:4096
	ds_read_b128 v[184:187], v147 offset:5120
	ds_read_b128 v[188:191], v147 offset:6144
	ds_read_b128 v[192:195], v147 offset:7168
	global_load_lds_dwordx4 v[214:215], off
	v_lshl_add_u64 v[214:215], v[142:143], 0, s[12:13]
	s_add_i32 m0, s54, 0xe000
	s_nop 0
	global_load_lds_dwordx4 v[214:215], off
	s_waitcnt lgkmcnt(8)
	s_barrier
	s_waitcnt lgkmcnt(0)
	s_setprio 1
	s_waitcnt lgkmcnt(0)
	v_mfma_f32_16x16x32_bf16 v[126:129], v[148:151], v[164:167], v[126:129]
	v_mfma_f32_16x16x32_bf16 v[122:125], v[156:159], v[164:167], v[122:125]
	v_mfma_f32_16x16x32_bf16 v[118:121], v[148:151], v[172:175], v[118:121]
	v_mfma_f32_16x16x32_bf16 v[114:117], v[156:159], v[172:175], v[114:117]
	v_mfma_f32_16x16x32_bf16 v[110:113], v[148:151], v[180:183], v[110:113]
	v_mfma_f32_16x16x32_bf16 v[106:109], v[156:159], v[180:183], v[106:109]
	v_mfma_f32_16x16x32_bf16 v[102:105], v[148:151], v[188:191], v[102:105]
	v_mfma_f32_16x16x32_bf16 v[98:101], v[156:159], v[188:191], v[98:101]
	v_mfma_f32_16x16x32_bf16 v[126:129], v[152:155], v[168:171], v[126:129]
	v_mfma_f32_16x16x32_bf16 v[122:125], v[160:163], v[168:171], v[122:125]
	v_mfma_f32_16x16x32_bf16 v[118:121], v[152:155], v[176:179], v[118:121]
	v_mfma_f32_16x16x32_bf16 v[114:117], v[160:163], v[176:179], v[114:117]
	v_mfma_f32_16x16x32_bf16 v[110:113], v[152:155], v[184:187], v[110:113]
	v_mfma_f32_16x16x32_bf16 v[106:109], v[160:163], v[184:187], v[106:109]
	v_mfma_f32_16x16x32_bf16 v[102:105], v[152:155], v[192:195], v[102:105]
	v_mfma_f32_16x16x32_bf16 v[98:101], v[160:163], v[192:195], v[98:101]
	s_setprio 0
	s_barrier
	s_add_i32 s21, 0, 0x14000
	v_add_u32_e32 v214, s21, v145
	s_add_i32 s2, s20, s63
	ds_read_b128 v[216:219], v214
	ds_read_b128 v[220:223], v214 offset:1024
	ds_read_b128 v[224:227], v214 offset:2048
	ds_read_b128 v[228:231], v214 offset:3072
	v_lshl_add_u64 v[214:215], s[14:15], 0, v[0:1]
	s_mov_b32 m0, s2
	v_lshl_add_u64 v[232:233], s[14:15], 0, v[134:135]
	global_load_lds_dwordx4 v[214:215], off
	s_add_i32 m0, s2, 0x2000
	s_nop 0
	global_load_lds_dwordx4 v[232:233], off
	s_barrier
	s_waitcnt lgkmcnt(0)
	s_setprio 1
	s_waitcnt lgkmcnt(0)
	v_mfma_f32_16x16x32_bf16 v[94:97], v[216:219], v[164:167], v[94:97]
	v_mfma_f32_16x16x32_bf16 v[90:93], v[224:227], v[164:167], v[90:93]
	v_mfma_f32_16x16x32_bf16 v[86:89], v[216:219], v[172:175], v[86:89]
	v_mfma_f32_16x16x32_bf16 v[82:85], v[224:227], v[172:175], v[82:85]
	v_mfma_f32_16x16x32_bf16 v[78:81], v[216:219], v[180:183], v[78:81]
	v_mfma_f32_16x16x32_bf16 v[74:77], v[224:227], v[180:183], v[74:77]
	v_mfma_f32_16x16x32_bf16 v[70:73], v[216:219], v[188:191], v[70:73]
	v_mfma_f32_16x16x32_bf16 v[66:69], v[224:227], v[188:191], v[66:69]
	v_mfma_f32_16x16x32_bf16 v[94:97], v[220:223], v[168:171], v[94:97]
	v_mfma_f32_16x16x32_bf16 v[90:93], v[228:231], v[168:171], v[90:93]
	v_mfma_f32_16x16x32_bf16 v[86:89], v[220:223], v[176:179], v[86:89]
	v_mfma_f32_16x16x32_bf16 v[82:85], v[228:231], v[176:179], v[82:85]
	v_mfma_f32_16x16x32_bf16 v[78:81], v[220:223], v[184:187], v[78:81]
	v_mfma_f32_16x16x32_bf16 v[74:77], v[228:231], v[184:187], v[74:77]
	v_mfma_f32_16x16x32_bf16 v[70:73], v[220:223], v[192:195], v[70:73]
	v_mfma_f32_16x16x32_bf16 v[66:69], v[228:231], v[192:195], v[66:69]
	s_setprio 0
	s_mov_b32 m0, s54
	v_lshl_add_u64 v[234:235], s[16:17], 0, v[130:131]
	s_barrier
	ds_read_b128 v[164:167], v147 offset:16384
	ds_read_b128 v[168:171], v147 offset:17408
	ds_read_b128 v[172:175], v147 offset:18432
	ds_read_b128 v[176:179], v147 offset:19456
	ds_read_b128 v[180:183], v147 offset:20480
	ds_read_b128 v[184:187], v147 offset:21504
	ds_read_b128 v[188:191], v147 offset:22528
	ds_read_b128 v[192:195], v147 offset:23552
	global_load_lds_dwordx4 v[234:235], off
	v_lshl_add_u64 v[236:237], s[16:17], 0, v[132:133]
	s_mov_b32 m0, s55
	s_nop 0
	global_load_lds_dwordx4 v[236:237], off
	s_barrier
	s_waitcnt lgkmcnt(0)
	s_setprio 1
	s_waitcnt lgkmcnt(0)
	v_mfma_f32_16x16x32_bf16 v[62:65], v[148:151], v[164:167], v[62:65]
	v_mfma_f32_16x16x32_bf16 v[58:61], v[156:159], v[164:167], v[58:61]
	v_mfma_f32_16x16x32_bf16 v[54:57], v[148:151], v[172:175], v[54:57]
	v_mfma_f32_16x16x32_bf16 v[50:53], v[156:159], v[172:175], v[50:53]
	v_mfma_f32_16x16x32_bf16 v[46:49], v[148:151], v[180:183], v[46:49]
	v_mfma_f32_16x16x32_bf16 v[42:45], v[156:159], v[180:183], v[42:45]
	v_mfma_f32_16x16x32_bf16 v[38:41], v[148:151], v[188:191], v[38:41]
	v_mfma_f32_16x16x32_bf16 v[34:37], v[156:159], v[188:191], v[34:37]
	v_mfma_f32_16x16x32_bf16 v[62:65], v[152:155], v[168:171], v[62:65]
	v_mfma_f32_16x16x32_bf16 v[58:61], v[160:163], v[168:171], v[58:61]
	v_mfma_f32_16x16x32_bf16 v[54:57], v[152:155], v[176:179], v[54:57]
	v_mfma_f32_16x16x32_bf16 v[50:53], v[160:163], v[176:179], v[50:53]
	v_mfma_f32_16x16x32_bf16 v[46:49], v[152:155], v[184:187], v[46:49]
	v_mfma_f32_16x16x32_bf16 v[42:45], v[160:163], v[184:187], v[42:45]
	v_mfma_f32_16x16x32_bf16 v[38:41], v[152:155], v[192:195], v[38:41]
	v_mfma_f32_16x16x32_bf16 v[34:37], v[160:163], v[192:195], v[34:37]
	s_setprio 0
	s_barrier
; #define PG8_STAGE(bufoff, gbase, voff) do { _Pragma("unroll") for (int _i = 0; _i < 2; ++_i) \
;         __builtin_amdgcn_global_load_lds((const unsigned*)((const char*)(gbase) + (voff)[_i]), (LAS unsigned*)(lds + (bufoff) + ldsw + _i * 8192), 16, 0, 0); } while (0)
; #define PG8_STAGE_A(bufoff, gbase, h, vv) do { if constexpr (GATHER) { _Pragma("unroll") for (int _i = 0; _i < 2; ++_i) \
;         __builtin_amdgcn_global_load_lds((const unsigned*)((const char*)(gbase) + (vv)[h][_i]), (LAS unsigned*)(lds + (bufoff) + ldsw + _i * 8192), 16, 0, 0); } \
;         else { PG8_STAGE(bufoff, (gbase) + (h) * hstepA, voffA); } } while (0)
; #define PG8_LDA(dst, b, h) do { _Pragma("unroll") for (int m = 0; m < 4; ++m) _Pragma("unroll") for (int k = 0; k < 2; ++k) dst[m][k] = *(const LAS bf16x8*)(lds + PG8_SA(b, h) + aoff + m * 2048 + k * 1024); } while (0)
; #define PG8_LDB(dst, b, h) do { _Pragma("unroll") for (int n = 0; n < 2; ++n) _Pragma("unroll") for (int k = 0; k < 2; ++k) dst[n][k] = *(const LAS bf16x8*)(lds + PG8_SB(b, h) + boff + n * 2048 + k * 1024); } while (0)
; #define PG8_MMA(ai, bj, At, Bt) do { __builtin_amdgcn_s_setprio(1); _Pragma("unroll") for (int m = 0; m < 4; ++m) _Pragma("unroll") for (int n = 0; n < 2; ++n) _Pragma("unroll") for (int k = 0; k < 2; ++k) \
;         acc[ai][bj][m][n] = __builtin_amdgcn_mfma_f32_16x16x32_bf16(Bt[n][k], At[m][k], acc[ai][bj][m][n], 0, 0, 0); __builtin_amdgcn_s_setprio(0); } while (0)
; #define PG8_BAR __builtin_amdgcn_s_barrier()
; template <class Epi, class Sched>
; __device__ __forceinline__ void gemm_phase(LAS unsigned char* lds, const int K, const int lda, const int ldb, const Sched& S, const Epi& E) {
;     ...
;             PG8_WAIT_V(6); PG8_BAR; PG8_MMA(1, 1, At, B1); PG8_BAR;
;             PG8_LDB(B0, 1, 0); PG8_SCHED; PG8_LDA(At, 1, 0); PG8_STAGE_A(PG8_SA(0, 1), a2, 1, vcur);
;             PG8_WAIT_L(8); PG8_BAR; PG8_WAIT_L(0); PG8_MMA(0, 0, At, B0); PG8_BAR; PG8_SCHED;
;             PG8_LDB(B1, 1, 1); PG8_STAGE(PG8_SB(1, 0), b3, voffB);
;             PG8_BAR; PG8_WAIT_L(0); PG8_MMA(0, 1, At, B1); PG8_BAR;
;             PG8_LDA(At, 1, 1); PG8_STAGE_A(PG8_SA(1, 0), a3, 0, vcur);
;             PG8_BAR; PG8_WAIT_L(0); PG8_MMA(1, 0, At, B0); PG8_BAR; PG8_SCHED;
;             PG8_STAGE(PG8_SB(1, 1), b3 + hstepB, voffB);
;             PG8_WAIT_V(6); PG8_BAR; PG8_MMA(1, 1, At, B1); PG8_BAR;
	s_add_u32 s2, s14, 0xe0000
	s_addc_u32 s3, s15, 0
	s_add_i32 s20, s21, s63
	v_lshl_add_u64 v[148:149], s[2:3], 0, v[0:1]
	s_mov_b32 m0, s20
	s_nop 0
	global_load_lds_dwordx4 v[148:149], off
	v_lshl_add_u64 v[148:149], s[2:3], 0, v[134:135]
	s_add_i32 m0, s20, 0x2000
	s_nop 0
	global_load_lds_dwordx4 v[148:149], off
	s_waitcnt vmcnt(6)
	s_barrier
	s_setprio 1
	v_mfma_f32_16x16x32_bf16 v[30:33], v[216:219], v[164:167], v[30:33]
	v_mfma_f32_16x16x32_bf16 v[26:29], v[224:227], v[164:167], v[26:29]
	v_mfma_f32_16x16x32_bf16 v[22:25], v[216:219], v[172:175], v[22:25]
	v_mfma_f32_16x16x32_bf16 v[18:21], v[224:227], v[172:175], v[18:21]
	v_mfma_f32_16x16x32_bf16 v[14:17], v[216:219], v[180:183], v[14:17]
	v_mfma_f32_16x16x32_bf16 v[10:13], v[224:227], v[180:183], v[10:13]
	v_mfma_f32_16x16x32_bf16 v[6:9], v[216:219], v[188:191], v[6:9]
	v_mfma_f32_16x16x32_bf16 v[2:5], v[224:227], v[188:191], v[2:5]
	v_mfma_f32_16x16x32_bf16 v[30:33], v[220:223], v[168:171], v[30:33]
	v_mfma_f32_16x16x32_bf16 v[26:29], v[228:231], v[168:171], v[26:29]
	v_mfma_f32_16x16x32_bf16 v[22:25], v[220:223], v[176:179], v[22:25]
	v_mfma_f32_16x16x32_bf16 v[18:21], v[228:231], v[176:179], v[18:21]
	v_mfma_f32_16x16x32_bf16 v[14:17], v[220:223], v[184:187], v[14:17]
	v_mfma_f32_16x16x32_bf16 v[10:13], v[228:231], v[184:187], v[10:13]
	v_mfma_f32_16x16x32_bf16 v[6:9], v[220:223], v[192:195], v[6:9]
	v_mfma_f32_16x16x32_bf16 v[2:5], v[228:231], v[192:195], v[2:5]
	s_setprio 0
	s_add_i32 s20, 0, 0x18000
	v_add_u32_e32 v160, s20, v145
	s_barrier
	ds_read_b128 v[148:151], v160
	ds_read_b128 v[152:155], v160 offset:1024
	ds_read_b128 v[156:159], v160 offset:2048
	ds_read_b128 v[160:163], v160 offset:3072
	s_add_u32 s2, s16, 0xe0000
	s_addc_u32 s3, s17, 0
	s_mov_b32 m0, s69
	v_lshl_add_u64 v[216:217], s[2:3], 0, v[130:131]
	ds_read_b128 v[164:167], v147 offset:32768
	ds_read_b128 v[168:171], v147 offset:33792
	ds_read_b128 v[172:175], v147 offset:34816
	ds_read_b128 v[176:179], v147 offset:35840
	ds_read_b128 v[180:183], v147 offset:36864
	ds_read_b128 v[184:187], v147 offset:37888
	ds_read_b128 v[188:191], v147 offset:38912
	ds_read_b128 v[192:195], v147 offset:39936
	global_load_lds_dwordx4 v[216:217], off
	v_lshl_add_u64 v[216:217], s[2:3], 0, v[132:133]
	s_mov_b32 m0, s70
	s_nop 0
	global_load_lds_dwordx4 v[216:217], off
	s_waitcnt lgkmcnt(8)
	s_barrier
	s_waitcnt lgkmcnt(0)
	s_setprio 1
	s_waitcnt lgkmcnt(0)
	v_mfma_f32_16x16x32_bf16 v[126:129], v[148:151], v[164:167], v[126:129]
	v_mfma_f32_16x16x32_bf16 v[122:125], v[156:159], v[164:167], v[122:125]
	v_mfma_f32_16x16x32_bf16 v[118:121], v[148:151], v[172:175], v[118:121]
	v_mfma_f32_16x16x32_bf16 v[114:117], v[156:159], v[172:175], v[114:117]
	v_mfma_f32_16x16x32_bf16 v[110:113], v[148:151], v[180:183], v[110:113]
	v_mfma_f32_16x16x32_bf16 v[106:109], v[156:159], v[180:183], v[106:109]
	v_mfma_f32_16x16x32_bf16 v[102:105], v[148:151], v[188:191], v[102:105]
	v_mfma_f32_16x16x32_bf16 v[98:101], v[156:159], v[188:191], v[98:101]
	v_mfma_f32_16x16x32_bf16 v[126:129], v[152:155], v[168:171], v[126:129]
	v_mfma_f32_16x16x32_bf16 v[122:125], v[160:163], v[168:171], v[122:125]
	v_mfma_f32_16x16x32_bf16 v[118:121], v[152:155], v[176:179], v[118:121]
	v_mfma_f32_16x16x32_bf16 v[114:117], v[160:163], v[176:179], v[114:117]
	v_mfma_f32_16x16x32_bf16 v[110:113], v[152:155], v[184:187], v[110:113]
	v_mfma_f32_16x16x32_bf16 v[106:109], v[160:163], v[184:187], v[106:109]
	v_mfma_f32_16x16x32_bf16 v[102:105], v[152:155], v[192:195], v[102:105]
	v_mfma_f32_16x16x32_bf16 v[98:101], v[160:163], v[192:195], v[98:101]
	s_setprio 0
	s_barrier
	s_add_i32 s16, 0, 0x1c000
	s_add_i32 s2, s20, s63
	v_add_u32_e32 v228, s16, v145
	v_lshl_add_u64 v[214:215], v[214:215], 0, s[64:65]
	s_mov_b32 m0, s2
	ds_read_b128 v[216:219], v228
	ds_read_b128 v[220:223], v228 offset:1024
	ds_read_b128 v[224:227], v228 offset:2048
	ds_read_b128 v[228:231], v228 offset:3072
	global_load_lds_dwordx4 v[214:215], off
	v_lshl_add_u64 v[214:215], v[232:233], 0, s[64:65]
	s_add_i32 m0, s2, 0x2000
	s_nop 0
	global_load_lds_dwordx4 v[214:215], off
	s_barrier
	s_waitcnt lgkmcnt(0)
	s_setprio 1
	s_waitcnt lgkmcnt(0)
	v_mfma_f32_16x16x32_bf16 v[94:97], v[216:219], v[164:167], v[94:97]
	v_mfma_f32_16x16x32_bf16 v[90:93], v[224:227], v[164:167], v[90:93]
	v_mfma_f32_16x16x32_bf16 v[86:89], v[216:219], v[172:175], v[86:89]
	v_mfma_f32_16x16x32_bf16 v[82:85], v[224:227], v[172:175], v[82:85]
	v_mfma_f32_16x16x32_bf16 v[78:81], v[216:219], v[180:183], v[78:81]
	v_mfma_f32_16x16x32_bf16 v[74:77], v[224:227], v[180:183], v[74:77]
	v_mfma_f32_16x16x32_bf16 v[70:73], v[216:219], v[188:191], v[70:73]
	v_mfma_f32_16x16x32_bf16 v[66:69], v[224:227], v[188:191], v[66:69]
	v_mfma_f32_16x16x32_bf16 v[94:97], v[220:223], v[168:171], v[94:97]
	v_mfma_f32_16x16x32_bf16 v[90:93], v[228:231], v[168:171], v[90:93]
	v_mfma_f32_16x16x32_bf16 v[86:89], v[220:223], v[176:179], v[86:89]
	v_mfma_f32_16x16x32_bf16 v[82:85], v[228:231], v[176:179], v[82:85]
	v_mfma_f32_16x16x32_bf16 v[78:81], v[220:223], v[184:187], v[78:81]
	v_mfma_f32_16x16x32_bf16 v[74:77], v[228:231], v[184:187], v[74:77]
	v_mfma_f32_16x16x32_bf16 v[70:73], v[220:223], v[192:195], v[70:73]
	v_mfma_f32_16x16x32_bf16 v[66:69], v[228:231], v[192:195], v[66:69]
	s_setprio 0
	s_mov_b32 m0, s71
	v_lshl_add_u64 v[214:215], v[234:235], 0, s[64:65]
	s_barrier
	ds_read_b128 v[164:167], v147 offset:49152
	ds_read_b128 v[168:171], v147 offset:50176
	ds_read_b128 v[172:175], v147 offset:51200
	ds_read_b128 v[176:179], v147 offset:52224
	ds_read_b128 v[180:183], v147 offset:53248
	ds_read_b128 v[184:187], v147 offset:54272
	ds_read_b128 v[188:191], v147 offset:55296
	ds_read_b128 v[192:195], v147 offset:56320
	global_load_lds_dwordx4 v[214:215], off
	v_lshl_add_u64 v[214:215], v[236:237], 0, s[64:65]
	s_mov_b32 m0, s72
	s_nop 0
	global_load_lds_dwordx4 v[214:215], off
	s_barrier
; #define PG8_STAGE(bufoff, gbase, voff) do { _Pragma("unroll") for (int _i = 0; _i < 2; ++_i) \
;         __builtin_amdgcn_global_load_lds((const unsigned*)((const char*)(gbase) + (voff)[_i]), (LAS unsigned*)(lds + (bufoff) + ldsw + _i * 8192), 16, 0, 0); } while (0)
; #define PG8_STAGE_A(bufoff, gbase, h, vv) do { if constexpr (GATHER) { _Pragma("unroll") for (int _i = 0; _i < 2; ++_i) \
;         __builtin_amdgcn_global_load_lds((const unsigned*)((const char*)(gbase) + (vv)[h][_i]), (LAS unsigned*)(lds + (bufoff) + ldsw + _i * 8192), 16, 0, 0); } \
;         else { PG8_STAGE(bufoff, (gbase) + (h) * hstepA, voffA); } } while (0)
; #define PG8_LDA(dst, b, h) do { _Pragma("unroll") for (int m = 0; m < 4; ++m) _Pragma("unroll") for (int k = 0; k < 2; ++k) dst[m][k] = *(const LAS bf16x8*)(lds + PG8_SA(b, h) + aoff + m * 2048 + k * 1024); } while (0)
; #define PG8_MMA(ai, bj, At, Bt) do { __builtin_amdgcn_s_setprio(1); _Pragma("unroll") for (int m = 0; m < 4; ++m) _Pragma("unroll") for (int n = 0; n < 2; ++n) _Pragma("unroll") for (int k = 0; k < 2; ++k) \
;         acc[ai][bj][m][n] = __builtin_amdgcn_mfma_f32_16x16x32_bf16(Bt[n][k], At[m][k], acc[ai][bj][m][n], 0, 0, 0); __builtin_amdgcn_s_setprio(0); } while (0)
; #define PG8_WAIT_V(n) asm volatile("s_waitcnt vmcnt(" #n ")" ::: "memory")
; #define PG8_WAIT_L(n) asm volatile("s_waitcnt lgkmcnt(" #n ")" ::: "memory")
; #define PG8_BAR __builtin_amdgcn_s_barrier()
; #define PG8_SCHED __builtin_amdgcn_sched_barrier(0)
; template <class Epi, class Sched>
; __device__ __forceinline__ void gemm_phase(LAS unsigned char* lds, const int K, const int lda, const int ldb, const Sched& S, const Epi& E) {
;     ...
;             PG8_BAR; PG8_WAIT_L(0); PG8_MMA(0, 1, At, B1); PG8_BAR;
;             PG8_LDA(At, 1, 1); PG8_STAGE_A(PG8_SA(1, 0), a3, 0, vcur);
;             PG8_BAR; PG8_WAIT_L(0); PG8_MMA(1, 0, At, B0); PG8_BAR; PG8_SCHED;
;             PG8_STAGE(PG8_SB(1, 1), b3 + hstepB, voffB);
;             PG8_WAIT_V(6); PG8_BAR; PG8_MMA(1, 1, At, B1); PG8_BAR;
;         }
	s_waitcnt lgkmcnt(0)
	s_setprio 1
	s_waitcnt lgkmcnt(0)
	v_mfma_f32_16x16x32_bf16 v[62:65], v[148:151], v[164:167], v[62:65]
	v_mfma_f32_16x16x32_bf16 v[58:61], v[156:159], v[164:167], v[58:61]
	v_mfma_f32_16x16x32_bf16 v[54:57], v[148:151], v[172:175], v[54:57]
	v_mfma_f32_16x16x32_bf16 v[50:53], v[156:159], v[172:175], v[50:53]
	v_mfma_f32_16x16x32_bf16 v[46:49], v[148:151], v[180:183], v[46:49]
	v_mfma_f32_16x16x32_bf16 v[42:45], v[156:159], v[180:183], v[42:45]
	v_mfma_f32_16x16x32_bf16 v[38:41], v[148:151], v[188:191], v[38:41]
	v_mfma_f32_16x16x32_bf16 v[34:37], v[156:159], v[188:191], v[34:37]
	v_mfma_f32_16x16x32_bf16 v[62:65], v[152:155], v[168:171], v[62:65]
	v_mfma_f32_16x16x32_bf16 v[58:61], v[160:163], v[168:171], v[58:61]
	v_mfma_f32_16x16x32_bf16 v[54:57], v[152:155], v[176:179], v[54:57]
	v_mfma_f32_16x16x32_bf16 v[50:53], v[160:163], v[176:179], v[50:53]
	v_mfma_f32_16x16x32_bf16 v[46:49], v[152:155], v[184:187], v[46:49]
	v_mfma_f32_16x16x32_bf16 v[42:45], v[160:163], v[184:187], v[42:45]
	v_mfma_f32_16x16x32_bf16 v[38:41], v[152:155], v[192:195], v[38:41]
	v_mfma_f32_16x16x32_bf16 v[34:37], v[160:163], v[192:195], v[34:37]
	s_setprio 0
	s_barrier
	s_add_u32 s2, s14, 0xe0080
	s_addc_u32 s3, s15, 0
	s_add_i32 s14, s16, s63
	v_lshl_add_u64 v[148:149], s[2:3], 0, v[0:1]
	s_mov_b32 m0, s14
	s_nop 0
	global_load_lds_dwordx4 v[148:149], off
	v_lshl_add_u64 v[148:149], s[2:3], 0, v[134:135]
	s_add_i32 m0, s14, 0x2000
	s_nop 0
	global_load_lds_dwordx4 v[148:149], off
	s_waitcnt vmcnt(6)
	s_barrier
	s_setprio 1
	v_mfma_f32_16x16x32_bf16 v[30:33], v[216:219], v[164:167], v[30:33]
	v_mfma_f32_16x16x32_bf16 v[26:29], v[224:227], v[164:167], v[26:29]
	v_mfma_f32_16x16x32_bf16 v[22:25], v[216:219], v[172:175], v[22:25]
	v_mfma_f32_16x16x32_bf16 v[18:21], v[224:227], v[172:175], v[18:21]
	v_mfma_f32_16x16x32_bf16 v[14:17], v[216:219], v[180:183], v[14:17]
	v_mfma_f32_16x16x32_bf16 v[10:13], v[224:227], v[180:183], v[10:13]
	v_mfma_f32_16x16x32_bf16 v[6:9], v[216:219], v[188:191], v[6:9]
	v_mfma_f32_16x16x32_bf16 v[2:5], v[224:227], v[188:191], v[2:5]
	v_mfma_f32_16x16x32_bf16 v[30:33], v[220:223], v[168:171], v[30:33]
	v_mfma_f32_16x16x32_bf16 v[26:29], v[228:231], v[168:171], v[26:29]
	v_mfma_f32_16x16x32_bf16 v[22:25], v[220:223], v[176:179], v[22:25]
	v_mfma_f32_16x16x32_bf16 v[18:21], v[228:231], v[176:179], v[18:21]
	v_mfma_f32_16x16x32_bf16 v[14:17], v[220:223], v[184:187], v[14:17]
	v_mfma_f32_16x16x32_bf16 v[10:13], v[228:231], v[184:187], v[10:13]
	v_mfma_f32_16x16x32_bf16 v[6:9], v[220:223], v[192:195], v[6:9]
	v_mfma_f32_16x16x32_bf16 v[2:5], v[228:231], v[192:195], v[2:5]
	s_setprio 0
	s_add_i32 vcc_lo, vcc_lo, 2
	s_add_u32 s12, s12, 0x100
	s_addc_u32 s13, s13, 0
	s_cmp_gt_u32 vcc_lo, 53
	s_barrier
	s_cbranch_scc0 .LBB0_392
; __device__ __forceinline__ unsigned pk2(float lo, float hi) { unsigned r; asm("v_cvt_pk_bf16_f32 %0, %1, %2" : "=v"(r) : "v"(lo), "v"(hi)); return r; }
; template <class Epi, class Sched>
; __device__ __forceinline__ void gemm_phase(LAS unsigned char* lds, const int K, const int lda, const int ldb, const Sched& S, const Epi& E) {
;     ...
;         if (!has_next) break;
; #pragma unroll
;         for (int a = 0; a < 2; ++a)
; #pragma unroll
;             for (int b = 0; b < 2; ++b)
; #pragma unroll
;                 for (int m = 0; m < 4; ++m)
; #pragma unroll
;                     for (int n = 0; n < 2; ++n) acc[a][b][m][n] = (f32x4){0.f, 0.f, 0.f, 0.f};
;         cur = nxt; cA = nA; cB = nB; ++ui;
;     __device__ __forceinline__ void operator()(const Acc& acc, const Unit& u, int wr, int wc, int fr, int fq) const {
;         const int row0 = u.pm * BM + wr * 64 + fr, col0 = u.pn * BM + wc * 32 + 8 * fq;
; #pragma unroll
;         for (int ai = 0; ai < 2; ++ai)
; #pragma unroll
;             for (int m = 0; m < 4; ++m) { bf16_t* rp = O + (size_t)(row0 + ai * HALF + m * 16) * ld + col0;
; #pragma unroll
;                 for (int bj = 0; bj < 2; ++bj) { const f32x4 v0 = acc[ai][bj][m][0], v1 = acc[ai][bj][m][1];
;                     u32x4 o; o.x = pk2(v0[0], v0[1]); o.y = pk2(v0[2], v0[3]); o.z = pk2(v1[0], v1[1]); o.w = pk2(v1[2], v1[3]);
;                     *(u32x4*)(rp + bj * HALF) = o; } }
	v_lshl_add_u32 v142, s67, 8, v144
	v_lshl_or_b32 v140, s68, 8, v146
	v_ashrrev_i32_e32 v143, 31, v142
	v_readlane_b32 s2, v250, 17
	v_ashrrev_i32_e32 v141, 31, v140
	v_lshlrev_b64 v[148:149], 11, v[142:143]
	v_readlane_b32 s3, v250, 18
	v_lshlrev_b64 v[152:153], 1, v[140:141]
	v_cvt_pk_bf16_f32 v150, v122, v123
	v_cvt_pk_bf16_f32 v151, v124, v125
	s_add_u32 s12, s78, 0xffffff00
	v_lshl_add_u64 v[148:149], s[2:3], 0, v[148:149]
	v_lshl_add_u64 v[140:141], v[148:149], 0, v[152:153]
	v_cvt_pk_bf16_f32 v148, v126, v127
	v_cvt_pk_bf16_f32 v149, v128, v129
	global_store_dwordx4 v[140:141], v[148:151], off
	s_addc_u32 s13, s79, -1
	s_nop 0
	v_cvt_pk_bf16_f32 v148, v94, v95
	v_cvt_pk_bf16_f32 v149, v96, v97
	v_cvt_pk_bf16_f32 v150, v90, v91
	v_cvt_pk_bf16_f32 v151, v92, v93
	global_store_dwordx4 v[140:141], v[148:151], off offset:256
	s_nop 1
	v_or_b32_e32 v148, 16, v142
	v_ashrrev_i32_e32 v149, 31, v148
	v_lshlrev_b64 v[148:149], 11, v[148:149]
	v_lshl_add_u64 v[148:149], s[2:3], 0, v[148:149]
	v_lshl_add_u64 v[154:155], v[148:149], 0, v[152:153]
	v_cvt_pk_bf16_f32 v148, v118, v119
	v_cvt_pk_bf16_f32 v149, v120, v121
	v_cvt_pk_bf16_f32 v150, v114, v115
	v_cvt_pk_bf16_f32 v151, v116, v117
	global_store_dwordx4 v[154:155], v[148:151], off
	s_nop 1
	v_cvt_pk_bf16_f32 v148, v86, v87
	v_cvt_pk_bf16_f32 v149, v88, v89
	v_cvt_pk_bf16_f32 v150, v82, v83
	v_cvt_pk_bf16_f32 v151, v84, v85
	global_store_dwordx4 v[154:155], v[148:151], off offset:256
	s_nop 1
	v_or_b32_e32 v148, 32, v142
	v_ashrrev_i32_e32 v149, 31, v148
	v_lshlrev_b64 v[148:149], 11, v[148:149]
	v_or_b32_e32 v142, 48, v142
	v_lshl_add_u64 v[148:149], s[2:3], 0, v[148:149]
	v_ashrrev_i32_e32 v143, 31, v142
	v_lshl_add_u64 v[154:155], v[148:149], 0, v[152:153]
	v_cvt_pk_bf16_f32 v148, v110, v111
	v_cvt_pk_bf16_f32 v149, v112, v113
	v_cvt_pk_bf16_f32 v150, v106, v107
	v_cvt_pk_bf16_f32 v151, v108, v109
	v_lshlrev_b64 v[142:143], 11, v[142:143]
	global_store_dwordx4 v[154:155], v[148:151], off
	v_lshl_add_u64 v[142:143], s[2:3], 0, v[142:143]
	v_lshl_add_u64 v[142:143], v[142:143], 0, v[152:153]
	v_cvt_pk_bf16_f32 v148, v78, v79
	v_cvt_pk_bf16_f32 v149, v80, v81
	v_cvt_pk_bf16_f32 v150, v74, v75
	v_cvt_pk_bf16_f32 v151, v76, v77
	global_store_dwordx4 v[154:155], v[148:151], off offset:256
	s_mov_b64 s[2:3], 0x40000
	s_nop 0
	v_cvt_pk_bf16_f32 v148, v102, v103
	v_cvt_pk_bf16_f32 v149, v104, v105
	v_cvt_pk_bf16_f32 v150, v98, v99
	v_cvt_pk_bf16_f32 v151, v100, v101
	global_store_dwordx4 v[142:143], v[148:151], off
	s_nop 1
	v_cvt_pk_bf16_f32 v148, v70, v71
	v_cvt_pk_bf16_f32 v149, v72, v73
	v_cvt_pk_bf16_f32 v150, v66, v67
	v_cvt_pk_bf16_f32 v151, v68, v69
	global_store_dwordx4 v[142:143], v[148:151], off offset:256
	v_lshl_add_u64 v[142:143], v[140:141], 0, s[2:3]
	s_mov_b32 s2, 0x40000
	v_add_co_u32_e32 v152, vcc, s2, v140
	v_cvt_pk_bf16_f32 v148, v62, v63
	v_cvt_pk_bf16_f32 v149, v64, v65
	v_cvt_pk_bf16_f32 v150, v58, v59
	v_cvt_pk_bf16_f32 v151, v60, v61
	s_nop 1
	v_addc_co_u32_e32 v153, vcc, 0, v141, vcc
	global_store_dwordx4 v[152:153], v[148:151], off
	s_mov_b64 s[2:3], 0x48000
	v_add_co_u32_e32 v152, vcc, s43, v140
	v_cvt_pk_bf16_f32 v148, v30, v31
	v_cvt_pk_bf16_f32 v149, v32, v33
	v_cvt_pk_bf16_f32 v150, v26, v27
	v_cvt_pk_bf16_f32 v151, v28, v29
	global_store_dwordx4 v[142:143], v[148:151], off offset:256
	v_lshl_add_u64 v[142:143], v[140:141], 0, s[2:3]
	v_addc_co_u32_e32 v153, vcc, 0, v141, vcc
	v_cvt_pk_bf16_f32 v148, v54, v55
	v_cvt_pk_bf16_f32 v149, v56, v57
	v_cvt_pk_bf16_f32 v150, v50, v51
	v_cvt_pk_bf16_f32 v151, v52, v53
	s_mov_b64 s[2:3], 0x50000
	global_store_dwordx4 v[152:153], v[148:151], off
	s_nop 1
	v_cvt_pk_bf16_f32 v148, v22, v23
	v_cvt_pk_bf16_f32 v149, v24, v25
	v_cvt_pk_bf16_f32 v150, v18, v19
	v_cvt_pk_bf16_f32 v151, v20, v21
	global_store_dwordx4 v[142:143], v[148:151], off offset:256
	v_lshl_add_u64 v[142:143], v[140:141], 0, s[2:3]
	s_mov_b32 s2, 0x50000
	v_add_co_u32_e32 v152, vcc, s2, v140
	s_mov_b64 s[2:3], 0x58000
	s_nop 0
	v_addc_co_u32_e32 v153, vcc, 0, v141, vcc
	v_cvt_pk_bf16_f32 v148, v46, v47
	v_cvt_pk_bf16_f32 v149, v48, v49
	v_cvt_pk_bf16_f32 v150, v42, v43
	v_cvt_pk_bf16_f32 v151, v44, v45
	global_store_dwordx4 v[152:153], v[148:151], off
	v_lshl_add_u64 v[152:153], v[140:141], 0, s[2:3]
	s_mov_b32 s2, 0x58000
	v_add_co_u32_e32 v140, vcc, s2, v140
	v_cvt_pk_bf16_f32 v148, v14, v15
	v_cvt_pk_bf16_f32 v149, v16, v17
	v_cvt_pk_bf16_f32 v150, v10, v11
	v_cvt_pk_bf16_f32 v151, v12, v13
	s_nop 1
	v_addc_co_u32_e32 v141, vcc, 0, v141, vcc
	s_andn2_b64 vcc, exec, s[8:9]
	global_store_dwordx4 v[142:143], v[148:151], off offset:256
	v_cvt_pk_bf16_f32 v142, v2, v3
	v_cvt_pk_bf16_f32 v143, v4, v5
	s_nop 1
	v_cvt_pk_bf16_f32 v148, v38, v39
	v_cvt_pk_bf16_f32 v149, v40, v41
	v_cvt_pk_bf16_f32 v150, v34, v35
	v_cvt_pk_bf16_f32 v151, v36, v37
	global_store_dwordx4 v[140:141], v[148:151], off
	v_cvt_pk_bf16_f32 v140, v6, v7
	v_cvt_pk_bf16_f32 v141, v8, v9
	global_store_dwordx4 v[152:153], v[140:143], off offset:256
	s_cbranch_vccnz .LBB0_383
	v_mov_b32_e32 v2, 0
	s_mov_b32 s68, s76
	s_mov_b32 s67, s75
	s_mov_b64 s[0:1], s[10:11]
	s_mov_b32 s73, s77
	v_mov_b32_e32 v3, v2
	v_mov_b64_e32 v[4:5], 0
	v_mov_b64_e32 v[6:7], 0
	v_mov_b64_e32 v[8:9], 0
	v_mov_b64_e32 v[10:11], 0
	v_mov_b64_e32 v[12:13], 0
	v_mov_b64_e32 v[14:15], 0
	v_mov_b64_e32 v[16:17], 0
	v_mov_b64_e32 v[18:19], 0
	v_mov_b64_e32 v[20:21], 0
	v_mov_b64_e32 v[22:23], 0
	v_mov_b64_e32 v[24:25], 0
	v_mov_b64_e32 v[26:27], 0
	v_mov_b64_e32 v[28:29], 0
	v_mov_b64_e32 v[30:31], 0
	v_mov_b64_e32 v[32:33], 0
	v_mov_b64_e32 v[34:35], 0
	v_mov_b64_e32 v[36:37], 0
	v_mov_b64_e32 v[38:39], 0
	v_mov_b64_e32 v[40:41], 0
	v_mov_b64_e32 v[42:43], 0
	v_mov_b64_e32 v[44:45], 0
	v_mov_b64_e32 v[46:47], 0
	v_mov_b64_e32 v[48:49], 0
	v_mov_b64_e32 v[50:51], 0
	v_mov_b64_e32 v[52:53], 0
	v_mov_b64_e32 v[54:55], 0
	v_mov_b64_e32 v[56:57], 0
	v_mov_b64_e32 v[58:59], 0
	v_mov_b64_e32 v[60:61], 0
	v_mov_b64_e32 v[62:63], 0
	v_mov_b64_e32 v[64:65], 0
	v_mov_b64_e32 v[66:67], 0
	v_mov_b64_e32 v[68:69], 0
	v_mov_b64_e32 v[70:71], 0
	v_mov_b64_e32 v[72:73], 0
	v_mov_b64_e32 v[74:75], 0
	v_mov_b64_e32 v[76:77], 0
	v_mov_b64_e32 v[78:79], 0
	v_mov_b64_e32 v[80:81], 0
	v_mov_b64_e32 v[82:83], 0
	v_mov_b64_e32 v[84:85], 0
	v_mov_b64_e32 v[86:87], 0
	v_mov_b64_e32 v[88:89], 0
	v_mov_b64_e32 v[90:91], 0
	v_mov_b64_e32 v[92:93], 0
	v_mov_b64_e32 v[94:95], 0
	v_mov_b64_e32 v[96:97], 0
	v_mov_b64_e32 v[98:99], 0
	v_mov_b64_e32 v[100:101], 0
	v_mov_b64_e32 v[102:103], 0
	v_mov_b64_e32 v[104:105], 0
	v_mov_b64_e32 v[106:107], 0
	v_mov_b64_e32 v[108:109], 0
	v_mov_b64_e32 v[110:111], 0
	v_mov_b64_e32 v[112:113], 0
	v_mov_b64_e32 v[114:115], 0
	v_mov_b64_e32 v[116:117], 0
	v_mov_b64_e32 v[118:119], 0
	v_mov_b64_e32 v[120:121], 0
	v_mov_b64_e32 v[122:123], 0
	v_mov_b64_e32 v[124:125], 0
	v_mov_b64_e32 v[126:127], 0
	v_mov_b64_e32 v[128:129], 0
	s_branch .LBB0_384

; #define PG8_STAGE(bufoff, gbase, voff) do { _Pragma("unroll") for (int _i = 0; _i < 2; ++_i) \
;         __builtin_amdgcn_global_load_lds((const unsigned*)((const char*)(gbase) + (voff)[_i]), (LAS unsigned*)(lds + (bufoff) + ldsw + _i * 8192), 16, 0, 0); } while (0)
; #define PG8_STAGE_A(bufoff, gbase, h, vv) do { if constexpr (GATHER) { _Pragma("unroll") for (int _i = 0; _i < 2; ++_i) \
;         __builtin_amdgcn_global_load_lds((const unsigned*)((const char*)(gbase) + (vv)[h][_i]), (LAS unsigned*)(lds + (bufoff) + ldsw + _i * 8192), 16, 0, 0); } \
;         else { PG8_STAGE(bufoff, (gbase) + (h) * hstepA, voffA); } } while (0)
; #define PG8_WAIT_V(n) asm volatile("s_waitcnt vmcnt(" #n ")" ::: "memory")
; #define PG8_BAR __builtin_amdgcn_s_barrier()
; template <class Epi, class Sched>
; __device__ __forceinline__ void gemm_phase(LAS unsigned char* lds, const int K, const int lda, const int ldb, const Sched& S, const Epi& E) {
;     ...
;     PG8_STAGE(PG8_SB(0, 0), cB, voffB); PG8_STAGE_A(PG8_SA(0, 0), cA, 0, vcur); PG8_STAGE(PG8_SB(0, 1), cB + hstepB, voffB); PG8_STAGE_A(PG8_SA(0, 1), cA, 1, vcur);
;     if (wr == 1) PG8_BAR;
;     PG8_WAIT_V(4); PG8_BAR;
;     PG8_STAGE(PG8_SB(1, 0), cB + kstep, voffB); PG8_STAGE_A(PG8_SA(1, 0), cA + kstep, 0, vcur); PG8_STAGE(PG8_SB(1, 1), cB + hstepB + kstep, voffB);
;     PG8_WAIT_V(6); PG8_BAR;
;     ...
;         if (!has_next) break;
; #pragma unroll
;         for (int a = 0; a < 2; ++a)
; #pragma unroll
;             for (int b = 0; b < 2; ++b)
; #pragma unroll
;                 for (int m = 0; m < 4; ++m)
; #pragma unroll
;                     for (int n = 0; n < 2; ++n) acc[a][b][m][n] = (f32x4){0.f, 0.f, 0.f, 0.f};
;         cur = nxt; cA = nA; cB = nB; ++ui;
.LBB0_454:
	v_lshrrev_b32_e32 v8, 1, v2
	v_and_b32_e32 v8, 24, v8
	v_and_b32_e32 v3, 15, v2
	v_lshlrev_b32_e32 v9, 1, v8
	v_lshlrev_b32_e32 v2, 2, v2
	v_lshl_or_b32 v220, s0, 6, v3
	v_lshl_or_b32 v3, v3, 6, v9
	s_lshl_b32 s0, s0, 13
	v_and_b32_e32 v2, 32, v2
	v_bitop3_b32 v9, v3, s0, v2 bitop3:0xde
	s_lshl_b32 s0, s1, 5
	v_mov_b32_e32 v185, v1
	s_and_b32 s2, s0, 0x60
	v_lshl_add_u64 v[4:5], s[12:13], 0, v[184:185]
	v_mov_b32_e32 v187, v1
	s_lshl_b32 s0, s2, 7
	v_lshl_add_u64 v[6:7], s[12:13], 0, v[186:187]
	v_bitop3_b32 v221, v3, s0, v2 bitop3:0xde
	s_add_i32 m0, s19, 0x18000
	v_lshl_add_u64 v[2:3], v[4:5], 0, s[64:65]
	v_readlane_b32 s0, v250, 21
	v_mov_b32_e32 v179, v1
	s_waitcnt vmcnt(4)
	s_barrier
	global_load_lds_dwordx4 v[2:3], off
	v_lshl_add_u64 v[2:3], v[6:7], 0, s[64:65]
	s_add_i32 m0, s19, 0x1a000
	v_readlane_b32 s1, v250, 22
	s_add_i32 s41, s19, 0x8000
	v_mov_b32_e32 v181, v1
	global_load_lds_dwordx4 v[2:3], off
	v_lshl_add_u64 v[2:3], s[0:1], 0, v[178:179]
	s_mov_b32 m0, s41
	s_add_i32 s43, s19, 0xa000
	global_load_lds_dwordx4 v[2:3], off
	v_lshl_add_u64 v[2:3], s[0:1], 0, v[180:181]
	s_add_u32 s0, s12, 0x40080
	s_mov_b32 m0, s43
	s_addc_u32 s1, s13, 0
	global_load_lds_dwordx4 v[2:3], off
	s_add_i32 m0, s19, 0x1c000
	v_lshl_add_u64 v[2:3], s[0:1], 0, v[184:185]
	global_load_lds_dwordx4 v[2:3], off
	v_lshl_add_u64 v[2:3], s[0:1], 0, v[186:187]
	s_add_i32 m0, s19, 0x1e000
	s_ashr_i32 s68, s78, 3
	global_load_lds_dwordx4 v[2:3], off
	s_waitcnt vmcnt(6)
	s_and_b32 s69, s78, 4
	s_add_i32 s47, s68, 1
	v_mov_b32_e32 v2, 0
	s_mul_i32 s89, s47, s69
	v_or_b32_e32 v222, s2, v8
	s_mov_b32 s54, 0
	v_add_u32_e32 v223, 0, v9
	v_mov_b32_e32 v3, v2
	v_mov_b64_e32 v[4:5], 0
	v_mov_b64_e32 v[6:7], 0
	v_mov_b64_e32 v[8:9], 0
	v_mov_b64_e32 v[10:11], 0
	v_mov_b64_e32 v[12:13], 0
	v_mov_b64_e32 v[14:15], 0
	v_mov_b64_e32 v[16:17], 0
	v_mov_b64_e32 v[18:19], 0
	v_mov_b64_e32 v[20:21], 0
	v_mov_b64_e32 v[22:23], 0
	v_mov_b64_e32 v[24:25], 0
	v_mov_b64_e32 v[26:27], 0
	v_mov_b64_e32 v[28:29], 0
	v_mov_b64_e32 v[30:31], 0
	v_mov_b64_e32 v[32:33], 0
	v_mov_b64_e32 v[34:35], 0
	v_mov_b64_e32 v[36:37], 0
	v_mov_b64_e32 v[38:39], 0
	v_mov_b64_e32 v[40:41], 0
	v_mov_b64_e32 v[42:43], 0
	v_mov_b64_e32 v[44:45], 0
	v_mov_b64_e32 v[46:47], 0
	v_mov_b64_e32 v[48:49], 0
	v_mov_b64_e32 v[50:51], 0
	v_mov_b64_e32 v[52:53], 0
	v_mov_b64_e32 v[54:55], 0
	v_mov_b64_e32 v[56:57], 0
	v_mov_b64_e32 v[58:59], 0
	v_mov_b64_e32 v[60:61], 0
	v_mov_b64_e32 v[62:63], 0
	v_mov_b64_e32 v[64:65], 0
	v_mov_b64_e32 v[66:67], 0
	v_mov_b64_e32 v[68:69], 0
	v_mov_b64_e32 v[70:71], 0
	v_mov_b64_e32 v[72:73], 0
	v_mov_b64_e32 v[74:75], 0
	v_mov_b64_e32 v[76:77], 0
	v_mov_b64_e32 v[78:79], 0
	v_mov_b64_e32 v[80:81], 0
	v_mov_b64_e32 v[82:83], 0
	v_mov_b64_e32 v[84:85], 0
	v_mov_b64_e32 v[86:87], 0
	v_mov_b64_e32 v[88:89], 0
	v_mov_b64_e32 v[90:91], 0
	v_mov_b64_e32 v[92:93], 0
	v_mov_b64_e32 v[94:95], 0
	v_mov_b64_e32 v[96:97], 0
	v_mov_b64_e32 v[98:99], 0
	v_mov_b64_e32 v[100:101], 0
	v_mov_b64_e32 v[102:103], 0
	v_mov_b64_e32 v[104:105], 0
	v_mov_b64_e32 v[106:107], 0
	v_mov_b64_e32 v[108:109], 0
	v_mov_b64_e32 v[110:111], 0
	v_mov_b64_e32 v[112:113], 0
	v_mov_b64_e32 v[114:115], 0
	v_mov_b64_e32 v[116:117], 0
	v_mov_b64_e32 v[118:119], 0
	v_mov_b64_e32 v[120:121], 0
	v_mov_b64_e32 v[122:123], 0
	v_mov_b64_e32 v[124:125], 0
	v_mov_b64_e32 v[126:127], 0
	v_mov_b64_e32 v[128:129], 0
	s_mov_b64 s[10:11], s[12:13]
	s_barrier
	s_branch .LBB0_456
.LBB0_455:
	v_mov_b32_e32 v2, 0
	s_mov_b32 s4, s6
	s_mov_b32 s18, s75
	s_mov_b32 s54, s49
	v_mov_b32_e32 v3, v2
	v_mov_b64_e32 v[4:5], 0
	v_mov_b64_e32 v[6:7], 0
	v_mov_b64_e32 v[8:9], 0
	v_mov_b64_e32 v[10:11], 0
	v_mov_b64_e32 v[12:13], 0
	v_mov_b64_e32 v[14:15], 0
	v_mov_b64_e32 v[16:17], 0
	v_mov_b64_e32 v[18:19], 0
	v_mov_b64_e32 v[20:21], 0
	v_mov_b64_e32 v[22:23], 0
	v_mov_b64_e32 v[24:25], 0
	v_mov_b64_e32 v[26:27], 0
	v_mov_b64_e32 v[28:29], 0
	v_mov_b64_e32 v[30:31], 0
	v_mov_b64_e32 v[32:33], 0
	v_mov_b64_e32 v[34:35], 0
	v_mov_b64_e32 v[36:37], 0
	v_mov_b64_e32 v[38:39], 0
	v_mov_b64_e32 v[40:41], 0
	v_mov_b64_e32 v[42:43], 0
	v_mov_b64_e32 v[44:45], 0
	v_mov_b64_e32 v[46:47], 0
	v_mov_b64_e32 v[48:49], 0
	v_mov_b64_e32 v[50:51], 0
	v_mov_b64_e32 v[52:53], 0
	v_mov_b64_e32 v[54:55], 0
	v_mov_b64_e32 v[56:57], 0
	v_mov_b64_e32 v[58:59], 0
	v_mov_b64_e32 v[60:61], 0
	v_mov_b64_e32 v[62:63], 0
	v_mov_b64_e32 v[64:65], 0
	v_mov_b64_e32 v[66:67], 0
	v_mov_b64_e32 v[68:69], 0
	v_mov_b64_e32 v[70:71], 0
	v_mov_b64_e32 v[72:73], 0
	v_mov_b64_e32 v[74:75], 0
	v_mov_b64_e32 v[76:77], 0
	v_mov_b64_e32 v[78:79], 0
	v_mov_b64_e32 v[80:81], 0
	v_mov_b64_e32 v[82:83], 0
	v_mov_b64_e32 v[84:85], 0
	v_mov_b64_e32 v[86:87], 0
	v_mov_b64_e32 v[88:89], 0
	v_mov_b64_e32 v[90:91], 0
	v_mov_b64_e32 v[92:93], 0
	v_mov_b64_e32 v[94:95], 0
	v_mov_b64_e32 v[96:97], 0
	v_mov_b64_e32 v[98:99], 0
	v_mov_b64_e32 v[100:101], 0
	v_mov_b64_e32 v[102:103], 0
	v_mov_b64_e32 v[104:105], 0
	v_mov_b64_e32 v[106:107], 0
	v_mov_b64_e32 v[108:109], 0
	v_mov_b64_e32 v[110:111], 0
	v_mov_b64_e32 v[112:113], 0
	v_mov_b64_e32 v[114:115], 0
	v_mov_b64_e32 v[116:117], 0
	v_mov_b64_e32 v[118:119], 0
	v_mov_b64_e32 v[120:121], 0
	v_mov_b64_e32 v[122:123], 0
	v_mov_b64_e32 v[124:125], 0
	v_mov_b64_e32 v[126:127], 0
	v_mov_b64_e32 v[128:129], 0
	s_andn2_b64 vcc, exec, s[8:9]
	s_mov_b64 s[12:13], s[10:11]
	s_cbranch_vccz .LBB0_517
	s_cmpk_gt_u32 s88, 0xff
	s_cbranch_scc0 .LBB0_456
	s_barrier

; template <class Epi, class Sched>
; __device__ __forceinline__ void gemm_phase(LAS unsigned char* lds, const int K, const int lda, const int ldb, const Sched& S, const Epi& E) {
;     ...
; #pragma unroll
;         for (int a = 0; a < 2; ++a)
; #pragma unroll
;             for (int b = 0; b < 2; ++b)
; #pragma unroll
;                 for (int m = 0; m < 4; ++m)
; #pragma unroll
;                     for (int n = 0; n < 2; ++n) acc[a][b][m][n] = (f32x4){0.f, 0.f, 0.f, 0.f};
;         cur = nxt; cA = nA; cB = nB; ++ui;
.LBB0_710:
	s_add_u32 s12, s12, 0x40080
	s_addc_u32 s13, s13, 0
	s_add_u32 s1, s14, 0x100
	v_mov_b32_e32 v2, 0
	s_addc_u32 s42, s15, 0
	s_mov_b32 s43, -2
	v_mov_b32_e32 v3, v2
	v_mov_b32_e32 v4, v2
	v_mov_b32_e32 v5, v2
	v_mov_b32_e32 v22, v2
	v_mov_b32_e32 v23, v2
	v_mov_b32_e32 v24, v2
	v_mov_b32_e32 v25, v2
	v_mov_b32_e32 v6, v2
	v_mov_b32_e32 v7, v2
	v_mov_b32_e32 v8, v2
	v_mov_b32_e32 v9, v2
	v_mov_b32_e32 v30, v2
	v_mov_b32_e32 v31, v2
	v_mov_b32_e32 v32, v2
	v_mov_b32_e32 v33, v2
	v_mov_b32_e32 v10, v2
	v_mov_b32_e32 v11, v2
	v_mov_b32_e32 v12, v2
	v_mov_b32_e32 v13, v2
	s_waitcnt vmcnt(0)
	v_mov_b64_e32 v[38:39], 0
	v_mov_b64_e32 v[40:41], 0
	v_mov_b64_e32 v[14:15], 0
	v_mov_b64_e32 v[16:17], 0
	v_mov_b64_e32 v[46:47], 0
	v_mov_b64_e32 v[48:49], 0
	v_mov_b64_e32 v[58:59], 0
	v_mov_b64_e32 v[60:61], 0
	v_mov_b64_e32 v[86:87], 0
	v_mov_b64_e32 v[88:89], 0
	v_mov_b64_e32 v[66:67], 0
	v_mov_b64_e32 v[68:69], 0
	v_mov_b64_e32 v[90:91], 0
	v_mov_b64_e32 v[92:93], 0
	v_mov_b64_e32 v[74:75], 0
	v_mov_b64_e32 v[76:77], 0
	v_mov_b64_e32 v[98:99], 0
	v_mov_b64_e32 v[100:101], 0
	v_mov_b64_e32 v[78:79], 0
	v_mov_b64_e32 v[80:81], 0
	v_mov_b64_e32 v[102:103], 0
	v_mov_b64_e32 v[104:105], 0
	v_mov_b64_e32 v[18:19], 0
	v_mov_b64_e32 v[20:21], 0
	v_mov_b64_e32 v[50:51], 0
	v_mov_b64_e32 v[52:53], 0
	v_mov_b64_e32 v[26:27], 0
	v_mov_b64_e32 v[28:29], 0
	v_mov_b64_e32 v[54:55], 0
	v_mov_b64_e32 v[56:57], 0
	v_mov_b64_e32 v[34:35], 0
	v_mov_b64_e32 v[36:37], 0
	v_mov_b64_e32 v[62:63], 0
	v_mov_b64_e32 v[64:65], 0
	v_mov_b64_e32 v[42:43], 0
	v_mov_b64_e32 v[44:45], 0
	v_mov_b64_e32 v[70:71], 0
	v_mov_b64_e32 v[72:73], 0
	v_mov_b64_e32 v[82:83], 0
	v_mov_b64_e32 v[84:85], 0
	v_mov_b64_e32 v[114:115], 0
	v_mov_b64_e32 v[116:117], 0
	v_mov_b64_e32 v[94:95], 0
	v_mov_b64_e32 v[96:97], 0
	v_mov_b64_e32 v[118:119], 0
	v_mov_b64_e32 v[120:121], 0
	v_mov_b64_e32 v[106:107], 0
	v_mov_b64_e32 v[108:109], 0
	v_mov_b64_e32 v[122:123], 0
	v_mov_b64_e32 v[124:125], 0
	v_mov_b64_e32 v[110:111], 0
	v_mov_b64_e32 v[112:113], 0
	v_mov_b64_e32 v[126:127], 0
	v_mov_b64_e32 v[128:129], 0

; #define PG8_STAGE(bufoff, gbase, voff) do { _Pragma("unroll") for (int _i = 0; _i < 2; ++_i) \
;         __builtin_amdgcn_global_load_lds((const unsigned*)((const char*)(gbase) + (voff)[_i]), (LAS unsigned*)(lds + (bufoff) + ldsw + _i * 8192), 16, 0, 0); } while (0)
; #define PG8_STAGE_A(bufoff, gbase, h, vv) do { if constexpr (GATHER) { _Pragma("unroll") for (int _i = 0; _i < 2; ++_i) \
;         __builtin_amdgcn_global_load_lds((const unsigned*)((const char*)(gbase) + (vv)[h][_i]), (LAS unsigned*)(lds + (bufoff) + ldsw + _i * 8192), 16, 0, 0); } \
;         else { PG8_STAGE(bufoff, (gbase) + (h) * hstepA, voffA); } } while (0)
; #define PG8_WAIT_L(n) asm volatile("s_waitcnt lgkmcnt(" #n ")" ::: "memory")
; #define PG8_BAR __builtin_amdgcn_s_barrier()
; #define PG8_SCHED __builtin_amdgcn_sched_barrier(0)
; template <class Epi, class Sched>
; __device__ __forceinline__ void gemm_phase(LAS unsigned char* lds, const int K, const int lda, const int ldb, const Sched& S, const Epi& E) {
;     ...
;         for (int t = 0; t < nt; t += 2) {
;             const bool last = (t == nt - 2);
;             const char* a1 = cA + (size_t)(t + 1) * kstep;
;             const char* a2 = last ? nA : cA + (size_t)(t + 2) * kstep; const char* b2 = last ? nB : cB + (size_t)(t + 2) * kstep;
;             const char* a3 = a2 + kstep; const char* b3 = b2 + kstep;
;             PG8_LDB(B0, 0, 0); PG8_SCHED; PG8_LDA(At, 0, 0); PG8_STAGE_A(PG8_SA(1, 1), a1, 1, vcur);
;             if constexpr (GATHER) { if (last) {
; #pragma unroll
;                 for (int h = 0; h < 2; ++h)
; #pragma unroll
;                     for (int i = 0; i < 2; ++i) vcur[h][i] = vnxt[h][i]; } }
;             PG8_WAIT_L(8); PG8_BAR; PG8_WAIT_L(0); PG8_MMA(0, 0, At, B0); PG8_BAR; PG8_SCHED;
;             PG8_LDB(B1, 0, 1); PG8_STAGE(PG8_SB(0, 0), b2, voffB);
;             PG8_BAR; PG8_WAIT_L(0); PG8_MMA(0, 1, At, B1); PG8_BAR;
;             PG8_LDA(At, 0, 1); PG8_STAGE_A(PG8_SA(0, 0), a2, 0, vcur);
;             PG8_BAR; PG8_WAIT_L(0); PG8_MMA(1, 0, At, B0); PG8_BAR; PG8_SCHED;
;     ...
; #pragma unroll
;         for (int a = 0; a < 2; ++a)
; #pragma unroll
;             for (int b = 0; b < 2; ++b)
; #pragma unroll
;                 for (int m = 0; m < 4; ++m)
; #pragma unroll
;                     for (int n = 0; n < 2; ++n) acc[a][b][m][n] = (f32x4){0.f, 0.f, 0.f, 0.f};
;         cur = nxt; cA = nA; cB = nB; ++ui;
.LBB0_760:
	s_add_u32 s16, s16, 0x40080
	s_addc_u32 s17, s17, 0
	s_add_u32 s7, s34, 0x100
	v_mov_b32_e32 v2, 0
	s_addc_u32 s11, s35, 0
	s_mov_b32 s68, -2
	v_mov_b32_e32 v3, v2
	v_mov_b64_e32 v[4:5], 0
	v_mov_b64_e32 v[6:7], 0
	v_mov_b64_e32 v[8:9], 0
	v_mov_b64_e32 v[10:11], 0
	v_mov_b64_e32 v[12:13], 0
	v_mov_b64_e32 v[18:19], 0
	v_mov_b64_e32 v[20:21], 0
	v_mov_b64_e32 v[26:27], 0
	v_mov_b64_e32 v[28:29], 0
	v_mov_b64_e32 v[34:35], 0
	v_mov_b64_e32 v[36:37], 0
	v_mov_b64_e32 v[42:43], 0
	v_mov_b64_e32 v[44:45], 0
	v_mov_b64_e32 v[50:51], 0
	v_mov_b64_e32 v[52:53], 0
	v_mov_b64_e32 v[14:15], 0
	v_mov_b64_e32 v[16:17], 0
	v_mov_b64_e32 v[22:23], 0
	v_mov_b64_e32 v[24:25], 0
	v_mov_b64_e32 v[30:31], 0
	v_mov_b64_e32 v[32:33], 0
	v_mov_b64_e32 v[38:39], 0
	v_mov_b64_e32 v[40:41], 0
	v_mov_b64_e32 v[46:47], 0
	v_mov_b64_e32 v[48:49], 0
	v_mov_b64_e32 v[54:55], 0
	v_mov_b64_e32 v[56:57], 0
	v_mov_b64_e32 v[58:59], 0
	v_mov_b64_e32 v[60:61], 0
	v_mov_b64_e32 v[62:63], 0
	v_mov_b64_e32 v[64:65], 0
	v_mov_b64_e32 v[66:67], 0
	v_mov_b64_e32 v[68:69], 0
	v_mov_b64_e32 v[70:71], 0
	v_mov_b64_e32 v[72:73], 0
	v_mov_b64_e32 v[74:75], 0
	v_mov_b64_e32 v[76:77], 0
	v_mov_b64_e32 v[82:83], 0
	v_mov_b64_e32 v[84:85], 0
	v_mov_b64_e32 v[90:91], 0
	v_mov_b64_e32 v[92:93], 0
	v_mov_b64_e32 v[98:99], 0
	v_mov_b64_e32 v[100:101], 0
	v_mov_b64_e32 v[106:107], 0
	v_mov_b64_e32 v[108:109], 0
	v_mov_b64_e32 v[114:115], 0
	v_mov_b64_e32 v[116:117], 0
	v_mov_b64_e32 v[78:79], 0
	v_mov_b64_e32 v[80:81], 0
	v_mov_b64_e32 v[86:87], 0
	v_mov_b64_e32 v[88:89], 0
	v_mov_b64_e32 v[94:95], 0
	v_mov_b64_e32 v[96:97], 0
	v_mov_b64_e32 v[102:103], 0
	v_mov_b64_e32 v[104:105], 0
	v_mov_b64_e32 v[110:111], 0
	v_mov_b64_e32 v[112:113], 0
	v_mov_b64_e32 v[118:119], 0
	v_mov_b64_e32 v[120:121], 0
	v_mov_b64_e32 v[122:123], 0
	v_mov_b64_e32 v[124:125], 0
	v_mov_b64_e32 v[126:127], 0
	v_mov_b64_e32 v[128:129], 0
.LBB0_761:
	s_add_u32 s2, s16, 0xfffc0080
	s_addc_u32 s3, s17, -1
	s_add_i32 s20, 0, 0x10000
	v_add_u32_e32 v140, s20, v143
	ds_read_b128 v[146:149], v140
	ds_read_b128 v[150:153], v140 offset:1024
	ds_read_b128 v[154:157], v140 offset:2048
	ds_read_b128 v[158:161], v140 offset:3072
	s_cmp_eq_u32 s68, 12
	s_cselect_b32 s37, s13, s3
	s_cselect_b32 s36, s12, s2
	s_cselect_b32 s35, s15, s11
	s_cselect_b32 s34, s14, s7
	v_lshl_add_u64 v[140:141], s[16:17], 0, v[136:137]
	s_add_i32 m0, s9, 0xc000
	ds_read_b128 v[162:165], v145
	ds_read_b128 v[166:169], v145 offset:1024
	ds_read_b128 v[170:173], v145 offset:2048
	ds_read_b128 v[174:177], v145 offset:3072
	ds_read_b128 v[178:181], v145 offset:4096
	ds_read_b128 v[182:185], v145 offset:5120
	ds_read_b128 v[186:189], v145 offset:6144
	ds_read_b128 v[190:193], v145 offset:7168
	global_load_lds_dwordx4 v[140:141], off
	v_lshl_add_u64 v[140:141], s[16:17], 0, v[138:139]
	s_add_i32 m0, s9, 0xe000
	s_nop 0
	global_load_lds_dwordx4 v[140:141], off
	s_waitcnt lgkmcnt(8)
	s_barrier
	s_waitcnt lgkmcnt(0)
	s_setprio 1
	s_waitcnt lgkmcnt(0)
	v_mfma_f32_16x16x32_bf16 v[126:129], v[146:149], v[162:165], v[126:129]
	v_mfma_f32_16x16x32_bf16 v[122:125], v[154:157], v[162:165], v[122:125]
	v_mfma_f32_16x16x32_bf16 v[118:121], v[146:149], v[170:173], v[118:121]
	v_mfma_f32_16x16x32_bf16 v[110:113], v[154:157], v[170:173], v[110:113]
	v_mfma_f32_16x16x32_bf16 v[102:105], v[146:149], v[178:181], v[102:105]
	v_mfma_f32_16x16x32_bf16 v[94:97], v[154:157], v[178:181], v[94:97]
	v_mfma_f32_16x16x32_bf16 v[86:89], v[146:149], v[186:189], v[86:89]
	v_mfma_f32_16x16x32_bf16 v[78:81], v[154:157], v[186:189], v[78:81]
	v_mfma_f32_16x16x32_bf16 v[126:129], v[150:153], v[166:169], v[126:129]
	v_mfma_f32_16x16x32_bf16 v[122:125], v[158:161], v[166:169], v[122:125]
	v_mfma_f32_16x16x32_bf16 v[118:121], v[150:153], v[174:177], v[118:121]
	v_mfma_f32_16x16x32_bf16 v[110:113], v[158:161], v[174:177], v[110:113]
	v_mfma_f32_16x16x32_bf16 v[102:105], v[150:153], v[182:185], v[102:105]
	v_mfma_f32_16x16x32_bf16 v[94:97], v[158:161], v[182:185], v[94:97]
	v_mfma_f32_16x16x32_bf16 v[86:89], v[150:153], v[190:193], v[86:89]
	v_mfma_f32_16x16x32_bf16 v[78:81], v[158:161], v[190:193], v[78:81]
	s_setprio 0
	s_barrier
	s_add_i32 s2, 0, 0x14000
	v_add_u32_e32 v140, s2, v143
	s_add_i32 s3, s20, s49
	ds_read_b128 v[216:219], v140
	ds_read_b128 v[220:223], v140 offset:1024
	ds_read_b128 v[224:227], v140 offset:2048
	ds_read_b128 v[228:231], v140 offset:3072
	v_lshl_add_u64 v[140:141], s[34:35], 0, v[0:1]
	s_mov_b32 m0, s3
	v_lshl_add_u64 v[194:195], s[34:35], 0, v[134:135]
	global_load_lds_dwordx4 v[140:141], off
	s_add_i32 m0, s3, 0x2000
	s_nop 0
	global_load_lds_dwordx4 v[194:195], off
	s_barrier
	s_waitcnt lgkmcnt(0)
	s_setprio 1
	s_waitcnt lgkmcnt(0)
	v_mfma_f32_16x16x32_bf16 v[114:117], v[216:219], v[162:165], v[114:117]
	v_mfma_f32_16x16x32_bf16 v[106:109], v[224:227], v[162:165], v[106:109]
	v_mfma_f32_16x16x32_bf16 v[98:101], v[216:219], v[170:173], v[98:101]
	v_mfma_f32_16x16x32_bf16 v[90:93], v[224:227], v[170:173], v[90:93]
	v_mfma_f32_16x16x32_bf16 v[82:85], v[216:219], v[178:181], v[82:85]
	v_mfma_f32_16x16x32_bf16 v[74:77], v[224:227], v[178:181], v[74:77]
	v_mfma_f32_16x16x32_bf16 v[70:73], v[216:219], v[186:189], v[70:73]
	v_mfma_f32_16x16x32_bf16 v[66:69], v[224:227], v[186:189], v[66:69]
	v_mfma_f32_16x16x32_bf16 v[114:117], v[220:223], v[166:169], v[114:117]
	v_mfma_f32_16x16x32_bf16 v[106:109], v[228:231], v[166:169], v[106:109]
	v_mfma_f32_16x16x32_bf16 v[98:101], v[220:223], v[174:177], v[98:101]
	v_mfma_f32_16x16x32_bf16 v[90:93], v[228:231], v[174:177], v[90:93]
	v_mfma_f32_16x16x32_bf16 v[82:85], v[220:223], v[182:185], v[82:85]
	v_mfma_f32_16x16x32_bf16 v[74:77], v[228:231], v[182:185], v[74:77]
	v_mfma_f32_16x16x32_bf16 v[70:73], v[220:223], v[190:193], v[70:73]
	v_mfma_f32_16x16x32_bf16 v[66:69], v[228:231], v[190:193], v[66:69]
	s_setprio 0
	s_mov_b32 m0, s9
	v_lshl_add_u64 v[214:215], s[36:37], 0, v[130:131]
	s_barrier
; #define PG8_STAGE(bufoff, gbase, voff) do { _Pragma("unroll") for (int _i = 0; _i < 2; ++_i) \
;         __builtin_amdgcn_global_load_lds((const unsigned*)((const char*)(gbase) + (voff)[_i]), (LAS unsigned*)(lds + (bufoff) + ldsw + _i * 8192), 16, 0, 0); } while (0)
; #define PG8_STAGE_A(bufoff, gbase, h, vv) do { if constexpr (GATHER) { _Pragma("unroll") for (int _i = 0; _i < 2; ++_i) \
;         __builtin_amdgcn_global_load_lds((const unsigned*)((const char*)(gbase) + (vv)[h][_i]), (LAS unsigned*)(lds + (bufoff) + ldsw + _i * 8192), 16, 0, 0); } \
;         else { PG8_STAGE(bufoff, (gbase) + (h) * hstepA, voffA); } } while (0)
; #define PG8_LDA(dst, b, h) do { _Pragma("unroll") for (int m = 0; m < 4; ++m) _Pragma("unroll") for (int k = 0; k < 2; ++k) dst[m][k] = *(const LAS bf16x8*)(lds + PG8_SA(b, h) + aoff + m * 2048 + k * 1024); } while (0)
; #define PG8_LDB(dst, b, h) do { _Pragma("unroll") for (int n = 0; n < 2; ++n) _Pragma("unroll") for (int k = 0; k < 2; ++k) dst[n][k] = *(const LAS bf16x8*)(lds + PG8_SB(b, h) + boff + n * 2048 + k * 1024); } while (0)
; #define PG8_WAIT_V(n) asm volatile("s_waitcnt vmcnt(" #n ")" ::: "memory")
; #define PG8_WAIT_L(n) asm volatile("s_waitcnt lgkmcnt(" #n ")" ::: "memory")
; #define PG8_BAR __builtin_amdgcn_s_barrier()
; #define PG8_SCHED __builtin_amdgcn_sched_barrier(0)
; template <class Epi, class Sched>
; __device__ __forceinline__ void gemm_phase(LAS unsigned char* lds, const int K, const int lda, const int ldb, const Sched& S, const Epi& E) {
;     ...
;             PG8_LDA(At, 0, 1); PG8_STAGE_A(PG8_SA(0, 0), a2, 0, vcur);
;             PG8_BAR; PG8_WAIT_L(0); PG8_MMA(1, 0, At, B0); PG8_BAR; PG8_SCHED;
;             PG8_STAGE(PG8_SB(0, 1), b2 + hstepB, voffB);
;             PG8_WAIT_V(6); PG8_BAR; PG8_MMA(1, 1, At, B1); PG8_BAR;
;             PG8_LDB(B0, 1, 0); PG8_SCHED; PG8_LDA(At, 1, 0); PG8_STAGE_A(PG8_SA(0, 1), a2, 1, vcur);
;             PG8_WAIT_L(8); PG8_BAR; PG8_WAIT_L(0); PG8_MMA(0, 0, At, B0); PG8_BAR; PG8_SCHED;
;             PG8_LDB(B1, 1, 1); PG8_STAGE(PG8_SB(1, 0), b3, voffB);
;             PG8_BAR; PG8_WAIT_L(0); PG8_MMA(0, 1, At, B1); PG8_BAR;
;             PG8_LDA(At, 1, 1); PG8_STAGE_A(PG8_SA(1, 0), a3, 0, vcur);
;             PG8_BAR; PG8_WAIT_L(0); PG8_MMA(1, 0, At, B0); PG8_BAR; PG8_SCHED;
	ds_read_b128 v[162:165], v145 offset:16384
	ds_read_b128 v[166:169], v145 offset:17408
	ds_read_b128 v[170:173], v145 offset:18432
	ds_read_b128 v[174:177], v145 offset:19456
	ds_read_b128 v[178:181], v145 offset:20480
	ds_read_b128 v[182:185], v145 offset:21504
	ds_read_b128 v[186:189], v145 offset:22528
	ds_read_b128 v[190:193], v145 offset:23552
	global_load_lds_dwordx4 v[214:215], off
	v_lshl_add_u64 v[232:233], s[36:37], 0, v[132:133]
	s_mov_b32 m0, s53
	s_nop 0
	global_load_lds_dwordx4 v[232:233], off
	s_barrier
	s_waitcnt lgkmcnt(0)
	s_setprio 1
	s_waitcnt lgkmcnt(0)
	v_mfma_f32_16x16x32_bf16 v[62:65], v[146:149], v[162:165], v[62:65]
	v_mfma_f32_16x16x32_bf16 v[58:61], v[154:157], v[162:165], v[58:61]
	v_mfma_f32_16x16x32_bf16 v[54:57], v[146:149], v[170:173], v[54:57]
	v_mfma_f32_16x16x32_bf16 v[46:49], v[154:157], v[170:173], v[46:49]
	v_mfma_f32_16x16x32_bf16 v[38:41], v[146:149], v[178:181], v[38:41]
	v_mfma_f32_16x16x32_bf16 v[30:33], v[154:157], v[178:181], v[30:33]
	v_mfma_f32_16x16x32_bf16 v[22:25], v[146:149], v[186:189], v[22:25]
	v_mfma_f32_16x16x32_bf16 v[14:17], v[154:157], v[186:189], v[14:17]
	v_mfma_f32_16x16x32_bf16 v[62:65], v[150:153], v[166:169], v[62:65]
	v_mfma_f32_16x16x32_bf16 v[58:61], v[158:161], v[166:169], v[58:61]
	v_mfma_f32_16x16x32_bf16 v[54:57], v[150:153], v[174:177], v[54:57]
	v_mfma_f32_16x16x32_bf16 v[46:49], v[158:161], v[174:177], v[46:49]
	v_mfma_f32_16x16x32_bf16 v[38:41], v[150:153], v[182:185], v[38:41]
	v_mfma_f32_16x16x32_bf16 v[30:33], v[158:161], v[182:185], v[30:33]
	v_mfma_f32_16x16x32_bf16 v[22:25], v[150:153], v[190:193], v[22:25]
	v_mfma_f32_16x16x32_bf16 v[14:17], v[158:161], v[190:193], v[14:17]
	s_setprio 0
	s_barrier
	s_add_u32 s70, s34, 0x40000
	s_addc_u32 s71, s35, 0
	s_add_i32 s2, s2, s49
	v_lshl_add_u64 v[146:147], s[70:71], 0, v[0:1]
	s_mov_b32 m0, s2
	s_nop 0
	global_load_lds_dwordx4 v[146:147], off
	v_lshl_add_u64 v[146:147], s[70:71], 0, v[134:135]
	s_add_i32 m0, s2, 0x2000
	s_nop 0
	global_load_lds_dwordx4 v[146:147], off
	s_waitcnt vmcnt(6)
	s_barrier
	s_setprio 1
	v_mfma_f32_16x16x32_bf16 v[50:53], v[216:219], v[162:165], v[50:53]
	v_mfma_f32_16x16x32_bf16 v[42:45], v[224:227], v[162:165], v[42:45]
	v_mfma_f32_16x16x32_bf16 v[34:37], v[216:219], v[170:173], v[34:37]
	v_mfma_f32_16x16x32_bf16 v[26:29], v[224:227], v[170:173], v[26:29]
	v_mfma_f32_16x16x32_bf16 v[18:21], v[216:219], v[178:181], v[18:21]
	v_mfma_f32_16x16x32_bf16 v[10:13], v[224:227], v[178:181], v[10:13]
	v_mfma_f32_16x16x32_bf16 v[6:9], v[216:219], v[186:189], v[6:9]
	v_mfma_f32_16x16x32_bf16 v[2:5], v[224:227], v[186:189], v[2:5]
	v_mfma_f32_16x16x32_bf16 v[50:53], v[220:223], v[166:169], v[50:53]
	v_mfma_f32_16x16x32_bf16 v[42:45], v[228:231], v[166:169], v[42:45]
	v_mfma_f32_16x16x32_bf16 v[34:37], v[220:223], v[174:177], v[34:37]
	v_mfma_f32_16x16x32_bf16 v[26:29], v[228:231], v[174:177], v[26:29]
	v_mfma_f32_16x16x32_bf16 v[18:21], v[220:223], v[182:185], v[18:21]
	v_mfma_f32_16x16x32_bf16 v[10:13], v[228:231], v[182:185], v[10:13]
	v_mfma_f32_16x16x32_bf16 v[6:9], v[220:223], v[190:193], v[6:9]
	v_mfma_f32_16x16x32_bf16 v[2:5], v[228:231], v[190:193], v[2:5]
	s_setprio 0
	s_add_i32 s2, 0, 0x18000
	v_add_u32_e32 v158, s2, v143
	s_barrier
	ds_read_b128 v[146:149], v158
	ds_read_b128 v[150:153], v158 offset:1024
	ds_read_b128 v[154:157], v158 offset:2048
	ds_read_b128 v[158:161], v158 offset:3072
	s_add_u32 s36, s36, 0x40000
	s_addc_u32 s37, s37, 0
	s_mov_b32 m0, s54
	v_lshl_add_u64 v[216:217], s[36:37], 0, v[130:131]
	ds_read_b128 v[162:165], v145 offset:32768
	ds_read_b128 v[166:169], v145 offset:33792
	ds_read_b128 v[170:173], v145 offset:34816
	ds_read_b128 v[174:177], v145 offset:35840
	ds_read_b128 v[178:181], v145 offset:36864
	ds_read_b128 v[182:185], v145 offset:37888
	ds_read_b128 v[186:189], v145 offset:38912
	ds_read_b128 v[190:193], v145 offset:39936
	global_load_lds_dwordx4 v[216:217], off
	v_lshl_add_u64 v[216:217], s[36:37], 0, v[132:133]
	s_mov_b32 m0, s55
	s_nop 0
	global_load_lds_dwordx4 v[216:217], off
	s_waitcnt lgkmcnt(8)
	s_barrier
	s_waitcnt lgkmcnt(0)
	s_setprio 1
	s_waitcnt lgkmcnt(0)
	v_mfma_f32_16x16x32_bf16 v[126:129], v[146:149], v[162:165], v[126:129]
	v_mfma_f32_16x16x32_bf16 v[122:125], v[154:157], v[162:165], v[122:125]
	v_mfma_f32_16x16x32_bf16 v[118:121], v[146:149], v[170:173], v[118:121]
	v_mfma_f32_16x16x32_bf16 v[110:113], v[154:157], v[170:173], v[110:113]
	v_mfma_f32_16x16x32_bf16 v[102:105], v[146:149], v[178:181], v[102:105]
	v_mfma_f32_16x16x32_bf16 v[94:97], v[154:157], v[178:181], v[94:97]
	v_mfma_f32_16x16x32_bf16 v[86:89], v[146:149], v[186:189], v[86:89]
	v_mfma_f32_16x16x32_bf16 v[78:81], v[154:157], v[186:189], v[78:81]
	v_mfma_f32_16x16x32_bf16 v[126:129], v[150:153], v[166:169], v[126:129]
	v_mfma_f32_16x16x32_bf16 v[122:125], v[158:161], v[166:169], v[122:125]
	v_mfma_f32_16x16x32_bf16 v[118:121], v[150:153], v[174:177], v[118:121]
	v_mfma_f32_16x16x32_bf16 v[110:113], v[158:161], v[174:177], v[110:113]
	v_mfma_f32_16x16x32_bf16 v[102:105], v[150:153], v[182:185], v[102:105]
	v_mfma_f32_16x16x32_bf16 v[94:97], v[158:161], v[182:185], v[94:97]
	v_mfma_f32_16x16x32_bf16 v[86:89], v[150:153], v[190:193], v[86:89]
	v_mfma_f32_16x16x32_bf16 v[78:81], v[158:161], v[190:193], v[78:81]
	s_setprio 0
	s_barrier
	s_add_i32 s3, 0, 0x1c000
	s_add_i32 s2, s2, s49
	v_add_u32_e32 v228, s3, v143
	v_lshl_add_u64 v[140:141], v[140:141], 0, s[64:65]
	s_mov_b32 m0, s2
	ds_read_b128 v[216:219], v228
	ds_read_b128 v[220:223], v228 offset:1024
	ds_read_b128 v[224:227], v228 offset:2048
	ds_read_b128 v[228:231], v228 offset:3072
	global_load_lds_dwordx4 v[140:141], off
	v_lshl_add_u64 v[140:141], v[194:195], 0, s[64:65]
	s_add_i32 m0, s2, 0x2000
	s_nop 0
	global_load_lds_dwordx4 v[140:141], off
	s_barrier
; #define PG8_STAGE(bufoff, gbase, voff) do { _Pragma("unroll") for (int _i = 0; _i < 2; ++_i) \
;         __builtin_amdgcn_global_load_lds((const unsigned*)((const char*)(gbase) + (voff)[_i]), (LAS unsigned*)(lds + (bufoff) + ldsw + _i * 8192), 16, 0, 0); } while (0)
; #define PG8_STAGE_A(bufoff, gbase, h, vv) do { if constexpr (GATHER) { _Pragma("unroll") for (int _i = 0; _i < 2; ++_i) \
;         __builtin_amdgcn_global_load_lds((const unsigned*)((const char*)(gbase) + (vv)[h][_i]), (LAS unsigned*)(lds + (bufoff) + ldsw + _i * 8192), 16, 0, 0); } \
;         else { PG8_STAGE(bufoff, (gbase) + (h) * hstepA, voffA); } } while (0)
; #define PG8_LDA(dst, b, h) do { _Pragma("unroll") for (int m = 0; m < 4; ++m) _Pragma("unroll") for (int k = 0; k < 2; ++k) dst[m][k] = *(const LAS bf16x8*)(lds + PG8_SA(b, h) + aoff + m * 2048 + k * 1024); } while (0)
; #define PG8_MMA(ai, bj, At, Bt) do { __builtin_amdgcn_s_setprio(1); _Pragma("unroll") for (int m = 0; m < 4; ++m) _Pragma("unroll") for (int n = 0; n < 2; ++n) _Pragma("unroll") for (int k = 0; k < 2; ++k) \
;         acc[ai][bj][m][n] = __builtin_amdgcn_mfma_f32_16x16x32_bf16(Bt[n][k], At[m][k], acc[ai][bj][m][n], 0, 0, 0); __builtin_amdgcn_s_setprio(0); } while (0)
; #define PG8_WAIT_V(n) asm volatile("s_waitcnt vmcnt(" #n ")" ::: "memory")
; #define PG8_WAIT_L(n) asm volatile("s_waitcnt lgkmcnt(" #n ")" ::: "memory")
; #define PG8_BAR __builtin_amdgcn_s_barrier()
; #define PG8_SCHED __builtin_amdgcn_sched_barrier(0)
; template <class Epi, class Sched>
; __device__ __forceinline__ void gemm_phase(LAS unsigned char* lds, const int K, const int lda, const int ldb, const Sched& S, const Epi& E) {
;     ...
;             PG8_BAR; PG8_WAIT_L(0); PG8_MMA(0, 1, At, B1); PG8_BAR;
;             PG8_LDA(At, 1, 1); PG8_STAGE_A(PG8_SA(1, 0), a3, 0, vcur);
;             PG8_BAR; PG8_WAIT_L(0); PG8_MMA(1, 0, At, B0); PG8_BAR; PG8_SCHED;
;             PG8_STAGE(PG8_SB(1, 1), b3 + hstepB, voffB);
;             PG8_WAIT_V(6); PG8_BAR; PG8_MMA(1, 1, At, B1); PG8_BAR;
;         }
;     ...
;     PG8_WAIT_V(0);
;     if (wr == 0) PG8_BAR;
;     PG8_BAR;
	s_waitcnt lgkmcnt(0)
	s_setprio 1
	s_waitcnt lgkmcnt(0)
	v_mfma_f32_16x16x32_bf16 v[114:117], v[216:219], v[162:165], v[114:117]
	v_mfma_f32_16x16x32_bf16 v[106:109], v[224:227], v[162:165], v[106:109]
	v_mfma_f32_16x16x32_bf16 v[98:101], v[216:219], v[170:173], v[98:101]
	v_mfma_f32_16x16x32_bf16 v[90:93], v[224:227], v[170:173], v[90:93]
	v_mfma_f32_16x16x32_bf16 v[82:85], v[216:219], v[178:181], v[82:85]
	v_mfma_f32_16x16x32_bf16 v[74:77], v[224:227], v[178:181], v[74:77]
	v_mfma_f32_16x16x32_bf16 v[70:73], v[216:219], v[186:189], v[70:73]
	v_mfma_f32_16x16x32_bf16 v[66:69], v[224:227], v[186:189], v[66:69]
	v_mfma_f32_16x16x32_bf16 v[114:117], v[220:223], v[166:169], v[114:117]
	v_mfma_f32_16x16x32_bf16 v[106:109], v[228:231], v[166:169], v[106:109]
	v_mfma_f32_16x16x32_bf16 v[98:101], v[220:223], v[174:177], v[98:101]
	v_mfma_f32_16x16x32_bf16 v[90:93], v[228:231], v[174:177], v[90:93]
	v_mfma_f32_16x16x32_bf16 v[82:85], v[220:223], v[182:185], v[82:85]
	v_mfma_f32_16x16x32_bf16 v[74:77], v[228:231], v[182:185], v[74:77]
	v_mfma_f32_16x16x32_bf16 v[70:73], v[220:223], v[190:193], v[70:73]
	v_mfma_f32_16x16x32_bf16 v[66:69], v[228:231], v[190:193], v[66:69]
	s_setprio 0
	s_mov_b32 m0, s63
	v_lshl_add_u64 v[140:141], v[214:215], 0, s[64:65]
	s_barrier
	ds_read_b128 v[162:165], v145 offset:49152
	ds_read_b128 v[166:169], v145 offset:50176
	ds_read_b128 v[170:173], v145 offset:51200
	ds_read_b128 v[174:177], v145 offset:52224
	ds_read_b128 v[178:181], v145 offset:53248
	ds_read_b128 v[182:185], v145 offset:54272
	ds_read_b128 v[186:189], v145 offset:55296
	ds_read_b128 v[190:193], v145 offset:56320
	global_load_lds_dwordx4 v[140:141], off
	v_lshl_add_u64 v[140:141], v[232:233], 0, s[64:65]
	s_mov_b32 m0, s66
	s_nop 0
	global_load_lds_dwordx4 v[140:141], off
	s_barrier
	s_waitcnt lgkmcnt(0)
	s_setprio 1
	s_waitcnt lgkmcnt(0)
	v_mfma_f32_16x16x32_bf16 v[62:65], v[146:149], v[162:165], v[62:65]
	v_mfma_f32_16x16x32_bf16 v[58:61], v[154:157], v[162:165], v[58:61]
	v_mfma_f32_16x16x32_bf16 v[54:57], v[146:149], v[170:173], v[54:57]
	v_mfma_f32_16x16x32_bf16 v[46:49], v[154:157], v[170:173], v[46:49]
	v_mfma_f32_16x16x32_bf16 v[38:41], v[146:149], v[178:181], v[38:41]
	v_mfma_f32_16x16x32_bf16 v[30:33], v[154:157], v[178:181], v[30:33]
	v_mfma_f32_16x16x32_bf16 v[22:25], v[146:149], v[186:189], v[22:25]
	v_mfma_f32_16x16x32_bf16 v[14:17], v[154:157], v[186:189], v[14:17]
	v_mfma_f32_16x16x32_bf16 v[62:65], v[150:153], v[166:169], v[62:65]
	v_mfma_f32_16x16x32_bf16 v[58:61], v[158:161], v[166:169], v[58:61]
	v_mfma_f32_16x16x32_bf16 v[54:57], v[150:153], v[174:177], v[54:57]
	v_mfma_f32_16x16x32_bf16 v[46:49], v[158:161], v[174:177], v[46:49]
	v_mfma_f32_16x16x32_bf16 v[38:41], v[150:153], v[182:185], v[38:41]
	v_mfma_f32_16x16x32_bf16 v[30:33], v[158:161], v[182:185], v[30:33]
	v_mfma_f32_16x16x32_bf16 v[22:25], v[150:153], v[190:193], v[22:25]
	v_mfma_f32_16x16x32_bf16 v[14:17], v[158:161], v[190:193], v[14:17]
	s_setprio 0
	s_barrier
	s_add_u32 s34, s34, 0x40080
	s_addc_u32 s35, s35, 0
	s_add_i32 s2, s3, s49
	v_lshl_add_u64 v[140:141], s[34:35], 0, v[0:1]
	s_mov_b32 m0, s2
	s_nop 0
	global_load_lds_dwordx4 v[140:141], off
	v_lshl_add_u64 v[140:141], s[34:35], 0, v[134:135]
	s_add_i32 m0, s2, 0x2000
	s_nop 0
	global_load_lds_dwordx4 v[140:141], off
	s_waitcnt vmcnt(6)
	s_barrier
	s_setprio 1
	v_mfma_f32_16x16x32_bf16 v[50:53], v[216:219], v[162:165], v[50:53]
	v_mfma_f32_16x16x32_bf16 v[42:45], v[224:227], v[162:165], v[42:45]
	v_mfma_f32_16x16x32_bf16 v[34:37], v[216:219], v[170:173], v[34:37]
	v_mfma_f32_16x16x32_bf16 v[26:29], v[224:227], v[170:173], v[26:29]
	v_mfma_f32_16x16x32_bf16 v[18:21], v[216:219], v[178:181], v[18:21]
	v_mfma_f32_16x16x32_bf16 v[10:13], v[224:227], v[178:181], v[10:13]
	v_mfma_f32_16x16x32_bf16 v[6:9], v[216:219], v[186:189], v[6:9]
	v_mfma_f32_16x16x32_bf16 v[2:5], v[224:227], v[186:189], v[2:5]
	v_mfma_f32_16x16x32_bf16 v[50:53], v[220:223], v[166:169], v[50:53]
	v_mfma_f32_16x16x32_bf16 v[42:45], v[228:231], v[166:169], v[42:45]
	v_mfma_f32_16x16x32_bf16 v[34:37], v[220:223], v[174:177], v[34:37]
	v_mfma_f32_16x16x32_bf16 v[26:29], v[228:231], v[174:177], v[26:29]
	v_mfma_f32_16x16x32_bf16 v[18:21], v[220:223], v[182:185], v[18:21]
	v_mfma_f32_16x16x32_bf16 v[10:13], v[228:231], v[182:185], v[10:13]
	v_mfma_f32_16x16x32_bf16 v[6:9], v[220:223], v[190:193], v[6:9]
	v_mfma_f32_16x16x32_bf16 v[2:5], v[228:231], v[190:193], v[2:5]
	s_setprio 0
	s_add_i32 s68, s68, 2
	s_add_u32 s16, s16, 0x100
	s_addc_u32 s17, s17, 0
	s_add_u32 s7, s7, 0x100
	s_addc_u32 s11, s11, 0
	s_cmp_gt_u32 s68, 13
	s_barrier
	s_cbranch_scc0 .LBB0_761
	s_cmpk_gt_u32 s38, 0xff
	s_cbranch_scc1 .Lgx_e_pre
	s_barrier
; __device__ __forceinline__ unsigned pk2(float lo, float hi) { unsigned r; asm("v_cvt_pk_bf16_f32 %0, %1, %2" : "=v"(r) : "v"(lo), "v"(hi)); return r; }
; #define PG8_WAIT_V(n) asm volatile("s_waitcnt vmcnt(" #n ")" ::: "memory")
; #define PG8_BAR __builtin_amdgcn_s_barrier()
; template <class Epi, class Sched>
; __device__ __forceinline__ void gemm_phase(LAS unsigned char* lds, const int K, const int lda, const int ldb, const Sched& S, const Epi& E) {
;     ...
;     PG8_WAIT_V(0);
;     if (wr == 0) PG8_BAR;
;     PG8_BAR;
;     __device__ __forceinline__ void operator()(const Acc& acc, const Unit& u, int wr, int wc, int fr, int fq) const {
;         const int row0 = u.pm * BM + wr * 64 + fr, col0 = u.pn * BM + wc * 32 + 8 * fq;
; #pragma unroll
;         for (int ai = 0; ai < 2; ++ai)
; #pragma unroll
;             for (int m = 0; m < 4; ++m) { bf16_t* rp = O + (size_t)(row0 + ai * HALF + m * 16) * ld + col0;
; #pragma unroll
;                 for (int bj = 0; bj < 2; ++bj) { const f32x4 v0 = acc[ai][bj][m][0], v1 = acc[ai][bj][m][1];
;                     u32x4 o; o.x = pk2(v0[0], v0[1]); o.y = pk2(v0[2], v0[3]); o.z = pk2(v1[0], v1[1]); o.w = pk2(v1[2], v1[3]);
;                     *(u32x4*)(rp + bj * HALF) = o; } }
.Lgx_e_pre:
	v_lshl_add_u32 v148, s8, 8, v142
	v_lshl_or_b32 v140, s67, 8, v144
	v_ashrrev_i32_e32 v141, 31, v140
	v_mad_i64_i32 v[146:147], s[16:17], s62, v148, 0
	v_cvt_pk_bf16_f32 v114, v114, v115
	v_cvt_pk_bf16_f32 v115, v116, v117
	v_cvt_pk_bf16_f32 v116, v106, v107
	v_or_b32_e32 v106, 16, v148
	v_lshl_add_u64 v[146:147], v[146:147], 1, s[0:1]
	v_lshlrev_b64 v[140:141], 1, v[140:141]
	v_mad_i64_i32 v[106:107], s[16:17], s62, v106, 0
	v_cvt_pk_bf16_f32 v98, v98, v99
	v_cvt_pk_bf16_f32 v99, v100, v101
	v_cvt_pk_bf16_f32 v100, v90, v91
	v_or_b32_e32 v90, 32, v148
	v_lshl_add_u64 v[146:147], v[146:147], 0, v[140:141]
	v_lshl_add_u64 v[106:107], v[106:107], 1, s[0:1]
	v_mad_i64_i32 v[90:91], s[16:17], s62, v90, 0
	v_cvt_pk_bf16_f32 v82, v82, v83
	v_cvt_pk_bf16_f32 v83, v84, v85
	v_cvt_pk_bf16_f32 v84, v74, v75
	v_or_b32_e32 v74, 48, v148
	v_cvt_pk_bf16_f32 v70, v70, v71
	v_cvt_pk_bf16_f32 v71, v72, v73
	v_cvt_pk_bf16_f32 v72, v66, v67
	v_add_u32_e32 v66, 0x80, v148
	v_cvt_pk_bf16_f32 v117, v108, v109
	global_store_dwordx4 v[146:147], v[114:117], off offset:256
	v_lshl_add_u64 v[90:91], v[90:91], 1, s[0:1]
	v_mad_i64_i32 v[74:75], s[16:17], s62, v74, 0
	v_lshl_add_u64 v[114:115], v[106:107], 0, v[140:141]
	v_mad_i64_i32 v[66:67], s[16:17], s62, v66, 0
	v_cvt_pk_bf16_f32 v50, v50, v51
	v_cvt_pk_bf16_f32 v51, v52, v53
	v_cvt_pk_bf16_f32 v52, v42, v43
	v_add_u32_e32 v42, 0x90, v148
	v_cvt_pk_bf16_f32 v126, v126, v127
	v_cvt_pk_bf16_f32 v127, v128, v129
	v_cvt_pk_bf16_f32 v128, v122, v123
	v_cvt_pk_bf16_f32 v129, v124, v125
	global_store_dwordx4 v[146:147], v[126:129], off
	v_cvt_pk_bf16_f32 v101, v92, v93
	global_store_dwordx4 v[114:115], v[98:101], off offset:256
	v_lshl_add_u64 v[74:75], v[74:75], 1, s[0:1]
	v_lshl_add_u64 v[66:67], v[66:67], 1, s[0:1]
	v_lshl_add_u64 v[98:99], v[90:91], 0, v[140:141]
	v_mad_i64_i32 v[42:43], s[16:17], s62, v42, 0
	v_cvt_pk_bf16_f32 v34, v34, v35
	v_cvt_pk_bf16_f32 v35, v36, v37
	v_cvt_pk_bf16_f32 v36, v26, v27
	v_add_u32_e32 v26, 0xa0, v148
	v_cvt_pk_bf16_f32 v106, v118, v119
	v_cvt_pk_bf16_f32 v107, v120, v121
	v_cvt_pk_bf16_f32 v108, v110, v111
	v_cvt_pk_bf16_f32 v109, v112, v113
	global_store_dwordx4 v[114:115], v[106:109], off
	v_cvt_pk_bf16_f32 v85, v76, v77
	global_store_dwordx4 v[98:99], v[82:85], off offset:256
	v_lshl_add_u64 v[66:67], v[66:67], 0, v[140:141]
	v_lshl_add_u64 v[42:43], v[42:43], 1, s[0:1]
	v_lshl_add_u64 v[82:83], v[74:75], 0, v[140:141]
	v_mad_i64_i32 v[26:27], s[16:17], s62, v26, 0
	v_cvt_pk_bf16_f32 v18, v18, v19
	v_cvt_pk_bf16_f32 v19, v20, v21
	v_cvt_pk_bf16_f32 v20, v10, v11
	v_add_u32_e32 v10, 0xb0, v148
	v_cvt_pk_bf16_f32 v90, v102, v103
	v_cvt_pk_bf16_f32 v91, v104, v105
	v_cvt_pk_bf16_f32 v92, v94, v95
	v_cvt_pk_bf16_f32 v93, v96, v97
	global_store_dwordx4 v[98:99], v[90:93], off
	v_cvt_pk_bf16_f32 v74, v86, v87
	v_cvt_pk_bf16_f32 v75, v88, v89
	v_cvt_pk_bf16_f32 v76, v78, v79
	v_cvt_pk_bf16_f32 v77, v80, v81
	global_store_dwordx4 v[82:83], v[74:77], off
	v_cvt_pk_bf16_f32 v73, v68, v69
	global_store_dwordx4 v[82:83], v[70:73], off offset:256
	v_cvt_pk_bf16_f32 v53, v44, v45
	global_store_dwordx4 v[66:67], v[50:53], off offset:256
	v_lshl_add_u64 v[26:27], v[26:27], 1, s[0:1]
	v_mad_i64_i32 v[10:11], s[16:17], s62, v10, 0
	v_lshl_add_u64 v[50:51], v[42:43], 0, v[140:141]
	v_cvt_pk_bf16_f32 v62, v62, v63
	v_cvt_pk_bf16_f32 v63, v64, v65
	v_cvt_pk_bf16_f32 v64, v58, v59
	v_cvt_pk_bf16_f32 v65, v60, v61
	global_store_dwordx4 v[66:67], v[62:65], off
	v_cvt_pk_bf16_f32 v37, v28, v29
	global_store_dwordx4 v[50:51], v[34:37], off offset:256
	v_lshl_add_u64 v[10:11], v[10:11], 1, s[0:1]
	v_readlane_b32 s70, v253, 15
	v_lshl_add_u64 v[34:35], v[26:27], 0, v[140:141]
	v_cvt_pk_bf16_f32 v42, v54, v55
	v_cvt_pk_bf16_f32 v43, v56, v57
	v_cvt_pk_bf16_f32 v44, v46, v47
	v_cvt_pk_bf16_f32 v45, v48, v49
	global_store_dwordx4 v[50:51], v[42:45], off
	v_cvt_pk_bf16_f32 v21, v12, v13
	global_store_dwordx4 v[34:35], v[18:21], off offset:256
	s_and_b64 vcc, exec, s[4:5]
	s_mov_b32 s67, s6
	v_lshl_add_u64 v[18:19], v[10:11], 0, v[140:141]
	s_mov_b32 s8, s10
	s_mov_b64 s[34:35], s[14:15]
	s_mov_b64 s[16:17], s[12:13]
	v_readlane_b32 s71, v253, 16
	s_mov_b32 s68, 0x48000
	v_cvt_pk_bf16_f32 v26, v38, v39
	v_cvt_pk_bf16_f32 v27, v40, v41
	v_cvt_pk_bf16_f32 v28, v30, v31
	v_cvt_pk_bf16_f32 v29, v32, v33
	global_store_dwordx4 v[34:35], v[26:29], off
	v_cvt_pk_bf16_f32 v10, v22, v23
	v_cvt_pk_bf16_f32 v11, v24, v25
	v_cvt_pk_bf16_f32 v12, v14, v15
	v_cvt_pk_bf16_f32 v13, v16, v17
	global_store_dwordx4 v[18:19], v[10:13], off
	v_cvt_pk_bf16_f32 v6, v6, v7
	v_cvt_pk_bf16_f32 v7, v8, v9
	v_cvt_pk_bf16_f32 v8, v2, v3
	v_cvt_pk_bf16_f32 v9, v4, v5
	global_store_dwordx4 v[18:19], v[6:9], off offset:256
	s_cbranch_vccnz .Lgx_e_exit
	s_cmpk_gt_u32 s38, 0xff
	s_cbranch_scc0 .LBB0_754
	s_barrier
	s_branch .LBB0_754
.Lgx_e_exit:
	s_waitcnt vmcnt(0)
.LBB0_765:
	v_readlane_b32 s52, v253, 11
	v_readlane_b32 s54, v253, 13
	v_readlane_b32 s66, v253, 17
	v_readlane_b32 s60, v253, 19
	v_readlane_b32 s53, v253, 12
	v_readlane_b32 s55, v253, 14
	v_readlane_b32 s67, v253, 18
	v_readlane_b32 s61, v253, 20
	s_movk_i32 s62, 0x14ff
	s_movk_i32 s48, 0x7000
	s_movk_i32 s45, 0x3fff
	s_mov_b32 s47, s94
	s_barrier

; #define PG8_STAGE(bufoff, gbase, voff) do { _Pragma("unroll") for (int _i = 0; _i < 2; ++_i) \
;         __builtin_amdgcn_global_load_lds((const unsigned*)((const char*)(gbase) + (voff)[_i]), (LAS unsigned*)(lds + (bufoff) + ldsw + _i * 8192), 16, 0, 0); } while (0)
; #define PG8_STAGE_A(bufoff, gbase, h, vv) do { if constexpr (GATHER) { _Pragma("unroll") for (int _i = 0; _i < 2; ++_i) \
;         __builtin_amdgcn_global_load_lds((const unsigned*)((const char*)(gbase) + (vv)[h][_i]), (LAS unsigned*)(lds + (bufoff) + ldsw + _i * 8192), 16, 0, 0); } \
;         else { PG8_STAGE(bufoff, (gbase) + (h) * hstepA, voffA); } } while (0)
; #define PG8_LDA(dst, b, h) do { _Pragma("unroll") for (int m = 0; m < 4; ++m) _Pragma("unroll") for (int k = 0; k < 2; ++k) dst[m][k] = *(const LAS bf16x8*)(lds + PG8_SA(b, h) + aoff + m * 2048 + k * 1024); } while (0)
; #define PG8_LDB(dst, b, h) do { _Pragma("unroll") for (int n = 0; n < 2; ++n) _Pragma("unroll") for (int k = 0; k < 2; ++k) dst[n][k] = *(const LAS bf16x8*)(lds + PG8_SB(b, h) + boff + n * 2048 + k * 1024); } while (0)
; #define PG8_WAIT_L(n) asm volatile("s_waitcnt lgkmcnt(" #n ")" ::: "memory")
; template <class Epi, class Sched>
; __device__ __forceinline__ void gemm_phase(LAS unsigned char* lds, const int K, const int lda, const int ldb, const Sched& S, const Epi& E) {
;     ...
;         for (int t = 0; t < nt; t += 2) {
;             const bool last = (t == nt - 2);
;             const char* a1 = cA + (size_t)(t + 1) * kstep;
;             const char* a2 = last ? nA : cA + (size_t)(t + 2) * kstep; const char* b2 = last ? nB : cB + (size_t)(t + 2) * kstep;
;             const char* a3 = a2 + kstep; const char* b3 = b2 + kstep;
;             PG8_LDB(B0, 0, 0); PG8_SCHED; PG8_LDA(At, 0, 0); PG8_STAGE_A(PG8_SA(1, 1), a1, 1, vcur);
;             if constexpr (GATHER) { if (last) {
; #pragma unroll
;                 for (int h = 0; h < 2; ++h)
; #pragma unroll
;                     for (int i = 0; i < 2; ++i) vcur[h][i] = vnxt[h][i]; } }
;             PG8_WAIT_L(8); PG8_BAR; PG8_WAIT_L(0); PG8_MMA(0, 0, At, B0); PG8_BAR; PG8_SCHED;
;             PG8_LDB(B1, 0, 1); PG8_STAGE(PG8_SB(0, 0), b2, voffB);
;             PG8_BAR; PG8_WAIT_L(0); PG8_MMA(0, 1, At, B1); PG8_BAR;
;             PG8_LDA(At, 0, 1); PG8_STAGE_A(PG8_SA(0, 0), a2, 0, vcur);
;             PG8_BAR; PG8_WAIT_L(0); PG8_MMA(1, 0, At, B0); PG8_BAR; PG8_SCHED;
.LBB0_824:
	s_add_u32 s2, s0, s14
	s_addc_u32 s3, s1, s15
	s_add_u32 s2, s2, 0x100
	s_addc_u32 s3, s3, 0
	s_add_u32 s16, s63, s14
	s_addc_u32 s17, s66, s15
	s_add_i32 s20, 0, 0x10000
	v_add_u32_e32 v146, s20, v140
	ds_read_b128 v[142:145], v146
	ds_read_b128 v[150:153], v146 offset:1024
	ds_read_b128 v[154:157], v146 offset:2048
	ds_read_b128 v[158:161], v146 offset:3072
	s_cmpk_eq_i32 s14, 0x1b00
	s_cselect_b32 s35, s13, s3
	s_cselect_b32 s34, s12, s2
	s_cselect_b32 s17, s9, s17
	s_cselect_b32 s16, s8, s16
	v_lshl_add_u64 v[146:147], v[136:137], 0, s[14:15]
	s_add_i32 m0, s46, 0xc000
	ds_read_b128 v[162:165], v141
	ds_read_b128 v[166:169], v141 offset:1024
	ds_read_b128 v[170:173], v141 offset:2048
	ds_read_b128 v[174:177], v141 offset:3072
	ds_read_b128 v[178:181], v141 offset:4096
	ds_read_b128 v[186:189], v141 offset:5120
	ds_read_b128 v[190:193], v141 offset:6144
	ds_read_b128 v[216:219], v141 offset:7168
	global_load_lds_dwordx4 v[146:147], off
	v_lshl_add_u64 v[146:147], v[138:139], 0, s[14:15]
	s_add_i32 m0, s46, 0xe000
	s_nop 0
	global_load_lds_dwordx4 v[146:147], off
	s_waitcnt lgkmcnt(8)
	s_barrier
	s_waitcnt lgkmcnt(0)
	s_setprio 1
	s_waitcnt lgkmcnt(0)
	v_mfma_f32_16x16x32_bf16 v[126:129], v[142:145], v[162:165], v[126:129]
	v_mfma_f32_16x16x32_bf16 v[102:105], v[154:157], v[162:165], v[102:105]
	v_mfma_f32_16x16x32_bf16 v[122:125], v[142:145], v[170:173], v[122:125]
	v_mfma_f32_16x16x32_bf16 v[98:101], v[154:157], v[170:173], v[98:101]
	v_mfma_f32_16x16x32_bf16 v[110:113], v[142:145], v[178:181], v[110:113]
	v_mfma_f32_16x16x32_bf16 v[78:81], v[154:157], v[178:181], v[78:81]
	v_mfma_f32_16x16x32_bf16 v[106:109], v[142:145], v[190:193], v[106:109]
	v_mfma_f32_16x16x32_bf16 v[74:77], v[154:157], v[190:193], v[74:77]
	v_mfma_f32_16x16x32_bf16 v[126:129], v[150:153], v[166:169], v[126:129]
	v_mfma_f32_16x16x32_bf16 v[102:105], v[158:161], v[166:169], v[102:105]
	v_mfma_f32_16x16x32_bf16 v[122:125], v[150:153], v[174:177], v[122:125]
	v_mfma_f32_16x16x32_bf16 v[98:101], v[158:161], v[174:177], v[98:101]
	v_mfma_f32_16x16x32_bf16 v[110:113], v[150:153], v[186:189], v[110:113]
	v_mfma_f32_16x16x32_bf16 v[78:81], v[158:161], v[186:189], v[78:81]
	v_mfma_f32_16x16x32_bf16 v[106:109], v[150:153], v[216:219], v[106:109]
	v_mfma_f32_16x16x32_bf16 v[74:77], v[158:161], v[216:219], v[74:77]
	s_setprio 0
	s_barrier
	s_add_i32 s2, 0, 0x14000
	v_add_u32_e32 v146, s2, v140
	s_add_i32 s3, s20, s45
	ds_read_b128 v[220:223], v146
	ds_read_b128 v[224:227], v146 offset:1024
	ds_read_b128 v[228:231], v146 offset:2048
	ds_read_b128 v[232:235], v146 offset:3072
	v_lshl_add_u64 v[146:147], s[16:17], 0, v[0:1]
	s_mov_b32 m0, s3
	v_lshl_add_u64 v[194:195], s[16:17], 0, v[130:131]
	global_load_lds_dwordx4 v[146:147], off
	s_add_i32 m0, s3, 0x2000
	s_nop 0
	global_load_lds_dwordx4 v[194:195], off
	s_barrier
	s_waitcnt lgkmcnt(0)
	s_setprio 1
	s_waitcnt lgkmcnt(0)
	v_mfma_f32_16x16x32_bf16 v[62:65], v[220:223], v[162:165], v[62:65]
	v_mfma_f32_16x16x32_bf16 v[118:121], v[228:231], v[162:165], v[118:121]
	v_mfma_f32_16x16x32_bf16 v[54:57], v[220:223], v[170:173], v[54:57]
	v_mfma_f32_16x16x32_bf16 v[30:33], v[228:231], v[170:173], v[30:33]
	v_mfma_f32_16x16x32_bf16 v[46:49], v[220:223], v[178:181], v[46:49]
	v_mfma_f32_16x16x32_bf16 v[114:117], v[228:231], v[178:181], v[114:117]
	v_mfma_f32_16x16x32_bf16 v[42:45], v[220:223], v[190:193], v[42:45]
	v_mfma_f32_16x16x32_bf16 v[22:25], v[228:231], v[190:193], v[22:25]
	v_mfma_f32_16x16x32_bf16 v[62:65], v[224:227], v[166:169], v[62:65]
	v_mfma_f32_16x16x32_bf16 v[118:121], v[232:235], v[166:169], v[118:121]
	v_mfma_f32_16x16x32_bf16 v[54:57], v[224:227], v[174:177], v[54:57]
	v_mfma_f32_16x16x32_bf16 v[30:33], v[232:235], v[174:177], v[30:33]
	v_mfma_f32_16x16x32_bf16 v[46:49], v[224:227], v[186:189], v[46:49]
	v_mfma_f32_16x16x32_bf16 v[114:117], v[232:235], v[186:189], v[114:117]
	v_mfma_f32_16x16x32_bf16 v[42:45], v[224:227], v[216:219], v[42:45]
	v_mfma_f32_16x16x32_bf16 v[22:25], v[232:235], v[216:219], v[22:25]
	s_setprio 0
	s_mov_b32 m0, s46
	v_lshl_add_u64 v[214:215], s[34:35], 0, v[0:1]
	s_barrier
	ds_read_b128 v[162:165], v141 offset:16384
	ds_read_b128 v[166:169], v141 offset:17408
	ds_read_b128 v[170:173], v141 offset:18432
	ds_read_b128 v[174:177], v141 offset:19456
	ds_read_b128 v[178:181], v141 offset:20480
	ds_read_b128 v[186:189], v141 offset:21504
	ds_read_b128 v[190:193], v141 offset:22528
	ds_read_b128 v[216:219], v141 offset:23552
	global_load_lds_dwordx4 v[214:215], off
	v_lshl_add_u64 v[236:237], s[34:35], 0, v[130:131]
	s_mov_b32 m0, s47
	s_nop 0
	global_load_lds_dwordx4 v[236:237], off
	s_barrier
	s_waitcnt lgkmcnt(0)
	s_setprio 1
	s_waitcnt lgkmcnt(0)
	v_mfma_f32_16x16x32_bf16 v[90:93], v[142:145], v[162:165], v[90:93]
	v_mfma_f32_16x16x32_bf16 v[70:73], v[154:157], v[162:165], v[70:73]
	v_mfma_f32_16x16x32_bf16 v[94:97], v[142:145], v[170:173], v[94:97]
	v_mfma_f32_16x16x32_bf16 v[66:69], v[154:157], v[170:173], v[66:69]
	v_mfma_f32_16x16x32_bf16 v[86:89], v[142:145], v[178:181], v[86:89]
	v_mfma_f32_16x16x32_bf16 v[58:61], v[154:157], v[178:181], v[58:61]
	v_mfma_f32_16x16x32_bf16 v[82:85], v[142:145], v[190:193], v[82:85]
	v_mfma_f32_16x16x32_bf16 v[50:53], v[154:157], v[190:193], v[50:53]
	v_mfma_f32_16x16x32_bf16 v[90:93], v[150:153], v[166:169], v[90:93]
	v_mfma_f32_16x16x32_bf16 v[70:73], v[158:161], v[166:169], v[70:73]
	v_mfma_f32_16x16x32_bf16 v[94:97], v[150:153], v[174:177], v[94:97]
	v_mfma_f32_16x16x32_bf16 v[66:69], v[158:161], v[174:177], v[66:69]
	v_mfma_f32_16x16x32_bf16 v[86:89], v[150:153], v[186:189], v[86:89]
	v_mfma_f32_16x16x32_bf16 v[58:61], v[158:161], v[186:189], v[58:61]
	v_mfma_f32_16x16x32_bf16 v[82:85], v[150:153], v[216:219], v[82:85]
	v_mfma_f32_16x16x32_bf16 v[50:53], v[158:161], v[216:219], v[50:53]
	s_setprio 0
	s_barrier
; #define PG8_STAGE(bufoff, gbase, voff) do { _Pragma("unroll") for (int _i = 0; _i < 2; ++_i) \
;         __builtin_amdgcn_global_load_lds((const unsigned*)((const char*)(gbase) + (voff)[_i]), (LAS unsigned*)(lds + (bufoff) + ldsw + _i * 8192), 16, 0, 0); } while (0)
; #define PG8_STAGE_A(bufoff, gbase, h, vv) do { if constexpr (GATHER) { _Pragma("unroll") for (int _i = 0; _i < 2; ++_i) \
;         __builtin_amdgcn_global_load_lds((const unsigned*)((const char*)(gbase) + (vv)[h][_i]), (LAS unsigned*)(lds + (bufoff) + ldsw + _i * 8192), 16, 0, 0); } \
;         else { PG8_STAGE(bufoff, (gbase) + (h) * hstepA, voffA); } } while (0)
; #define PG8_LDA(dst, b, h) do { _Pragma("unroll") for (int m = 0; m < 4; ++m) _Pragma("unroll") for (int k = 0; k < 2; ++k) dst[m][k] = *(const LAS bf16x8*)(lds + PG8_SA(b, h) + aoff + m * 2048 + k * 1024); } while (0)
; #define PG8_LDB(dst, b, h) do { _Pragma("unroll") for (int n = 0; n < 2; ++n) _Pragma("unroll") for (int k = 0; k < 2; ++k) dst[n][k] = *(const LAS bf16x8*)(lds + PG8_SB(b, h) + boff + n * 2048 + k * 1024); } while (0)
; #define PG8_MMA(ai, bj, At, Bt) do { __builtin_amdgcn_s_setprio(1); _Pragma("unroll") for (int m = 0; m < 4; ++m) _Pragma("unroll") for (int n = 0; n < 2; ++n) _Pragma("unroll") for (int k = 0; k < 2; ++k) \
;         acc[ai][bj][m][n] = __builtin_amdgcn_mfma_f32_16x16x32_bf16(Bt[n][k], At[m][k], acc[ai][bj][m][n], 0, 0, 0); __builtin_amdgcn_s_setprio(0); } while (0)
; #define PG8_BAR __builtin_amdgcn_s_barrier()
; template <class Epi, class Sched>
; __device__ __forceinline__ void gemm_phase(LAS unsigned char* lds, const int K, const int lda, const int ldb, const Sched& S, const Epi& E) {
;     ...
;             PG8_BAR; PG8_WAIT_L(0); PG8_MMA(1, 0, At, B0); PG8_BAR; PG8_SCHED;
;             PG8_STAGE(PG8_SB(0, 1), b2 + hstepB, voffB);
;             PG8_WAIT_V(6); PG8_BAR; PG8_MMA(1, 1, At, B1); PG8_BAR;
;             PG8_LDB(B0, 1, 0); PG8_SCHED; PG8_LDA(At, 1, 0); PG8_STAGE_A(PG8_SA(0, 1), a2, 1, vcur);
;             PG8_WAIT_L(8); PG8_BAR; PG8_WAIT_L(0); PG8_MMA(0, 0, At, B0); PG8_BAR; PG8_SCHED;
;             PG8_LDB(B1, 1, 1); PG8_STAGE(PG8_SB(1, 0), b3, voffB);
;             PG8_BAR; PG8_WAIT_L(0); PG8_MMA(0, 1, At, B1); PG8_BAR;
;             PG8_LDA(At, 1, 1); PG8_STAGE_A(PG8_SA(1, 0), a3, 0, vcur);
;             PG8_BAR; PG8_WAIT_L(0); PG8_MMA(1, 0, At, B0); PG8_BAR; PG8_SCHED;
	s_add_u32 s68, s16, 0xe0000
	s_addc_u32 s69, s17, 0
	s_add_i32 s2, s2, s45
	v_lshl_add_u64 v[142:143], s[68:69], 0, v[0:1]
	s_mov_b32 m0, s2
	s_nop 0
	global_load_lds_dwordx4 v[142:143], off
	v_lshl_add_u64 v[142:143], s[68:69], 0, v[130:131]
	s_add_i32 m0, s2, 0x2000
	s_nop 0
	global_load_lds_dwordx4 v[142:143], off
	s_waitcnt vmcnt(6)
	s_barrier
	s_setprio 1
	v_mfma_f32_16x16x32_bf16 v[38:41], v[220:223], v[162:165], v[38:41]
	v_mfma_f32_16x16x32_bf16 v[10:13], v[228:231], v[162:165], v[10:13]
	v_mfma_f32_16x16x32_bf16 v[34:37], v[220:223], v[170:173], v[34:37]
	v_mfma_f32_16x16x32_bf16 v[14:17], v[228:231], v[170:173], v[14:17]
	v_mfma_f32_16x16x32_bf16 v[26:29], v[220:223], v[178:181], v[26:29]
	v_mfma_f32_16x16x32_bf16 v[6:9], v[228:231], v[178:181], v[6:9]
	v_mfma_f32_16x16x32_bf16 v[18:21], v[220:223], v[190:193], v[18:21]
	v_mfma_f32_16x16x32_bf16 v[2:5], v[228:231], v[190:193], v[2:5]
	v_mfma_f32_16x16x32_bf16 v[38:41], v[224:227], v[166:169], v[38:41]
	v_mfma_f32_16x16x32_bf16 v[10:13], v[232:235], v[166:169], v[10:13]
	v_mfma_f32_16x16x32_bf16 v[34:37], v[224:227], v[174:177], v[34:37]
	v_mfma_f32_16x16x32_bf16 v[14:17], v[232:235], v[174:177], v[14:17]
	v_mfma_f32_16x16x32_bf16 v[26:29], v[224:227], v[186:189], v[26:29]
	v_mfma_f32_16x16x32_bf16 v[6:9], v[232:235], v[186:189], v[6:9]
	v_mfma_f32_16x16x32_bf16 v[18:21], v[224:227], v[216:219], v[18:21]
	v_mfma_f32_16x16x32_bf16 v[2:5], v[232:235], v[216:219], v[2:5]
	s_setprio 0
	s_add_i32 s2, 0, 0x18000
	v_add_u32_e32 v148, s2, v140
	s_barrier
	ds_read_b128 v[142:145], v148
	ds_read_b128 v[150:153], v148 offset:1024
	ds_read_b128 v[154:157], v148 offset:2048
	ds_read_b128 v[158:161], v148 offset:3072
	s_add_u32 s34, s34, 0xe0000
	s_addc_u32 s35, s35, 0
	s_mov_b32 m0, s48
	v_lshl_add_u64 v[220:221], s[34:35], 0, v[0:1]
	ds_read_b128 v[162:165], v141 offset:32768
	ds_read_b128 v[166:169], v141 offset:33792
	ds_read_b128 v[170:173], v141 offset:34816
	ds_read_b128 v[174:177], v141 offset:35840
	ds_read_b128 v[178:181], v141 offset:36864
	ds_read_b128 v[186:189], v141 offset:37888
	ds_read_b128 v[190:193], v141 offset:38912
	ds_read_b128 v[216:219], v141 offset:39936
	global_load_lds_dwordx4 v[220:221], off
	v_lshl_add_u64 v[220:221], s[34:35], 0, v[130:131]
	s_mov_b32 m0, s49
	s_nop 0
	global_load_lds_dwordx4 v[220:221], off
	s_waitcnt lgkmcnt(8)
	s_barrier
	s_waitcnt lgkmcnt(0)
	s_setprio 1
	s_waitcnt lgkmcnt(0)
	v_mfma_f32_16x16x32_bf16 v[126:129], v[142:145], v[162:165], v[126:129]
	v_mfma_f32_16x16x32_bf16 v[102:105], v[154:157], v[162:165], v[102:105]
	v_mfma_f32_16x16x32_bf16 v[122:125], v[142:145], v[170:173], v[122:125]
	v_mfma_f32_16x16x32_bf16 v[98:101], v[154:157], v[170:173], v[98:101]
	v_mfma_f32_16x16x32_bf16 v[110:113], v[142:145], v[178:181], v[110:113]
	v_mfma_f32_16x16x32_bf16 v[78:81], v[154:157], v[178:181], v[78:81]
	v_mfma_f32_16x16x32_bf16 v[106:109], v[142:145], v[190:193], v[106:109]
	v_mfma_f32_16x16x32_bf16 v[74:77], v[154:157], v[190:193], v[74:77]
	v_mfma_f32_16x16x32_bf16 v[126:129], v[150:153], v[166:169], v[126:129]
	v_mfma_f32_16x16x32_bf16 v[102:105], v[158:161], v[166:169], v[102:105]
	v_mfma_f32_16x16x32_bf16 v[122:125], v[150:153], v[174:177], v[122:125]
	v_mfma_f32_16x16x32_bf16 v[98:101], v[158:161], v[174:177], v[98:101]
	v_mfma_f32_16x16x32_bf16 v[110:113], v[150:153], v[186:189], v[110:113]
	v_mfma_f32_16x16x32_bf16 v[78:81], v[158:161], v[186:189], v[78:81]
	v_mfma_f32_16x16x32_bf16 v[106:109], v[150:153], v[216:219], v[106:109]
	v_mfma_f32_16x16x32_bf16 v[74:77], v[158:161], v[216:219], v[74:77]
	s_setprio 0
	s_barrier
	s_add_i32 s3, 0, 0x1c000
	s_add_i32 s2, s2, s45
	v_add_u32_e32 v148, s3, v140
	v_lshl_add_u64 v[146:147], v[146:147], 0, s[64:65]
	s_mov_b32 m0, s2
	ds_read_b128 v[220:223], v148
	ds_read_b128 v[224:227], v148 offset:1024
	ds_read_b128 v[228:231], v148 offset:2048
	ds_read_b128 v[232:235], v148 offset:3072
	global_load_lds_dwordx4 v[146:147], off
	v_lshl_add_u64 v[146:147], v[194:195], 0, s[64:65]
	s_add_i32 m0, s2, 0x2000
	s_nop 0
	global_load_lds_dwordx4 v[146:147], off
	s_barrier
	s_waitcnt lgkmcnt(0)
	s_setprio 1
	s_waitcnt lgkmcnt(0)
	v_mfma_f32_16x16x32_bf16 v[62:65], v[220:223], v[162:165], v[62:65]
	v_mfma_f32_16x16x32_bf16 v[118:121], v[228:231], v[162:165], v[118:121]
	v_mfma_f32_16x16x32_bf16 v[54:57], v[220:223], v[170:173], v[54:57]
	v_mfma_f32_16x16x32_bf16 v[30:33], v[228:231], v[170:173], v[30:33]
	v_mfma_f32_16x16x32_bf16 v[46:49], v[220:223], v[178:181], v[46:49]
	v_mfma_f32_16x16x32_bf16 v[114:117], v[228:231], v[178:181], v[114:117]
	v_mfma_f32_16x16x32_bf16 v[42:45], v[220:223], v[190:193], v[42:45]
	v_mfma_f32_16x16x32_bf16 v[22:25], v[228:231], v[190:193], v[22:25]
	v_mfma_f32_16x16x32_bf16 v[62:65], v[224:227], v[166:169], v[62:65]
	v_mfma_f32_16x16x32_bf16 v[118:121], v[232:235], v[166:169], v[118:121]
	v_mfma_f32_16x16x32_bf16 v[54:57], v[224:227], v[174:177], v[54:57]
	v_mfma_f32_16x16x32_bf16 v[30:33], v[232:235], v[174:177], v[30:33]
	v_mfma_f32_16x16x32_bf16 v[46:49], v[224:227], v[186:189], v[46:49]
	v_mfma_f32_16x16x32_bf16 v[114:117], v[232:235], v[186:189], v[114:117]
	v_mfma_f32_16x16x32_bf16 v[42:45], v[224:227], v[216:219], v[42:45]
	v_mfma_f32_16x16x32_bf16 v[22:25], v[232:235], v[216:219], v[22:25]
	s_setprio 0
	s_mov_b32 m0, s52
	v_lshl_add_u64 v[146:147], v[214:215], 0, s[64:65]
	s_barrier
; #define PG8_STAGE(bufoff, gbase, voff) do { _Pragma("unroll") for (int _i = 0; _i < 2; ++_i) \
;         __builtin_amdgcn_global_load_lds((const unsigned*)((const char*)(gbase) + (voff)[_i]), (LAS unsigned*)(lds + (bufoff) + ldsw + _i * 8192), 16, 0, 0); } while (0)
; #define PG8_MMA(ai, bj, At, Bt) do { __builtin_amdgcn_s_setprio(1); _Pragma("unroll") for (int m = 0; m < 4; ++m) _Pragma("unroll") for (int n = 0; n < 2; ++n) _Pragma("unroll") for (int k = 0; k < 2; ++k) \
;         acc[ai][bj][m][n] = __builtin_amdgcn_mfma_f32_16x16x32_bf16(Bt[n][k], At[m][k], acc[ai][bj][m][n], 0, 0, 0); __builtin_amdgcn_s_setprio(0); } while (0)
; #define PG8_WAIT_V(n) asm volatile("s_waitcnt vmcnt(" #n ")" ::: "memory")
; #define PG8_WAIT_L(n) asm volatile("s_waitcnt lgkmcnt(" #n ")" ::: "memory")
; #define PG8_BAR __builtin_amdgcn_s_barrier()
; #define PG8_SCHED __builtin_amdgcn_sched_barrier(0)
; template <class Epi, class Sched>
; __device__ __forceinline__ void gemm_phase(LAS unsigned char* lds, const int K, const int lda, const int ldb, const Sched& S, const Epi& E) {
;     ...
;             PG8_BAR; PG8_WAIT_L(0); PG8_MMA(1, 0, At, B0); PG8_BAR; PG8_SCHED;
;             PG8_STAGE(PG8_SB(1, 1), b3 + hstepB, voffB);
;             PG8_WAIT_V(6); PG8_BAR; PG8_MMA(1, 1, At, B1); PG8_BAR;
;         }
;     ...
;         if (!has_next) break;
; #pragma unroll
;         for (int a = 0; a < 2; ++a)
; #pragma unroll
;             for (int b = 0; b < 2; ++b)
; #pragma unroll
;                 for (int m = 0; m < 4; ++m)
; #pragma unroll
;                     for (int n = 0; n < 2; ++n) acc[a][b][m][n] = (f32x4){0.f, 0.f, 0.f, 0.f};
;         cur = nxt; cA = nA; cB = nB; ++ui;
	ds_read_b128 v[162:165], v141 offset:49152
	ds_read_b128 v[166:169], v141 offset:50176
	ds_read_b128 v[170:173], v141 offset:51200
	ds_read_b128 v[174:177], v141 offset:52224
	ds_read_b128 v[178:181], v141 offset:53248
	ds_read_b128 v[186:189], v141 offset:54272
	ds_read_b128 v[190:193], v141 offset:55296
	ds_read_b128 v[216:219], v141 offset:56320
	global_load_lds_dwordx4 v[146:147], off
	v_lshl_add_u64 v[146:147], v[236:237], 0, s[64:65]
	s_mov_b32 m0, s53
	s_nop 0
	global_load_lds_dwordx4 v[146:147], off
	s_barrier
	s_waitcnt lgkmcnt(0)
	s_setprio 1
	s_waitcnt lgkmcnt(0)
	v_mfma_f32_16x16x32_bf16 v[90:93], v[142:145], v[162:165], v[90:93]
	v_mfma_f32_16x16x32_bf16 v[70:73], v[154:157], v[162:165], v[70:73]
	v_mfma_f32_16x16x32_bf16 v[94:97], v[142:145], v[170:173], v[94:97]
	v_mfma_f32_16x16x32_bf16 v[66:69], v[154:157], v[170:173], v[66:69]
	v_mfma_f32_16x16x32_bf16 v[86:89], v[142:145], v[178:181], v[86:89]
	v_mfma_f32_16x16x32_bf16 v[58:61], v[154:157], v[178:181], v[58:61]
	v_mfma_f32_16x16x32_bf16 v[82:85], v[142:145], v[190:193], v[82:85]
	v_mfma_f32_16x16x32_bf16 v[50:53], v[154:157], v[190:193], v[50:53]
	v_mfma_f32_16x16x32_bf16 v[90:93], v[150:153], v[166:169], v[90:93]
	v_mfma_f32_16x16x32_bf16 v[70:73], v[158:161], v[166:169], v[70:73]
	v_mfma_f32_16x16x32_bf16 v[94:97], v[150:153], v[174:177], v[94:97]
	v_mfma_f32_16x16x32_bf16 v[66:69], v[158:161], v[174:177], v[66:69]
	v_mfma_f32_16x16x32_bf16 v[86:89], v[150:153], v[186:189], v[86:89]
	v_mfma_f32_16x16x32_bf16 v[58:61], v[158:161], v[186:189], v[58:61]
	v_mfma_f32_16x16x32_bf16 v[82:85], v[150:153], v[216:219], v[82:85]
	v_mfma_f32_16x16x32_bf16 v[50:53], v[158:161], v[216:219], v[50:53]
	s_setprio 0
	s_barrier
	s_add_u32 s16, s16, 0xe0080
	s_addc_u32 s17, s17, 0
	s_add_i32 s2, s3, s45
	v_lshl_add_u64 v[142:143], s[16:17], 0, v[0:1]
	s_mov_b32 m0, s2
	s_nop 0
	global_load_lds_dwordx4 v[142:143], off
	v_lshl_add_u64 v[142:143], s[16:17], 0, v[130:131]
	s_add_i32 m0, s2, 0x2000
	s_nop 0
	global_load_lds_dwordx4 v[142:143], off
	s_waitcnt vmcnt(6)
	s_barrier
	s_setprio 1
	v_mfma_f32_16x16x32_bf16 v[38:41], v[220:223], v[162:165], v[38:41]
	v_mfma_f32_16x16x32_bf16 v[10:13], v[228:231], v[162:165], v[10:13]
	v_mfma_f32_16x16x32_bf16 v[34:37], v[220:223], v[170:173], v[34:37]
	v_mfma_f32_16x16x32_bf16 v[14:17], v[228:231], v[170:173], v[14:17]
	v_mfma_f32_16x16x32_bf16 v[26:29], v[220:223], v[178:181], v[26:29]
	v_mfma_f32_16x16x32_bf16 v[6:9], v[228:231], v[178:181], v[6:9]
	v_mfma_f32_16x16x32_bf16 v[18:21], v[220:223], v[190:193], v[18:21]
	v_mfma_f32_16x16x32_bf16 v[2:5], v[228:231], v[190:193], v[2:5]
	v_mfma_f32_16x16x32_bf16 v[38:41], v[224:227], v[166:169], v[38:41]
	v_mfma_f32_16x16x32_bf16 v[10:13], v[232:235], v[166:169], v[10:13]
	v_mfma_f32_16x16x32_bf16 v[34:37], v[224:227], v[174:177], v[34:37]
	v_mfma_f32_16x16x32_bf16 v[14:17], v[232:235], v[174:177], v[14:17]
	v_mfma_f32_16x16x32_bf16 v[26:29], v[224:227], v[186:189], v[26:29]
	v_mfma_f32_16x16x32_bf16 v[6:9], v[232:235], v[186:189], v[6:9]
	v_mfma_f32_16x16x32_bf16 v[18:21], v[224:227], v[216:219], v[18:21]
	v_mfma_f32_16x16x32_bf16 v[2:5], v[232:235], v[216:219], v[2:5]
	s_setprio 0
	s_add_i32 s67, s67, 2
	s_add_u32 s14, s14, 0x100
	s_addc_u32 s15, s15, 0
	s_cmp_gt_u32 s67, 53
	s_barrier
	s_cbranch_scc0 .LBB0_824
	s_add_u32 s14, s63, 0xffffff00
	s_addc_u32 s15, s66, -1
	s_andn2_b64 vcc, exec, s[10:11]
	s_cbranch_vccnz .LBB0_827
	v_mov_b32_e32 v2, 0
	s_mov_b32 s5, s55
	s_mov_b32 s4, s60
	s_mov_b64 s[0:1], s[12:13]
	s_mov_b32 s54, s62
	v_mov_b32_e32 v3, v2
	v_mov_b64_e32 v[4:5], 0
	v_mov_b64_e32 v[18:19], 0
	v_mov_b64_e32 v[20:21], 0
	v_mov_b64_e32 v[6:7], 0
	v_mov_b64_e32 v[8:9], 0
	v_mov_b64_e32 v[26:27], 0
	v_mov_b64_e32 v[28:29], 0
	v_mov_b64_e32 v[14:15], 0
	v_mov_b64_e32 v[16:17], 0
	v_mov_b64_e32 v[34:35], 0
	v_mov_b64_e32 v[36:37], 0
	v_mov_b64_e32 v[10:11], 0
	v_mov_b64_e32 v[12:13], 0
	v_mov_b64_e32 v[38:39], 0
	v_mov_b64_e32 v[40:41], 0
	v_mov_b64_e32 v[50:51], 0
	v_mov_b64_e32 v[52:53], 0
	v_mov_b64_e32 v[82:83], 0
	v_mov_b64_e32 v[84:85], 0
	v_mov_b64_e32 v[58:59], 0
	v_mov_b64_e32 v[60:61], 0
	v_mov_b64_e32 v[86:87], 0
	v_mov_b64_e32 v[88:89], 0
	v_mov_b64_e32 v[66:67], 0
	v_mov_b64_e32 v[68:69], 0
	v_mov_b64_e32 v[94:95], 0
	v_mov_b64_e32 v[96:97], 0
	v_mov_b64_e32 v[70:71], 0
	v_mov_b64_e32 v[72:73], 0
	v_mov_b64_e32 v[90:91], 0
	v_mov_b64_e32 v[92:93], 0
	v_mov_b64_e32 v[22:23], 0
	v_mov_b64_e32 v[24:25], 0
	v_mov_b64_e32 v[42:43], 0
	v_mov_b64_e32 v[44:45], 0
	v_mov_b64_e32 v[114:115], 0
	v_mov_b64_e32 v[116:117], 0
	v_mov_b64_e32 v[46:47], 0
	v_mov_b64_e32 v[48:49], 0
	v_mov_b64_e32 v[30:31], 0
	v_mov_b64_e32 v[32:33], 0
	v_mov_b64_e32 v[54:55], 0
	v_mov_b64_e32 v[56:57], 0
	v_mov_b64_e32 v[118:119], 0
	v_mov_b64_e32 v[120:121], 0
	v_mov_b64_e32 v[62:63], 0
	v_mov_b64_e32 v[64:65], 0
	v_mov_b64_e32 v[74:75], 0
	v_mov_b64_e32 v[76:77], 0
	v_mov_b64_e32 v[106:107], 0
	v_mov_b64_e32 v[108:109], 0
	v_mov_b64_e32 v[78:79], 0
	v_mov_b64_e32 v[80:81], 0
	v_mov_b64_e32 v[110:111], 0
	v_mov_b64_e32 v[112:113], 0
	v_mov_b64_e32 v[98:99], 0
	v_mov_b64_e32 v[100:101], 0
	v_mov_b64_e32 v[122:123], 0
	v_mov_b64_e32 v[124:125], 0
	v_mov_b64_e32 v[102:103], 0
	v_mov_b64_e32 v[104:105], 0
	v_mov_b64_e32 v[126:127], 0
	v_mov_b64_e32 v[128:129], 0
	s_branch .LBB0_828

; template <class Epi, class Sched>
; __device__ __forceinline__ void gemm_phase(LAS unsigned char* lds, const int K, const int lda, const int ldb, const Sched& S, const Epi& E) {
;     ...
; #pragma unroll
;         for (int a = 0; a < 2; ++a)
; #pragma unroll
;             for (int b = 0; b < 2; ++b)
; #pragma unroll
;                 for (int m = 0; m < 4; ++m)
; #pragma unroll
;                     for (int n = 0; n < 2; ++n) acc[a][b][m][n] = (f32x4){0.f, 0.f, 0.f, 0.f};
;         cur = nxt; cA = nA; cB = nB; ++ui;
.LBB0_880:
	s_add_u32 s14, s14, 0x40080
	s_addc_u32 s15, s15, 0
	s_add_u32 s5, s16, 0x100
	v_mov_b32_e32 v2, 0
	s_addc_u32 s7, s17, 0
	s_mov_b32 s53, -2
	v_mov_b32_e32 v3, v2
	v_mov_b64_e32 v[4:5], 0
	v_mov_b64_e32 v[10:11], 0
	v_mov_b64_e32 v[12:13], 0
	v_mov_b64_e32 v[18:19], 0
	v_mov_b64_e32 v[20:21], 0
	v_mov_b64_e32 v[26:27], 0
	v_mov_b64_e32 v[28:29], 0
	v_mov_b64_e32 v[34:35], 0
	v_mov_b64_e32 v[36:37], 0
	v_mov_b64_e32 v[42:43], 0
	v_mov_b64_e32 v[44:45], 0
	v_mov_b64_e32 v[50:51], 0
	v_mov_b64_e32 v[52:53], 0
	v_mov_b64_e32 v[58:59], 0
	v_mov_b64_e32 v[60:61], 0
	v_mov_b64_e32 v[6:7], 0
	v_mov_b64_e32 v[8:9], 0
	v_mov_b64_e32 v[14:15], 0
	v_mov_b64_e32 v[16:17], 0
	v_mov_b64_e32 v[22:23], 0
	v_mov_b64_e32 v[24:25], 0
	v_mov_b64_e32 v[30:31], 0
	v_mov_b64_e32 v[32:33], 0
	v_mov_b64_e32 v[38:39], 0
	v_mov_b64_e32 v[40:41], 0
	v_mov_b64_e32 v[46:47], 0
	v_mov_b64_e32 v[48:49], 0
	v_mov_b64_e32 v[54:55], 0
	v_mov_b64_e32 v[56:57], 0
	v_mov_b64_e32 v[62:63], 0
	v_mov_b64_e32 v[64:65], 0
	v_mov_b64_e32 v[66:67], 0
	v_mov_b64_e32 v[68:69], 0
	v_mov_b64_e32 v[74:75], 0
	v_mov_b64_e32 v[76:77], 0
	v_mov_b64_e32 v[82:83], 0
	v_mov_b64_e32 v[84:85], 0
	v_mov_b64_e32 v[90:91], 0
	v_mov_b64_e32 v[92:93], 0
	v_mov_b64_e32 v[98:99], 0
	v_mov_b64_e32 v[100:101], 0
	v_mov_b64_e32 v[106:107], 0
	v_mov_b64_e32 v[108:109], 0
	v_mov_b64_e32 v[114:115], 0
	v_mov_b64_e32 v[116:117], 0
	v_mov_b64_e32 v[122:123], 0
	v_mov_b64_e32 v[124:125], 0
	v_mov_b64_e32 v[70:71], 0
	v_mov_b64_e32 v[72:73], 0
	v_mov_b64_e32 v[78:79], 0
	v_mov_b64_e32 v[80:81], 0
	v_mov_b64_e32 v[86:87], 0
	v_mov_b64_e32 v[88:89], 0
	v_mov_b64_e32 v[94:95], 0
	v_mov_b64_e32 v[96:97], 0
	v_mov_b64_e32 v[102:103], 0
	v_mov_b64_e32 v[104:105], 0
	v_mov_b64_e32 v[110:111], 0
	v_mov_b64_e32 v[112:113], 0
	v_mov_b64_e32 v[118:119], 0
	v_mov_b64_e32 v[120:121], 0
	v_mov_b64_e32 v[126:127], 0
	v_mov_b64_e32 v[128:129], 0

; #define PG8_STAGE(bufoff, gbase, voff) do { _Pragma("unroll") for (int _i = 0; _i < 2; ++_i) \
;         __builtin_amdgcn_global_load_lds((const unsigned*)((const char*)(gbase) + (voff)[_i]), (LAS unsigned*)(lds + (bufoff) + ldsw + _i * 8192), 16, 0, 0); } while (0)
; #define PG8_WAIT_V(n) asm volatile("s_waitcnt vmcnt(" #n ")" ::: "memory")
; #define PG8_BAR __builtin_amdgcn_s_barrier()
; template <class Epi, class Sched>
; __device__ __forceinline__ void gemm_phase(LAS unsigned char* lds, const int K, const int lda, const int ldb, const Sched& S, const Epi& E) {
;     ...
;         for (int t = 0; t < nt; t += 2) {
;             const bool last = (t == nt - 2);
;             const char* a1 = cA + (size_t)(t + 1) * kstep;
;             const char* a2 = last ? nA : cA + (size_t)(t + 2) * kstep; const char* b2 = last ? nB : cB + (size_t)(t + 2) * kstep;
;             const char* a3 = a2 + kstep; const char* b3 = b2 + kstep;
;             PG8_LDB(B0, 0, 0); PG8_SCHED; PG8_LDA(At, 0, 0); PG8_STAGE_A(PG8_SA(1, 1), a1, 1, vcur);
;             if constexpr (GATHER) { if (last) {
; #pragma unroll
;                 for (int h = 0; h < 2; ++h)
; #pragma unroll
;                     for (int i = 0; i < 2; ++i) vcur[h][i] = vnxt[h][i]; } }
;             PG8_WAIT_L(8); PG8_BAR; PG8_WAIT_L(0); PG8_MMA(0, 0, At, B0); PG8_BAR; PG8_SCHED;
;             PG8_LDB(B1, 0, 1); PG8_STAGE(PG8_SB(0, 0), b2, voffB);
;             PG8_BAR; PG8_WAIT_L(0); PG8_MMA(0, 1, At, B1); PG8_BAR;
;             PG8_LDA(At, 0, 1); PG8_STAGE_A(PG8_SA(0, 0), a2, 0, vcur);
;             PG8_BAR; PG8_WAIT_L(0); PG8_MMA(1, 0, At, B0); PG8_BAR; PG8_SCHED;
;             PG8_STAGE(PG8_SB(0, 1), b2 + hstepB, voffB);
;             PG8_WAIT_V(6); PG8_BAR; PG8_MMA(1, 1, At, B1); PG8_BAR;
;             PG8_LDB(B0, 1, 0); PG8_SCHED; PG8_LDA(At, 1, 0); PG8_STAGE_A(PG8_SA(0, 1), a2, 1, vcur);
;             PG8_WAIT_L(8); PG8_BAR; PG8_WAIT_L(0); PG8_MMA(0, 0, At, B0); PG8_BAR; PG8_SCHED;
;             PG8_LDB(B1, 1, 1); PG8_STAGE(PG8_SB(1, 0), b3, voffB);
;             PG8_BAR; PG8_WAIT_L(0); PG8_MMA(0, 1, At, B1); PG8_BAR;
;             PG8_LDA(At, 1, 1); PG8_STAGE_A(PG8_SA(1, 0), a3, 0, vcur);
;             PG8_BAR; PG8_WAIT_L(0); PG8_MMA(1, 0, At, B0); PG8_BAR; PG8_SCHED;
;             PG8_STAGE(PG8_SB(1, 1), b3 + hstepB, voffB);
;             PG8_WAIT_V(6); PG8_BAR; PG8_MMA(1, 1, At, B1); PG8_BAR;
.LBB0_937:
	s_add_u32 s2, s8, s16
	s_addc_u32 s3, s9, s17
	s_add_u32 s20, s2, 0x100
	s_addc_u32 s21, s3, 0
	s_and_b64 s[18:19], s[14:15], exec
	s_cselect_b32 s19, s5, s21
	s_cselect_b32 s18, s4, s20
	s_add_u32 s16, s10, s16
	s_addc_u32 s17, s11, s17
	s_add_u32 s16, s16, 0x100
	s_addc_u32 s17, s17, 0
	s_add_i32 s20, 0, 0x10000
	s_and_b64 s[14:15], s[14:15], exec
	s_cselect_b32 s37, s7, s17
	s_cselect_b32 s36, s6, s16
	s_add_u32 s38, s2, 0x10080
	s_addc_u32 s39, s3, 0
	s_add_i32 s21, s20, s41
	s_add_i32 m0, s42, 0xc000
	s_add_i32 s2, s42, 0xe000
	s_add_i32 s3, 0, 0x14000
	s_add_i32 s50, s21, 0x2000
	s_add_u32 s34, s36, 0x10000
	v_add_u32_e32 v72, s20, v74
	s_addc_u32 s35, s37, 0
	s_add_i32 s51, s3, s41
	ds_read_b128 v[68:71], v72
	ds_read_b128 v[82:85], v72 offset:1024
	ds_read_b128 v[86:89], v72 offset:2048
	ds_read_b128 v[90:93], v72 offset:3072
	s_add_i32 s56, s51, 0x2000
	s_add_i32 s57, 0, 0x18000
	s_add_u32 s16, s18, 0x10000
	s_addc_u32 s17, s19, 0
	s_add_i32 s55, s57, s41
	s_add_i32 s54, 0, 0x1c000
	s_add_i32 s53, s55, 0x2000
	s_add_u32 s14, s36, 0x10080
	s_addc_u32 s15, s37, 0
	s_add_i32 s20, s54, s41
	s_add_i32 s60, s20, 0x2000
	v_lshl_add_u64 v[72:73], s[38:39], 0, v[0:1]
	ds_read_b128 v[94:97], v80
	ds_read_b128 v[98:101], v80 offset:1024
	ds_read_b128 v[102:105], v80 offset:2048
	ds_read_b128 v[106:109], v80 offset:3072
	ds_read_b128 v[110:113], v80 offset:4096
	ds_read_b128 v[114:117], v80 offset:5120
	ds_read_b128 v[118:121], v80 offset:6144
	ds_read_b128 v[122:125], v80 offset:7168
	global_load_lds_dwordx4 v[72:73], off
	v_lshl_add_u64 v[72:73], s[38:39], 0, v[66:67]
	s_mov_b32 m0, s2
	s_nop 0
	global_load_lds_dwordx4 v[72:73], off
	s_waitcnt lgkmcnt(8)
	s_barrier
	s_waitcnt lgkmcnt(0)
	s_setprio 1
	s_waitcnt lgkmcnt(0)
	v_mfma_f32_16x16x32_bf16 v[62:65], v[68:71], v[94:97], v[62:65]
	v_mfma_f32_16x16x32_bf16 v[58:61], v[86:89], v[94:97], v[58:61]
	v_mfma_f32_16x16x32_bf16 v[46:49], v[68:71], v[102:105], v[46:49]
	v_mfma_f32_16x16x32_bf16 v[42:45], v[86:89], v[102:105], v[42:45]
	v_mfma_f32_16x16x32_bf16 v[30:33], v[68:71], v[110:113], v[30:33]
	v_mfma_f32_16x16x32_bf16 v[26:29], v[86:89], v[110:113], v[26:29]
	v_mfma_f32_16x16x32_bf16 v[14:17], v[68:71], v[118:121], v[14:17]
	v_mfma_f32_16x16x32_bf16 v[10:13], v[86:89], v[118:121], v[10:13]
	v_mfma_f32_16x16x32_bf16 v[62:65], v[82:85], v[98:101], v[62:65]
	v_mfma_f32_16x16x32_bf16 v[58:61], v[90:93], v[98:101], v[58:61]
	v_mfma_f32_16x16x32_bf16 v[46:49], v[82:85], v[106:109], v[46:49]
	v_mfma_f32_16x16x32_bf16 v[42:45], v[90:93], v[106:109], v[42:45]
	v_mfma_f32_16x16x32_bf16 v[30:33], v[82:85], v[114:117], v[30:33]
	v_mfma_f32_16x16x32_bf16 v[26:29], v[90:93], v[114:117], v[26:29]
	v_mfma_f32_16x16x32_bf16 v[14:17], v[82:85], v[122:125], v[14:17]
	v_mfma_f32_16x16x32_bf16 v[10:13], v[90:93], v[122:125], v[10:13]
	s_setprio 0
	s_barrier
	v_add_u32_e32 v72, s3, v74
	s_mov_b32 m0, s21
	ds_read_b128 v[68:71], v72
	ds_read_b128 v[82:85], v72 offset:1024
	ds_read_b128 v[86:89], v72 offset:2048
	ds_read_b128 v[90:93], v72 offset:3072
	v_lshl_add_u64 v[72:73], s[36:37], 0, v[0:1]
	global_load_lds_dwordx4 v[72:73], off
	v_lshl_add_u64 v[126:127], s[36:37], 0, v[66:67]
	s_mov_b32 m0, s50
	s_nop 0
	global_load_lds_dwordx4 v[126:127], off
	s_barrier
	s_waitcnt lgkmcnt(0)
	s_setprio 1
	s_waitcnt lgkmcnt(0)
	v_mfma_f32_16x16x32_bf16 v[54:57], v[68:71], v[94:97], v[54:57]
	v_mfma_f32_16x16x32_bf16 v[50:53], v[86:89], v[94:97], v[50:53]
	v_mfma_f32_16x16x32_bf16 v[38:41], v[68:71], v[102:105], v[38:41]
	v_mfma_f32_16x16x32_bf16 v[34:37], v[86:89], v[102:105], v[34:37]
	v_mfma_f32_16x16x32_bf16 v[22:25], v[68:71], v[110:113], v[22:25]
	v_mfma_f32_16x16x32_bf16 v[18:21], v[86:89], v[110:113], v[18:21]
	v_mfma_f32_16x16x32_bf16 v[6:9], v[68:71], v[118:121], v[6:9]
	v_mfma_f32_16x16x32_bf16 v[2:5], v[86:89], v[118:121], v[2:5]
	v_mfma_f32_16x16x32_bf16 v[54:57], v[82:85], v[98:101], v[54:57]
	v_mfma_f32_16x16x32_bf16 v[50:53], v[90:93], v[98:101], v[50:53]
	v_mfma_f32_16x16x32_bf16 v[38:41], v[82:85], v[106:109], v[38:41]
	v_mfma_f32_16x16x32_bf16 v[34:37], v[90:93], v[106:109], v[34:37]
	v_mfma_f32_16x16x32_bf16 v[22:25], v[82:85], v[114:117], v[22:25]
	v_mfma_f32_16x16x32_bf16 v[18:21], v[90:93], v[114:117], v[18:21]
	v_mfma_f32_16x16x32_bf16 v[6:9], v[82:85], v[122:125], v[6:9]
	v_mfma_f32_16x16x32_bf16 v[2:5], v[90:93], v[122:125], v[2:5]
	s_setprio 0
	s_mov_b32 m0, s42
	v_lshl_add_u64 v[128:129], s[18:19], 0, v[0:1]
	s_barrier
	global_load_lds_dwordx4 v[128:129], off
	v_lshl_add_u64 v[130:131], s[18:19], 0, v[66:67]
	s_mov_b32 m0, s43
	s_nop 0
	global_load_lds_dwordx4 v[130:131], off
	s_barrier
	s_waitcnt lgkmcnt(0)
	s_setprio 1
	s_setprio 0
	s_barrier
	s_mov_b32 m0, s51
	v_lshl_add_u64 v[68:69], s[34:35], 0, v[0:1]
	global_load_lds_dwordx4 v[68:69], off
	v_lshl_add_u64 v[68:69], s[34:35], 0, v[66:67]
	s_mov_b32 m0, s56
	s_nop 0
	global_load_lds_dwordx4 v[68:69], off
	s_waitcnt vmcnt(6)
	s_barrier
	s_setprio 1
	s_setprio 0
	v_add_u32_e32 v81, s57, v74
	s_barrier
	ds_read_b128 v[68:71], v81
	ds_read_b128 v[82:85], v81 offset:1024
	ds_read_b128 v[86:89], v81 offset:2048
	ds_read_b128 v[90:93], v81 offset:3072
	s_mov_b32 m0, s44
	v_lshl_add_u64 v[132:133], s[16:17], 0, v[0:1]
	ds_read_b128 v[94:97], v80 offset:32768
	ds_read_b128 v[98:101], v80 offset:33792
	ds_read_b128 v[102:105], v80 offset:34816
	ds_read_b128 v[106:109], v80 offset:35840
	ds_read_b128 v[110:113], v80 offset:36864
	ds_read_b128 v[114:117], v80 offset:37888
	ds_read_b128 v[118:121], v80 offset:38912
	ds_read_b128 v[122:125], v80 offset:39936
	global_load_lds_dwordx4 v[132:133], off
	v_lshl_add_u64 v[132:133], s[16:17], 0, v[66:67]
	s_mov_b32 m0, s45
	s_nop 0
	global_load_lds_dwordx4 v[132:133], off
	s_waitcnt lgkmcnt(8)
	s_barrier
; #define PG8_STAGE(bufoff, gbase, voff) do { _Pragma("unroll") for (int _i = 0; _i < 2; ++_i) \
;         __builtin_amdgcn_global_load_lds((const unsigned*)((const char*)(gbase) + (voff)[_i]), (LAS unsigned*)(lds + (bufoff) + ldsw + _i * 8192), 16, 0, 0); } while (0)
; #define PG8_STAGE_A(bufoff, gbase, h, vv) do { if constexpr (GATHER) { _Pragma("unroll") for (int _i = 0; _i < 2; ++_i) \
;         __builtin_amdgcn_global_load_lds((const unsigned*)((const char*)(gbase) + (vv)[h][_i]), (LAS unsigned*)(lds + (bufoff) + ldsw + _i * 8192), 16, 0, 0); } \
;         else { PG8_STAGE(bufoff, (gbase) + (h) * hstepA, voffA); } } while (0)
; #define PG8_LDA(dst, b, h) do { _Pragma("unroll") for (int m = 0; m < 4; ++m) _Pragma("unroll") for (int k = 0; k < 2; ++k) dst[m][k] = *(const LAS bf16x8*)(lds + PG8_SA(b, h) + aoff + m * 2048 + k * 1024); } while (0)
; #define PG8_BAR __builtin_amdgcn_s_barrier()
; template <class Epi, class Sched>
; __device__ __forceinline__ void gemm_phase(LAS unsigned char* lds, const int K, const int lda, const int ldb, const Sched& S, const Epi& E) {
;     ...
;             PG8_WAIT_L(8); PG8_BAR; PG8_WAIT_L(0); PG8_MMA(0, 0, At, B0); PG8_BAR; PG8_SCHED;
;             PG8_LDB(B1, 1, 1); PG8_STAGE(PG8_SB(1, 0), b3, voffB);
;             PG8_BAR; PG8_WAIT_L(0); PG8_MMA(0, 1, At, B1); PG8_BAR;
;             PG8_LDA(At, 1, 1); PG8_STAGE_A(PG8_SA(1, 0), a3, 0, vcur);
;             PG8_BAR; PG8_WAIT_L(0); PG8_MMA(1, 0, At, B0); PG8_BAR; PG8_SCHED;
;             PG8_STAGE(PG8_SB(1, 1), b3 + hstepB, voffB);
;             PG8_WAIT_V(6); PG8_BAR; PG8_MMA(1, 1, At, B1); PG8_BAR;
;         }
;     __device__ __forceinline__ void operator()(const Acc& acc, const Unit& u, int wr, int wc, int fr, int fq) const {
;         const int col0 = u.pn * BM + wc * 32 + 4 * fq;
; #pragma unroll
;         for (int m = 0; m < 4; ++m) { const int kb = wr * 64 + m * 16 + fr;
; #pragma unroll
;             for (int bj = 0; bj < 2; ++bj)
; #pragma unroll
;                 for (int n = 0; n < 2; ++n) { const int q = col0 + bj * HALF + n * 16, ka = q >> 10, nn = q & 1023;
;                     const f32x4 g = *(const f32x4*)(gate + nn) * (1.f / 2048.f);
;                     const size_t o = (size_t)(ka + 128 * kb) * D + nn; *(f32x4*)(X + o) = *(const f32x4*)(Xin + o) + g * acc[0][bj][m][n]; }
;             if (m & 1) __builtin_amdgcn_sched_barrier(0); }
	s_waitcnt lgkmcnt(0)
	s_setprio 1
	s_waitcnt lgkmcnt(0)
	v_mfma_f32_16x16x32_bf16 v[62:65], v[68:71], v[94:97], v[62:65]
	v_mfma_f32_16x16x32_bf16 v[58:61], v[86:89], v[94:97], v[58:61]
	v_mfma_f32_16x16x32_bf16 v[46:49], v[68:71], v[102:105], v[46:49]
	v_mfma_f32_16x16x32_bf16 v[42:45], v[86:89], v[102:105], v[42:45]
	v_mfma_f32_16x16x32_bf16 v[30:33], v[68:71], v[110:113], v[30:33]
	v_mfma_f32_16x16x32_bf16 v[26:29], v[86:89], v[110:113], v[26:29]
	v_mfma_f32_16x16x32_bf16 v[14:17], v[68:71], v[118:121], v[14:17]
	v_mfma_f32_16x16x32_bf16 v[10:13], v[86:89], v[118:121], v[10:13]
	v_mfma_f32_16x16x32_bf16 v[62:65], v[82:85], v[98:101], v[62:65]
	v_mfma_f32_16x16x32_bf16 v[58:61], v[90:93], v[98:101], v[58:61]
	v_mfma_f32_16x16x32_bf16 v[46:49], v[82:85], v[106:109], v[46:49]
	v_mfma_f32_16x16x32_bf16 v[42:45], v[90:93], v[106:109], v[42:45]
	v_mfma_f32_16x16x32_bf16 v[30:33], v[82:85], v[114:117], v[30:33]
	v_mfma_f32_16x16x32_bf16 v[26:29], v[90:93], v[114:117], v[26:29]
	v_mfma_f32_16x16x32_bf16 v[14:17], v[82:85], v[122:125], v[14:17]
	v_mfma_f32_16x16x32_bf16 v[10:13], v[90:93], v[122:125], v[10:13]
	s_setprio 0
	s_barrier
	s_mov_b32 m0, s55
	v_add_u32_e32 v81, s54, v74
	v_lshl_add_u64 v[72:73], v[72:73], 0, s[64:65]
	ds_read_b128 v[68:71], v81
	ds_read_b128 v[82:85], v81 offset:1024
	ds_read_b128 v[86:89], v81 offset:2048
	ds_read_b128 v[90:93], v81 offset:3072
	global_load_lds_dwordx4 v[72:73], off
	v_lshl_add_u64 v[72:73], v[126:127], 0, s[64:65]
	s_mov_b32 m0, s53
	s_nop 0
	global_load_lds_dwordx4 v[72:73], off
	s_barrier
	s_waitcnt lgkmcnt(0)
	s_setprio 1
	s_waitcnt lgkmcnt(0)
	v_mfma_f32_16x16x32_bf16 v[54:57], v[68:71], v[94:97], v[54:57]
	v_mfma_f32_16x16x32_bf16 v[50:53], v[86:89], v[94:97], v[50:53]
	v_mfma_f32_16x16x32_bf16 v[38:41], v[68:71], v[102:105], v[38:41]
	v_mfma_f32_16x16x32_bf16 v[34:37], v[86:89], v[102:105], v[34:37]
	v_mfma_f32_16x16x32_bf16 v[22:25], v[68:71], v[110:113], v[22:25]
	v_mfma_f32_16x16x32_bf16 v[18:21], v[86:89], v[110:113], v[18:21]
	v_mfma_f32_16x16x32_bf16 v[6:9], v[68:71], v[118:121], v[6:9]
	v_mfma_f32_16x16x32_bf16 v[2:5], v[86:89], v[118:121], v[2:5]
	v_mfma_f32_16x16x32_bf16 v[54:57], v[82:85], v[98:101], v[54:57]
	v_mfma_f32_16x16x32_bf16 v[50:53], v[90:93], v[98:101], v[50:53]
	v_mfma_f32_16x16x32_bf16 v[38:41], v[82:85], v[106:109], v[38:41]
	v_mfma_f32_16x16x32_bf16 v[34:37], v[90:93], v[106:109], v[34:37]
	v_mfma_f32_16x16x32_bf16 v[22:25], v[82:85], v[114:117], v[22:25]
	v_mfma_f32_16x16x32_bf16 v[18:21], v[90:93], v[114:117], v[18:21]
	v_mfma_f32_16x16x32_bf16 v[6:9], v[82:85], v[122:125], v[6:9]
	v_mfma_f32_16x16x32_bf16 v[2:5], v[90:93], v[122:125], v[2:5]
	s_setprio 0
	s_mov_b32 m0, s46
	v_lshl_add_u64 v[68:69], v[128:129], 0, s[64:65]
	s_barrier
	global_load_lds_dwordx4 v[68:69], off
	v_lshl_add_u64 v[68:69], v[130:131], 0, s[64:65]
	s_mov_b32 m0, s47
	s_nop 0
	global_load_lds_dwordx4 v[68:69], off
	s_barrier
	s_waitcnt lgkmcnt(0)
	s_setprio 1
	s_setprio 0
	s_barrier
	s_mov_b32 m0, s20
	v_lshl_add_u64 v[68:69], s[14:15], 0, v[0:1]
	global_load_lds_dwordx4 v[68:69], off
	v_lshl_add_u64 v[68:69], s[14:15], 0, v[66:67]
	s_mov_b32 m0, s60
	s_nop 0
	global_load_lds_dwordx4 v[68:69], off
	s_waitcnt vmcnt(6)
	s_barrier
	s_setprio 1
	s_setprio 0
	s_andn2_b64 vcc, exec, s[12:13]
	s_mov_b64 s[14:15], -1
	s_mov_b64 s[12:13], 0
	s_mov_b64 s[16:17], 0x100
	s_barrier
	s_cbranch_vccz .LBB0_937
	s_cmpk_gt_u32 s40, 0xff
	s_cbranch_scc1 .Lgx_c_pre
	s_barrier
.Lgx_c_pre:
	s_ashr_i32 s8, s52, 2
	s_lshl_b32 s2, s52, 8
	v_add_u32_e32 v68, s8, v75
	s_and_b32 s2, s2, 0x300
	v_ashrrev_i32_e32 v69, 31, v68
	v_or_b32_e32 v81, s2, v79
	v_lshlrev_b64 v[72:73], 10, v[68:69]
	v_or_b32_e32 v82, v72, v81
	v_mov_b32_e32 v83, v73
	v_readlane_b32 s10, v253, 28
	v_lshlrev_b32_e32 v92, 2, v81
	v_lshlrev_b64 v[86:87], 2, v[82:83]
	v_readlane_b32 s11, v253, 29
	global_load_dwordx4 v[68:71], v92, s[92:93]
	s_mov_b32 s2, 0x3a000000
	v_lshl_add_u64 v[88:89], s[10:11], 0, v[86:87]
	global_load_dwordx4 v[82:85], v[88:89], off
	v_mov_b32_e32 v91, v73
	s_waitcnt vmcnt(0)
	v_pk_mul_f32 v[68:69], v[68:69], s[2:3] op_sel_hi:[1,0]
	v_pk_mul_f32 v[70:71], v[70:71], s[2:3] op_sel_hi:[1,0]
	v_pk_fma_f32 v[62:63], v[62:63], v[68:69], v[82:83]
	v_pk_fma_f32 v[64:65], v[64:65], v[70:71], v[84:85]
	v_lshl_add_u64 v[82:83], s[22:23], 0, v[86:87]
	global_store_dwordx4 v[82:83], v[62:65], off
	v_or_b32_e32 v82, 16, v81
	v_lshlrev_b32_e32 v93, 2, v82
	global_load_dwordx4 v[62:65], v93, s[92:93]
	global_load_dwordx4 v[84:87], v[88:89], off offset:64
	v_or_b32_e32 v90, v72, v82
	v_or_b32_e32 v83, 0x80, v81
	v_lshlrev_b32_e32 v94, 2, v83
	s_waitcnt vmcnt(0)
	v_pk_mul_f32 v[62:63], v[62:63], s[2:3] op_sel_hi:[1,0]
	v_pk_mul_f32 v[64:65], v[64:65], s[2:3] op_sel_hi:[1,0]
	v_pk_fma_f32 v[58:59], v[58:59], v[62:63], v[84:85]
	v_pk_fma_f32 v[60:61], v[60:61], v[64:65], v[86:87]
	v_lshl_add_u64 v[84:85], v[90:91], 2, s[22:23]
	global_store_dwordx4 v[84:85], v[58:61], off
	global_load_dwordx4 v[58:61], v94, s[92:93]
	v_or_b32_e32 v90, v72, v83
	global_load_dwordx4 v[84:87], v[88:89], off offset:512
	s_waitcnt vmcnt(0)
	v_pk_mul_f32 v[58:59], v[58:59], s[2:3] op_sel_hi:[1,0]
	v_pk_mul_f32 v[60:61], v[60:61], s[2:3] op_sel_hi:[1,0]
	v_pk_fma_f32 v[54:55], v[54:55], v[58:59], v[84:85]
	v_pk_fma_f32 v[56:57], v[56:57], v[60:61], v[86:87]
	v_lshl_add_u64 v[84:85], v[90:91], 2, s[22:23]
	global_store_dwordx4 v[84:85], v[54:57], off
	s_nop 1
	v_or_b32_e32 v54, 0x90, v81
	v_lshlrev_b32_e32 v55, 2, v54
	global_load_dwordx4 v[84:87], v55, s[92:93]
	v_or_b32_e32 v72, v72, v54
	v_lshl_add_u64 v[72:73], v[72:73], 2, s[22:23]
	s_waitcnt vmcnt(0)
; template <class Epi, class Sched>
; __device__ __forceinline__ void gemm_phase(LAS unsigned char* lds, const int K, const int lda, const int ldb, const Sched& S, const Epi& E) {
;     ...
;         if (!has_next) break;
;     __device__ __forceinline__ void operator()(const Acc& acc, const Unit& u, int wr, int wc, int fr, int fq) const {
;         const int col0 = u.pn * BM + wc * 32 + 4 * fq;
; #pragma unroll
;         for (int m = 0; m < 4; ++m) { const int kb = wr * 64 + m * 16 + fr;
; #pragma unroll
;             for (int bj = 0; bj < 2; ++bj)
; #pragma unroll
;                 for (int n = 0; n < 2; ++n) { const int q = col0 + bj * HALF + n * 16, ka = q >> 10, nn = q & 1023;
;                     const f32x4 g = *(const f32x4*)(gate + nn) * (1.f / 2048.f);
;                     const size_t o = (size_t)(ka + 128 * kb) * D + nn; *(f32x4*)(X + o) = *(const f32x4*)(Xin + o) + g * acc[0][bj][m][n]; }
;             if (m & 1) __builtin_amdgcn_sched_barrier(0); }
	v_pk_mul_f32 v[56:57], v[84:85], s[2:3] op_sel_hi:[1,0]
	v_pk_mul_f32 v[90:91], v[86:87], s[2:3] op_sel_hi:[1,0]
	global_load_dwordx4 v[84:87], v[88:89], off offset:576
	s_waitcnt vmcnt(0)
	v_pk_fma_f32 v[52:53], v[52:53], v[90:91], v[86:87]
	v_pk_fma_f32 v[50:51], v[50:51], v[56:57], v[84:85]
	global_store_dwordx4 v[72:73], v[50:53], off
	s_nop 1
	v_add_u32_e32 v50, s8, v76
	v_ashrrev_i32_e32 v51, 31, v50
	v_lshlrev_b64 v[72:73], 10, v[50:51]
	v_or_b32_e32 v50, v72, v81
	v_mov_b32_e32 v51, v73
	v_lshlrev_b64 v[84:85], 2, v[50:51]
	v_lshl_add_u64 v[86:87], s[10:11], 0, v[84:85]
	global_load_dwordx4 v[50:53], v[86:87], off
	s_waitcnt vmcnt(0)
	v_pk_fma_f32 v[48:49], v[48:49], v[70:71], v[52:53]
	v_pk_fma_f32 v[46:47], v[46:47], v[68:69], v[50:51]
	v_lshl_add_u64 v[50:51], s[22:23], 0, v[84:85]
	global_store_dwordx4 v[50:51], v[46:49], off
	global_load_dwordx4 v[46:49], v[86:87], off offset:64
	v_or_b32_e32 v50, v72, v82
	v_mov_b32_e32 v51, v73
	s_waitcnt vmcnt(0)
	v_pk_fma_f32 v[44:45], v[44:45], v[64:65], v[48:49]
	v_pk_fma_f32 v[42:43], v[42:43], v[62:63], v[46:47]
	v_lshl_add_u64 v[46:47], v[50:51], 2, s[22:23]
	global_store_dwordx4 v[46:47], v[42:45], off
	global_load_dwordx4 v[42:45], v[86:87], off offset:512
	v_or_b32_e32 v46, v72, v83
	v_mov_b32_e32 v47, v73
	v_or_b32_e32 v72, v72, v54
	s_waitcnt vmcnt(0)
	v_pk_fma_f32 v[40:41], v[40:41], v[60:61], v[44:45]
	v_pk_fma_f32 v[38:39], v[38:39], v[58:59], v[42:43]
	v_lshl_add_u64 v[42:43], v[46:47], 2, s[22:23]
	global_store_dwordx4 v[42:43], v[38:41], off
	global_load_dwordx4 v[38:41], v[86:87], off offset:576
	s_waitcnt vmcnt(0)
	v_pk_fma_f32 v[36:37], v[36:37], v[90:91], v[40:41]
	v_pk_fma_f32 v[34:35], v[34:35], v[56:57], v[38:39]
	v_lshl_add_u64 v[38:39], v[72:73], 2, s[22:23]
	global_store_dwordx4 v[38:39], v[34:37], off
	s_nop 1
	v_add_u32_e32 v34, s8, v77
	v_ashrrev_i32_e32 v35, 31, v34
	v_lshlrev_b64 v[42:43], 10, v[34:35]
	v_or_b32_e32 v38, v42, v81
	v_mov_b32_e32 v39, v43
	v_lshlrev_b64 v[44:45], 2, v[38:39]
	global_load_dwordx4 v[34:37], v92, s[92:93]
	v_lshl_add_u64 v[46:47], s[10:11], 0, v[44:45]
	global_load_dwordx4 v[38:41], v[46:47], off
	s_waitcnt vmcnt(0)
	v_pk_mul_f32 v[34:35], v[34:35], s[2:3] op_sel_hi:[1,0]
	v_pk_mul_f32 v[36:37], v[36:37], s[2:3] op_sel_hi:[1,0]
	v_pk_fma_f32 v[30:31], v[30:31], v[34:35], v[38:39]
	v_pk_fma_f32 v[32:33], v[32:33], v[36:37], v[40:41]
	v_lshl_add_u64 v[38:39], s[22:23], 0, v[44:45]
	global_store_dwordx4 v[38:39], v[30:33], off
	global_load_dwordx4 v[30:33], v93, s[92:93]
	v_or_b32_e32 v44, v42, v82
	global_load_dwordx4 v[38:41], v[46:47], off offset:64
	v_mov_b32_e32 v45, v43
	s_waitcnt vmcnt(0)
	v_pk_mul_f32 v[30:31], v[30:31], s[2:3] op_sel_hi:[1,0]
	v_pk_mul_f32 v[32:33], v[32:33], s[2:3] op_sel_hi:[1,0]
	v_pk_fma_f32 v[26:27], v[26:27], v[30:31], v[38:39]
	v_pk_fma_f32 v[28:29], v[28:29], v[32:33], v[40:41]
	v_lshl_add_u64 v[38:39], v[44:45], 2, s[22:23]
	global_store_dwordx4 v[38:39], v[26:29], off
	global_load_dwordx4 v[26:29], v94, s[92:93]
	v_or_b32_e32 v44, v42, v83
	v_or_b32_e32 v42, v42, v54
	s_waitcnt vmcnt(0)
	v_pk_mul_f32 v[38:39], v[26:27], s[2:3] op_sel_hi:[1,0]
	v_pk_mul_f32 v[40:41], v[28:29], s[2:3] op_sel_hi:[1,0]
	global_load_dwordx4 v[26:29], v[46:47], off offset:512
	s_waitcnt vmcnt(0)
	v_pk_fma_f32 v[24:25], v[24:25], v[40:41], v[28:29]
	v_pk_fma_f32 v[22:23], v[22:23], v[38:39], v[26:27]
	v_lshl_add_u64 v[26:27], v[44:45], 2, s[22:23]
	global_store_dwordx4 v[26:27], v[22:25], off
	global_load_dwordx4 v[22:25], v55, s[92:93]
	s_waitcnt vmcnt(0)
	v_pk_mul_f32 v[26:27], v[22:23], s[2:3] op_sel_hi:[1,0]
	v_pk_mul_f32 v[28:29], v[24:25], s[2:3] op_sel_hi:[1,0]
	global_load_dwordx4 v[22:25], v[46:47], off offset:576
	s_waitcnt vmcnt(0)
	v_pk_fma_f32 v[20:21], v[20:21], v[28:29], v[24:25]
	v_pk_fma_f32 v[18:19], v[18:19], v[26:27], v[22:23]
	v_lshl_add_u64 v[22:23], v[42:43], 2, s[22:23]
	global_store_dwordx4 v[22:23], v[18:21], off
	s_nop 1
	v_add_u32_e32 v18, s8, v78
	v_ashrrev_i32_e32 v19, 31, v18
	v_lshlrev_b64 v[22:23], 10, v[18:19]
	v_or_b32_e32 v18, v22, v81
	v_mov_b32_e32 v19, v23
	v_lshlrev_b64 v[24:25], 2, v[18:19]
	v_lshl_add_u64 v[42:43], s[10:11], 0, v[24:25]
	global_load_dwordx4 v[18:21], v[42:43], off
	s_waitcnt vmcnt(0)
	v_pk_fma_f32 v[16:17], v[16:17], v[36:37], v[20:21]
	v_pk_fma_f32 v[14:15], v[14:15], v[34:35], v[18:19]
	v_lshl_add_u64 v[18:19], s[22:23], 0, v[24:25]
	global_store_dwordx4 v[18:19], v[14:17], off
	global_load_dwordx4 v[14:17], v[42:43], off offset:64
	v_or_b32_e32 v18, v22, v82
	v_mov_b32_e32 v19, v23
	s_waitcnt vmcnt(0)
	v_pk_fma_f32 v[12:13], v[12:13], v[32:33], v[16:17]
	v_pk_fma_f32 v[10:11], v[10:11], v[30:31], v[14:15]
	v_lshl_add_u64 v[14:15], v[18:19], 2, s[22:23]
	global_store_dwordx4 v[14:15], v[10:13], off
	global_load_dwordx4 v[10:13], v[42:43], off offset:512
	v_or_b32_e32 v14, v22, v83
	v_mov_b32_e32 v15, v23
	v_or_b32_e32 v22, v22, v54
	s_waitcnt vmcnt(0)
	v_pk_fma_f32 v[8:9], v[8:9], v[40:41], v[12:13]
	v_pk_fma_f32 v[6:7], v[6:7], v[38:39], v[10:11]
	v_lshl_add_u64 v[10:11], v[14:15], 2, s[22:23]
	global_store_dwordx4 v[10:11], v[6:9], off
	global_load_dwordx4 v[6:9], v[42:43], off offset:576
	s_waitcnt vmcnt(0)
	v_pk_fma_f32 v[4:5], v[4:5], v[28:29], v[8:9]
	v_pk_fma_f32 v[2:3], v[2:3], v[26:27], v[6:7]
	v_lshl_add_u64 v[6:7], v[22:23], 2, s[22:23]
	global_store_dwordx4 v[6:7], v[2:5], off
	s_and_b64 vcc, exec, s[0:1]
	s_mov_b32 s52, s49
	s_mov_b64 s[10:11], s[6:7]
	s_mov_b64 s[8:9], s[4:5]
	s_cbranch_vccnz .Lgx_c_exit
	s_cmpk_gt_u32 s40, 0xff
	s_cbranch_scc0 .LBB0_934
	s_barrier
	s_branch .LBB0_934
.Lgx_c_exit:
	s_waitcnt vmcnt(0)
	v_readlane_b32 s52, v253, 11
	s_cmpk_gt_u32 s40, 0xff
	v_readlane_b32 s53, v253, 12
	s_movk_i32 s48, 0x7000
	s_mov_b32 s47, s94

; #define PG8_STAGE(bufoff, gbase, voff) do { _Pragma("unroll") for (int _i = 0; _i < 2; ++_i) \
;         __builtin_amdgcn_global_load_lds((const unsigned*)((const char*)(gbase) + (voff)[_i]), (LAS unsigned*)(lds + (bufoff) + ldsw + _i * 8192), 16, 0, 0); } while (0)
; #define PG8_STAGE_A(bufoff, gbase, h, vv) do { if constexpr (GATHER) { _Pragma("unroll") for (int _i = 0; _i < 2; ++_i) \
;         __builtin_amdgcn_global_load_lds((const unsigned*)((const char*)(gbase) + (vv)[h][_i]), (LAS unsigned*)(lds + (bufoff) + ldsw + _i * 8192), 16, 0, 0); } \
;         else { PG8_STAGE(bufoff, (gbase) + (h) * hstepA, voffA); } } while (0)
; #define PG8_LDA(dst, b, h) do { _Pragma("unroll") for (int m = 0; m < 4; ++m) _Pragma("unroll") for (int k = 0; k < 2; ++k) dst[m][k] = *(const LAS bf16x8*)(lds + PG8_SA(b, h) + aoff + m * 2048 + k * 1024); } while (0)
; #define PG8_WAIT_L(n) asm volatile("s_waitcnt lgkmcnt(" #n ")" ::: "memory")
; template <class Epi, class Sched>
; __device__ __forceinline__ void gemm_phase(LAS unsigned char* lds, const int K, const int lda, const int ldb, const Sched& S, const Epi& E) {
;     ...
;         for (int t = 0; t < nt; t += 2) {
;             const bool last = (t == nt - 2);
;             const char* a1 = cA + (size_t)(t + 1) * kstep;
;             const char* a2 = last ? nA : cA + (size_t)(t + 2) * kstep; const char* b2 = last ? nB : cB + (size_t)(t + 2) * kstep;
;             const char* a3 = a2 + kstep; const char* b3 = b2 + kstep;
;             PG8_LDB(B0, 0, 0); PG8_SCHED; PG8_LDA(At, 0, 0); PG8_STAGE_A(PG8_SA(1, 1), a1, 1, vcur);
;             if constexpr (GATHER) { if (last) {
; #pragma unroll
;                 for (int h = 0; h < 2; ++h)
; #pragma unroll
;                     for (int i = 0; i < 2; ++i) vcur[h][i] = vnxt[h][i]; } }
;             PG8_WAIT_L(8); PG8_BAR; PG8_WAIT_L(0); PG8_MMA(0, 0, At, B0); PG8_BAR; PG8_SCHED;
;             PG8_LDB(B1, 0, 1); PG8_STAGE(PG8_SB(0, 0), b2, voffB);
;             PG8_BAR; PG8_WAIT_L(0); PG8_MMA(0, 1, At, B1); PG8_BAR;
;     ...
; #pragma unroll
;         for (int a = 0; a < 2; ++a)
; #pragma unroll
;             for (int b = 0; b < 2; ++b)
; #pragma unroll
;                 for (int m = 0; m < 4; ++m)
; #pragma unroll
;                     for (int n = 0; n < 2; ++n) acc[a][b][m][n] = (f32x4){0.f, 0.f, 0.f, 0.f};
;         cur = nxt; cA = nA; cB = nB; ++ui;
.LBB0_950:
	v_mov_b32_e32 v2, 0
	s_mov_b64 s[16:17], 0
	s_mov_b64 s[12:13], -1
	s_mov_b64 s[14:15], 0
	v_mov_b32_e32 v3, v2
	v_mov_b32_e32 v4, v2
	v_mov_b32_e32 v5, v2
	v_mov_b32_e32 v6, v2
	v_mov_b32_e32 v7, v2
	v_mov_b32_e32 v8, v2
	v_mov_b32_e32 v9, v2
	s_waitcnt vmcnt(0)
	v_mov_b64_e32 v[34:35], 0
	v_mov_b64_e32 v[36:37], 0
	v_mov_b64_e32 v[38:39], 0
	v_mov_b64_e32 v[40:41], 0
	v_mov_b64_e32 v[66:67], 0
	v_mov_b64_e32 v[68:69], 0
	v_mov_b64_e32 v[70:71], 0
	v_mov_b64_e32 v[72:73], 0
	v_mov_b64_e32 v[98:99], 0
	v_mov_b64_e32 v[100:101], 0
	v_mov_b64_e32 v[102:103], 0
	v_mov_b64_e32 v[104:105], 0
	v_mov_b64_e32 v[18:19], 0
	v_mov_b64_e32 v[20:21], 0
	v_mov_b64_e32 v[26:27], 0
	v_mov_b64_e32 v[28:29], 0
	v_mov_b64_e32 v[50:51], 0
	v_mov_b64_e32 v[52:53], 0
	v_mov_b64_e32 v[58:59], 0
	v_mov_b64_e32 v[60:61], 0
	v_mov_b64_e32 v[82:83], 0
	v_mov_b64_e32 v[84:85], 0
	v_mov_b64_e32 v[90:91], 0
	v_mov_b64_e32 v[92:93], 0
	v_mov_b64_e32 v[114:115], 0
	v_mov_b64_e32 v[116:117], 0
	v_mov_b64_e32 v[122:123], 0
	v_mov_b64_e32 v[124:125], 0
	v_mov_b64_e32 v[10:11], 0
	v_mov_b64_e32 v[12:13], 0
	v_mov_b64_e32 v[14:15], 0
	v_mov_b64_e32 v[16:17], 0
	v_mov_b64_e32 v[42:43], 0
	v_mov_b64_e32 v[44:45], 0
	v_mov_b64_e32 v[46:47], 0
	v_mov_b64_e32 v[48:49], 0
	v_mov_b64_e32 v[74:75], 0
	v_mov_b64_e32 v[76:77], 0
	v_mov_b64_e32 v[78:79], 0
	v_mov_b64_e32 v[80:81], 0
	v_mov_b64_e32 v[106:107], 0
	v_mov_b64_e32 v[108:109], 0
	v_mov_b64_e32 v[110:111], 0
	v_mov_b64_e32 v[112:113], 0
	v_mov_b64_e32 v[22:23], 0
	v_mov_b64_e32 v[24:25], 0
	v_mov_b64_e32 v[30:31], 0
	v_mov_b64_e32 v[32:33], 0
	v_mov_b64_e32 v[54:55], 0
	v_mov_b64_e32 v[56:57], 0
	v_mov_b64_e32 v[62:63], 0
	v_mov_b64_e32 v[64:65], 0
	v_mov_b64_e32 v[86:87], 0
	v_mov_b64_e32 v[88:89], 0
	v_mov_b64_e32 v[94:95], 0
	v_mov_b64_e32 v[96:97], 0
	v_mov_b64_e32 v[118:119], 0
	v_mov_b64_e32 v[120:121], 0
	v_mov_b64_e32 v[126:127], 0
	v_mov_b64_e32 v[128:129], 0
.LBB0_951:
	s_add_u32 s2, s8, s16
	s_addc_u32 s3, s9, s17
	s_add_u32 s20, s2, 0x100
	s_addc_u32 s21, s3, 0
	s_and_b64 s[18:19], s[14:15], exec
	s_cselect_b32 s21, s5, s21
	s_cselect_b32 s20, s4, s20
	s_add_u32 s16, s10, s16
	s_addc_u32 s17, s11, s17
	s_add_u32 s16, s16, 0x100
	s_addc_u32 s17, s17, 0
	s_add_i32 s50, 0, 0x10000
	s_and_b64 s[14:15], s[14:15], exec
	s_cselect_b32 s35, s7, s17
	s_cselect_b32 s34, s6, s16
	s_add_u32 s36, s2, 0x10080
	s_addc_u32 s37, s3, 0
	s_add_i32 s68, s50, s40
	s_add_i32 m0, s41, 0xc000
	s_add_i32 s2, s41, 0xe000
	s_add_i32 s67, 0, 0x14000
	s_add_i32 s66, s68, 0x2000
	s_add_u32 s18, s34, 0x10000
	v_add_u32_e32 v166, s50, v170
	s_addc_u32 s19, s35, 0
	s_add_i32 s55, s67, s40
	ds_read_b128 v[154:157], v166
	ds_read_b128 v[158:161], v166 offset:1024
	ds_read_b128 v[162:165], v166 offset:2048
	ds_read_b128 v[166:169], v166 offset:3072
	s_add_i32 s54, s55, 0x2000
	s_add_i32 s53, 0, 0x18000
	s_add_u32 s16, s20, 0x10000
	s_addc_u32 s17, s21, 0
	s_add_i32 s52, s53, s40
	s_add_i32 s45, 0, 0x1c000
	s_add_i32 s44, s52, 0x2000
	s_add_u32 s14, s34, 0x10080
	s_addc_u32 s15, s35, 0
	s_add_i32 s63, s45, s40
	s_add_i32 s62, s63, 0x2000
	v_lshl_add_u64 v[228:229], s[36:37], 0, v[134:135]
	ds_read_b128 v[176:179], v175
	ds_read_b128 v[180:183], v175 offset:1024
	ds_read_b128 v[184:187], v175 offset:2048
	ds_read_b128 v[188:191], v175 offset:3072
	ds_read_b128 v[192:195], v175 offset:4096
	ds_read_b128 v[216:219], v175 offset:5120
	ds_read_b128 v[220:223], v175 offset:6144
	ds_read_b128 v[224:227], v175 offset:7168
	global_load_lds_dwordx4 v[228:229], off
	v_lshl_add_u64 v[228:229], s[36:37], 0, v[132:133]
	s_mov_b32 m0, s2
	s_nop 0
	global_load_lds_dwordx4 v[228:229], off
	s_waitcnt lgkmcnt(8)
	s_barrier
	s_waitcnt lgkmcnt(0)
	s_setprio 1
	s_waitcnt lgkmcnt(0)
	v_mfma_f32_16x16x32_bf16 v[126:129], v[154:157], v[176:179], v[126:129]
	v_mfma_f32_16x16x32_bf16 v[118:121], v[162:165], v[176:179], v[118:121]
	v_mfma_f32_16x16x32_bf16 v[94:97], v[154:157], v[184:187], v[94:97]
	v_mfma_f32_16x16x32_bf16 v[86:89], v[162:165], v[184:187], v[86:89]
	v_mfma_f32_16x16x32_bf16 v[62:65], v[154:157], v[192:195], v[62:65]
	v_mfma_f32_16x16x32_bf16 v[54:57], v[162:165], v[192:195], v[54:57]
	v_mfma_f32_16x16x32_bf16 v[30:33], v[154:157], v[220:223], v[30:33]
	v_mfma_f32_16x16x32_bf16 v[22:25], v[162:165], v[220:223], v[22:25]
	v_mfma_f32_16x16x32_bf16 v[126:129], v[158:161], v[180:183], v[126:129]
	v_mfma_f32_16x16x32_bf16 v[118:121], v[166:169], v[180:183], v[118:121]
	v_mfma_f32_16x16x32_bf16 v[94:97], v[158:161], v[188:191], v[94:97]
	v_mfma_f32_16x16x32_bf16 v[86:89], v[166:169], v[188:191], v[86:89]
	v_mfma_f32_16x16x32_bf16 v[62:65], v[158:161], v[216:219], v[62:65]
	v_mfma_f32_16x16x32_bf16 v[54:57], v[166:169], v[216:219], v[54:57]
	v_mfma_f32_16x16x32_bf16 v[30:33], v[158:161], v[224:227], v[30:33]
	v_mfma_f32_16x16x32_bf16 v[22:25], v[166:169], v[224:227], v[22:25]
	s_setprio 0
	s_barrier
	s_mov_b32 m0, s68
	v_add_u32_e32 v214, s67, v170
	v_lshl_add_u64 v[244:245], s[34:35], 0, v[0:1]
	ds_read_b128 v[228:231], v214
	ds_read_b128 v[232:235], v214 offset:1024
	ds_read_b128 v[236:239], v214 offset:2048
	ds_read_b128 v[240:243], v214 offset:3072
	global_load_lds_dwordx4 v[244:245], off
	v_lshl_add_u64 v[246:247], s[34:35], 0, v[130:131]
	s_mov_b32 m0, s66
	s_nop 0
	global_load_lds_dwordx4 v[246:247], off
	s_barrier
; #define PG8_STAGE(bufoff, gbase, voff) do { _Pragma("unroll") for (int _i = 0; _i < 2; ++_i) \
;         __builtin_amdgcn_global_load_lds((const unsigned*)((const char*)(gbase) + (voff)[_i]), (LAS unsigned*)(lds + (bufoff) + ldsw + _i * 8192), 16, 0, 0); } while (0)
; #define PG8_STAGE_A(bufoff, gbase, h, vv) do { if constexpr (GATHER) { _Pragma("unroll") for (int _i = 0; _i < 2; ++_i) \
;         __builtin_amdgcn_global_load_lds((const unsigned*)((const char*)(gbase) + (vv)[h][_i]), (LAS unsigned*)(lds + (bufoff) + ldsw + _i * 8192), 16, 0, 0); } \
;         else { PG8_STAGE(bufoff, (gbase) + (h) * hstepA, voffA); } } while (0)
; #define PG8_LDA(dst, b, h) do { _Pragma("unroll") for (int m = 0; m < 4; ++m) _Pragma("unroll") for (int k = 0; k < 2; ++k) dst[m][k] = *(const LAS bf16x8*)(lds + PG8_SA(b, h) + aoff + m * 2048 + k * 1024); } while (0)
; #define PG8_LDB(dst, b, h) do { _Pragma("unroll") for (int n = 0; n < 2; ++n) _Pragma("unroll") for (int k = 0; k < 2; ++k) dst[n][k] = *(const LAS bf16x8*)(lds + PG8_SB(b, h) + boff + n * 2048 + k * 1024); } while (0)
; #define PG8_MMA(ai, bj, At, Bt) do { __builtin_amdgcn_s_setprio(1); _Pragma("unroll") for (int m = 0; m < 4; ++m) _Pragma("unroll") for (int n = 0; n < 2; ++n) _Pragma("unroll") for (int k = 0; k < 2; ++k) \
;         acc[ai][bj][m][n] = __builtin_amdgcn_mfma_f32_16x16x32_bf16(Bt[n][k], At[m][k], acc[ai][bj][m][n], 0, 0, 0); __builtin_amdgcn_s_setprio(0); } while (0)
; #define PG8_BAR __builtin_amdgcn_s_barrier()
; template <class Epi, class Sched>
; __device__ __forceinline__ void gemm_phase(LAS unsigned char* lds, const int K, const int lda, const int ldb, const Sched& S, const Epi& E) {
;     ...
;             PG8_BAR; PG8_WAIT_L(0); PG8_MMA(0, 1, At, B1); PG8_BAR;
;             PG8_LDA(At, 0, 1); PG8_STAGE_A(PG8_SA(0, 0), a2, 0, vcur);
;             PG8_BAR; PG8_WAIT_L(0); PG8_MMA(1, 0, At, B0); PG8_BAR; PG8_SCHED;
;             PG8_STAGE(PG8_SB(0, 1), b2 + hstepB, voffB);
;             PG8_WAIT_V(6); PG8_BAR; PG8_MMA(1, 1, At, B1); PG8_BAR;
;             PG8_LDB(B0, 1, 0); PG8_SCHED; PG8_LDA(At, 1, 0); PG8_STAGE_A(PG8_SA(0, 1), a2, 1, vcur);
;             PG8_WAIT_L(8); PG8_BAR; PG8_WAIT_L(0); PG8_MMA(0, 0, At, B0); PG8_BAR; PG8_SCHED;
;             PG8_LDB(B1, 1, 1); PG8_STAGE(PG8_SB(1, 0), b3, voffB);
;             PG8_BAR; PG8_WAIT_L(0); PG8_MMA(0, 1, At, B1); PG8_BAR;
	s_waitcnt lgkmcnt(0)
	s_setprio 1
	s_waitcnt lgkmcnt(0)
	v_mfma_f32_16x16x32_bf16 v[110:113], v[228:231], v[176:179], v[110:113]
	v_mfma_f32_16x16x32_bf16 v[106:109], v[236:239], v[176:179], v[106:109]
	v_mfma_f32_16x16x32_bf16 v[78:81], v[228:231], v[184:187], v[78:81]
	v_mfma_f32_16x16x32_bf16 v[74:77], v[236:239], v[184:187], v[74:77]
	v_mfma_f32_16x16x32_bf16 v[46:49], v[228:231], v[192:195], v[46:49]
	v_mfma_f32_16x16x32_bf16 v[42:45], v[236:239], v[192:195], v[42:45]
	v_mfma_f32_16x16x32_bf16 v[14:17], v[228:231], v[220:223], v[14:17]
	v_mfma_f32_16x16x32_bf16 v[10:13], v[236:239], v[220:223], v[10:13]
	v_mfma_f32_16x16x32_bf16 v[110:113], v[232:235], v[180:183], v[110:113]
	v_mfma_f32_16x16x32_bf16 v[106:109], v[240:243], v[180:183], v[106:109]
	v_mfma_f32_16x16x32_bf16 v[78:81], v[232:235], v[188:191], v[78:81]
	v_mfma_f32_16x16x32_bf16 v[74:77], v[240:243], v[188:191], v[74:77]
	v_mfma_f32_16x16x32_bf16 v[46:49], v[232:235], v[216:219], v[46:49]
	v_mfma_f32_16x16x32_bf16 v[42:45], v[240:243], v[216:219], v[42:45]
	v_mfma_f32_16x16x32_bf16 v[14:17], v[232:235], v[224:227], v[14:17]
	v_mfma_f32_16x16x32_bf16 v[10:13], v[240:243], v[224:227], v[10:13]
	s_setprio 0
	s_mov_b32 m0, s41
	v_lshl_add_u64 v[248:249], s[20:21], 0, v[134:135]
	s_barrier
	ds_read_b128 v[176:179], v175 offset:16384
	ds_read_b128 v[180:183], v175 offset:17408
	ds_read_b128 v[184:187], v175 offset:18432
	ds_read_b128 v[188:191], v175 offset:19456
	ds_read_b128 v[192:195], v175 offset:20480
	ds_read_b128 v[216:219], v175 offset:21504
	ds_read_b128 v[220:223], v175 offset:22528
	ds_read_b128 v[224:227], v175 offset:23552
	global_load_lds_dwordx4 v[248:249], off
	v_lshl_add_u64 v[214:215], s[20:21], 0, v[132:133]
	s_mov_b32 m0, s42
	s_nop 0
	global_load_lds_dwordx4 v[214:215], off
	s_barrier
	s_waitcnt lgkmcnt(0)
	s_setprio 1
	s_waitcnt lgkmcnt(0)
	v_mfma_f32_16x16x32_bf16 v[122:125], v[154:157], v[176:179], v[122:125]
	v_mfma_f32_16x16x32_bf16 v[114:117], v[162:165], v[176:179], v[114:117]
	v_mfma_f32_16x16x32_bf16 v[90:93], v[154:157], v[184:187], v[90:93]
	v_mfma_f32_16x16x32_bf16 v[82:85], v[162:165], v[184:187], v[82:85]
	v_mfma_f32_16x16x32_bf16 v[58:61], v[154:157], v[192:195], v[58:61]
	v_mfma_f32_16x16x32_bf16 v[50:53], v[162:165], v[192:195], v[50:53]
	v_mfma_f32_16x16x32_bf16 v[26:29], v[154:157], v[220:223], v[26:29]
	v_mfma_f32_16x16x32_bf16 v[18:21], v[162:165], v[220:223], v[18:21]
	v_mfma_f32_16x16x32_bf16 v[122:125], v[158:161], v[180:183], v[122:125]
	v_mfma_f32_16x16x32_bf16 v[114:117], v[166:169], v[180:183], v[114:117]
	v_mfma_f32_16x16x32_bf16 v[90:93], v[158:161], v[188:191], v[90:93]
	v_mfma_f32_16x16x32_bf16 v[82:85], v[166:169], v[188:191], v[82:85]
	v_mfma_f32_16x16x32_bf16 v[58:61], v[158:161], v[216:219], v[58:61]
	v_mfma_f32_16x16x32_bf16 v[50:53], v[166:169], v[216:219], v[50:53]
	v_mfma_f32_16x16x32_bf16 v[26:29], v[158:161], v[224:227], v[26:29]
	v_mfma_f32_16x16x32_bf16 v[18:21], v[166:169], v[224:227], v[18:21]
	s_setprio 0
	s_barrier
	s_mov_b32 m0, s55
	v_lshl_add_u64 v[154:155], s[18:19], 0, v[0:1]
	global_load_lds_dwordx4 v[154:155], off
	v_lshl_add_u64 v[154:155], s[18:19], 0, v[130:131]
	s_mov_b32 m0, s54
	s_nop 0
	global_load_lds_dwordx4 v[154:155], off
	s_waitcnt vmcnt(6)
	s_barrier
	s_setprio 1
	v_mfma_f32_16x16x32_bf16 v[102:105], v[228:231], v[176:179], v[102:105]
	v_mfma_f32_16x16x32_bf16 v[98:101], v[236:239], v[176:179], v[98:101]
	v_mfma_f32_16x16x32_bf16 v[70:73], v[228:231], v[184:187], v[70:73]
	v_mfma_f32_16x16x32_bf16 v[66:69], v[236:239], v[184:187], v[66:69]
	v_mfma_f32_16x16x32_bf16 v[38:41], v[228:231], v[192:195], v[38:41]
	v_mfma_f32_16x16x32_bf16 v[34:37], v[236:239], v[192:195], v[34:37]
	v_mfma_f32_16x16x32_bf16 v[6:9], v[228:231], v[220:223], v[6:9]
	v_mfma_f32_16x16x32_bf16 v[2:5], v[236:239], v[220:223], v[2:5]
	v_mfma_f32_16x16x32_bf16 v[102:105], v[232:235], v[180:183], v[102:105]
	v_mfma_f32_16x16x32_bf16 v[98:101], v[240:243], v[180:183], v[98:101]
	v_mfma_f32_16x16x32_bf16 v[70:73], v[232:235], v[188:191], v[70:73]
	v_mfma_f32_16x16x32_bf16 v[66:69], v[240:243], v[188:191], v[66:69]
	v_mfma_f32_16x16x32_bf16 v[38:41], v[232:235], v[216:219], v[38:41]
	v_mfma_f32_16x16x32_bf16 v[34:37], v[240:243], v[216:219], v[34:37]
	v_mfma_f32_16x16x32_bf16 v[6:9], v[232:235], v[224:227], v[6:9]
	v_mfma_f32_16x16x32_bf16 v[2:5], v[240:243], v[224:227], v[2:5]
	s_setprio 0
	v_add_u32_e32 v166, s53, v170
	s_barrier
	ds_read_b128 v[154:157], v166
	ds_read_b128 v[158:161], v166 offset:1024
	ds_read_b128 v[162:165], v166 offset:2048
	ds_read_b128 v[166:169], v166 offset:3072
	s_mov_b32 m0, s43
	v_lshl_add_u64 v[228:229], s[16:17], 0, v[134:135]
	ds_read_b128 v[176:179], v175 offset:32768
	ds_read_b128 v[180:183], v175 offset:33792
	ds_read_b128 v[184:187], v175 offset:34816
	ds_read_b128 v[188:191], v175 offset:35840
	ds_read_b128 v[192:195], v175 offset:36864
	ds_read_b128 v[216:219], v175 offset:37888
	ds_read_b128 v[220:223], v175 offset:38912
	ds_read_b128 v[224:227], v175 offset:39936
	global_load_lds_dwordx4 v[228:229], off
	v_lshl_add_u64 v[228:229], s[16:17], 0, v[132:133]
	s_mov_b32 m0, s46
	s_nop 0
	global_load_lds_dwordx4 v[228:229], off
	s_waitcnt lgkmcnt(8)
	s_barrier
; #define PG8_STAGE(bufoff, gbase, voff) do { _Pragma("unroll") for (int _i = 0; _i < 2; ++_i) \
;         __builtin_amdgcn_global_load_lds((const unsigned*)((const char*)(gbase) + (voff)[_i]), (LAS unsigned*)(lds + (bufoff) + ldsw + _i * 8192), 16, 0, 0); } while (0)
; #define PG8_STAGE_A(bufoff, gbase, h, vv) do { if constexpr (GATHER) { _Pragma("unroll") for (int _i = 0; _i < 2; ++_i) \
;         __builtin_amdgcn_global_load_lds((const unsigned*)((const char*)(gbase) + (vv)[h][_i]), (LAS unsigned*)(lds + (bufoff) + ldsw + _i * 8192), 16, 0, 0); } \
;         else { PG8_STAGE(bufoff, (gbase) + (h) * hstepA, voffA); } } while (0)
; #define PG8_LDA(dst, b, h) do { _Pragma("unroll") for (int m = 0; m < 4; ++m) _Pragma("unroll") for (int k = 0; k < 2; ++k) dst[m][k] = *(const LAS bf16x8*)(lds + PG8_SA(b, h) + aoff + m * 2048 + k * 1024); } while (0)
; #define PG8_MMA(ai, bj, At, Bt) do { __builtin_amdgcn_s_setprio(1); _Pragma("unroll") for (int m = 0; m < 4; ++m) _Pragma("unroll") for (int n = 0; n < 2; ++n) _Pragma("unroll") for (int k = 0; k < 2; ++k) \
;         acc[ai][bj][m][n] = __builtin_amdgcn_mfma_f32_16x16x32_bf16(Bt[n][k], At[m][k], acc[ai][bj][m][n], 0, 0, 0); __builtin_amdgcn_s_setprio(0); } while (0)
; #define PG8_WAIT_V(n) asm volatile("s_waitcnt vmcnt(" #n ")" ::: "memory")
; #define PG8_WAIT_L(n) asm volatile("s_waitcnt lgkmcnt(" #n ")" ::: "memory")
; #define PG8_BAR __builtin_amdgcn_s_barrier()
; #define PG8_SCHED __builtin_amdgcn_sched_barrier(0)
; template <class Epi, class Sched>
; __device__ __forceinline__ void gemm_phase(LAS unsigned char* lds, const int K, const int lda, const int ldb, const Sched& S, const Epi& E) {
;     ...
;             PG8_BAR; PG8_WAIT_L(0); PG8_MMA(0, 1, At, B1); PG8_BAR;
;             PG8_LDA(At, 1, 1); PG8_STAGE_A(PG8_SA(1, 0), a3, 0, vcur);
;             PG8_BAR; PG8_WAIT_L(0); PG8_MMA(1, 0, At, B0); PG8_BAR; PG8_SCHED;
;             PG8_STAGE(PG8_SB(1, 1), b3 + hstepB, voffB);
;             PG8_WAIT_V(6); PG8_BAR; PG8_MMA(1, 1, At, B1); PG8_BAR;
;         }
	s_waitcnt lgkmcnt(0)
	s_setprio 1
	s_waitcnt lgkmcnt(0)
	v_mfma_f32_16x16x32_bf16 v[126:129], v[154:157], v[176:179], v[126:129]
	v_mfma_f32_16x16x32_bf16 v[118:121], v[162:165], v[176:179], v[118:121]
	v_mfma_f32_16x16x32_bf16 v[94:97], v[154:157], v[184:187], v[94:97]
	v_mfma_f32_16x16x32_bf16 v[86:89], v[162:165], v[184:187], v[86:89]
	v_mfma_f32_16x16x32_bf16 v[62:65], v[154:157], v[192:195], v[62:65]
	v_mfma_f32_16x16x32_bf16 v[54:57], v[162:165], v[192:195], v[54:57]
	v_mfma_f32_16x16x32_bf16 v[30:33], v[154:157], v[220:223], v[30:33]
	v_mfma_f32_16x16x32_bf16 v[22:25], v[162:165], v[220:223], v[22:25]
	v_mfma_f32_16x16x32_bf16 v[126:129], v[158:161], v[180:183], v[126:129]
	v_mfma_f32_16x16x32_bf16 v[118:121], v[166:169], v[180:183], v[118:121]
	v_mfma_f32_16x16x32_bf16 v[94:97], v[158:161], v[188:191], v[94:97]
	v_mfma_f32_16x16x32_bf16 v[86:89], v[166:169], v[188:191], v[86:89]
	v_mfma_f32_16x16x32_bf16 v[62:65], v[158:161], v[216:219], v[62:65]
	v_mfma_f32_16x16x32_bf16 v[54:57], v[166:169], v[216:219], v[54:57]
	v_mfma_f32_16x16x32_bf16 v[30:33], v[158:161], v[224:227], v[30:33]
	v_mfma_f32_16x16x32_bf16 v[22:25], v[166:169], v[224:227], v[22:25]
	s_setprio 0
	s_barrier
	s_mov_b32 m0, s52
	v_add_u32_e32 v240, s45, v170
	v_lshl_add_u64 v[244:245], v[244:245], 0, s[64:65]
	ds_read_b128 v[228:231], v240
	ds_read_b128 v[232:235], v240 offset:1024
	ds_read_b128 v[236:239], v240 offset:2048
	ds_read_b128 v[240:243], v240 offset:3072
	global_load_lds_dwordx4 v[244:245], off
	v_lshl_add_u64 v[244:245], v[246:247], 0, s[64:65]
	s_mov_b32 m0, s44
	s_nop 0
	global_load_lds_dwordx4 v[244:245], off
	s_barrier
	s_waitcnt lgkmcnt(0)
	s_setprio 1
	s_waitcnt lgkmcnt(0)
	v_mfma_f32_16x16x32_bf16 v[110:113], v[228:231], v[176:179], v[110:113]
	v_mfma_f32_16x16x32_bf16 v[106:109], v[236:239], v[176:179], v[106:109]
	v_mfma_f32_16x16x32_bf16 v[78:81], v[228:231], v[184:187], v[78:81]
	v_mfma_f32_16x16x32_bf16 v[74:77], v[236:239], v[184:187], v[74:77]
	v_mfma_f32_16x16x32_bf16 v[46:49], v[228:231], v[192:195], v[46:49]
	v_mfma_f32_16x16x32_bf16 v[42:45], v[236:239], v[192:195], v[42:45]
	v_mfma_f32_16x16x32_bf16 v[14:17], v[228:231], v[220:223], v[14:17]
	v_mfma_f32_16x16x32_bf16 v[10:13], v[236:239], v[220:223], v[10:13]
	v_mfma_f32_16x16x32_bf16 v[110:113], v[232:235], v[180:183], v[110:113]
	v_mfma_f32_16x16x32_bf16 v[106:109], v[240:243], v[180:183], v[106:109]
	v_mfma_f32_16x16x32_bf16 v[78:81], v[232:235], v[188:191], v[78:81]
	v_mfma_f32_16x16x32_bf16 v[74:77], v[240:243], v[188:191], v[74:77]
	v_mfma_f32_16x16x32_bf16 v[46:49], v[232:235], v[216:219], v[46:49]
	v_mfma_f32_16x16x32_bf16 v[42:45], v[240:243], v[216:219], v[42:45]
	v_mfma_f32_16x16x32_bf16 v[14:17], v[232:235], v[224:227], v[14:17]
	v_mfma_f32_16x16x32_bf16 v[10:13], v[240:243], v[224:227], v[10:13]
	s_setprio 0
	s_mov_b32 m0, s47
	v_lshl_add_u64 v[244:245], v[248:249], 0, s[64:65]
	s_barrier
	ds_read_b128 v[176:179], v175 offset:49152
	ds_read_b128 v[180:183], v175 offset:50176
	ds_read_b128 v[184:187], v175 offset:51200
	ds_read_b128 v[188:191], v175 offset:52224
	ds_read_b128 v[192:195], v175 offset:53248
	ds_read_b128 v[216:219], v175 offset:54272
	ds_read_b128 v[220:223], v175 offset:55296
	ds_read_b128 v[224:227], v175 offset:56320
	global_load_lds_dwordx4 v[244:245], off
	v_lshl_add_u64 v[214:215], v[214:215], 0, s[64:65]
	s_mov_b32 m0, s48
	s_nop 0
	global_load_lds_dwordx4 v[214:215], off
	s_barrier
	s_waitcnt lgkmcnt(0)
	s_setprio 1
	s_waitcnt lgkmcnt(0)
	v_mfma_f32_16x16x32_bf16 v[122:125], v[154:157], v[176:179], v[122:125]
	v_mfma_f32_16x16x32_bf16 v[114:117], v[162:165], v[176:179], v[114:117]
	v_mfma_f32_16x16x32_bf16 v[90:93], v[154:157], v[184:187], v[90:93]
	v_mfma_f32_16x16x32_bf16 v[82:85], v[162:165], v[184:187], v[82:85]
	v_mfma_f32_16x16x32_bf16 v[58:61], v[154:157], v[192:195], v[58:61]
	v_mfma_f32_16x16x32_bf16 v[50:53], v[162:165], v[192:195], v[50:53]
	v_mfma_f32_16x16x32_bf16 v[26:29], v[154:157], v[220:223], v[26:29]
	v_mfma_f32_16x16x32_bf16 v[18:21], v[162:165], v[220:223], v[18:21]
	v_mfma_f32_16x16x32_bf16 v[122:125], v[158:161], v[180:183], v[122:125]
	v_mfma_f32_16x16x32_bf16 v[114:117], v[166:169], v[180:183], v[114:117]
	v_mfma_f32_16x16x32_bf16 v[90:93], v[158:161], v[188:191], v[90:93]
	v_mfma_f32_16x16x32_bf16 v[82:85], v[166:169], v[188:191], v[82:85]
	v_mfma_f32_16x16x32_bf16 v[58:61], v[158:161], v[216:219], v[58:61]
	v_mfma_f32_16x16x32_bf16 v[50:53], v[166:169], v[216:219], v[50:53]
	v_mfma_f32_16x16x32_bf16 v[26:29], v[158:161], v[224:227], v[26:29]
	v_mfma_f32_16x16x32_bf16 v[18:21], v[166:169], v[224:227], v[18:21]
	s_setprio 0
	s_barrier
	s_mov_b32 m0, s63
	v_lshl_add_u64 v[154:155], s[14:15], 0, v[0:1]
	global_load_lds_dwordx4 v[154:155], off
	v_lshl_add_u64 v[154:155], s[14:15], 0, v[130:131]
	s_mov_b32 m0, s62
	s_nop 0
	global_load_lds_dwordx4 v[154:155], off
	s_waitcnt vmcnt(6)
	s_barrier
	s_setprio 1
	v_mfma_f32_16x16x32_bf16 v[102:105], v[228:231], v[176:179], v[102:105]
	v_mfma_f32_16x16x32_bf16 v[98:101], v[236:239], v[176:179], v[98:101]
	v_mfma_f32_16x16x32_bf16 v[70:73], v[228:231], v[184:187], v[70:73]
	v_mfma_f32_16x16x32_bf16 v[66:69], v[236:239], v[184:187], v[66:69]
	v_mfma_f32_16x16x32_bf16 v[38:41], v[228:231], v[192:195], v[38:41]
	v_mfma_f32_16x16x32_bf16 v[34:37], v[236:239], v[192:195], v[34:37]
	v_mfma_f32_16x16x32_bf16 v[6:9], v[228:231], v[220:223], v[6:9]
	v_mfma_f32_16x16x32_bf16 v[2:5], v[236:239], v[220:223], v[2:5]
	v_mfma_f32_16x16x32_bf16 v[102:105], v[232:235], v[180:183], v[102:105]
	v_mfma_f32_16x16x32_bf16 v[98:101], v[240:243], v[180:183], v[98:101]
	v_mfma_f32_16x16x32_bf16 v[70:73], v[232:235], v[188:191], v[70:73]
	v_mfma_f32_16x16x32_bf16 v[66:69], v[240:243], v[188:191], v[66:69]
	v_mfma_f32_16x16x32_bf16 v[38:41], v[232:235], v[216:219], v[38:41]
	v_mfma_f32_16x16x32_bf16 v[34:37], v[240:243], v[216:219], v[34:37]
	v_mfma_f32_16x16x32_bf16 v[6:9], v[232:235], v[224:227], v[6:9]
	v_mfma_f32_16x16x32_bf16 v[2:5], v[240:243], v[224:227], v[2:5]
	s_setprio 0
	s_andn2_b64 vcc, exec, s[12:13]
	s_mov_b64 s[14:15], -1
	s_mov_b64 s[12:13], 0
	s_mov_b64 s[16:17], 0x100
	s_barrier
	s_cbranch_vccz .LBB0_951
	s_cmpk_gt_u32 s39, 0xff
	s_cbranch_scc1 .Lgx_d_pre
	s_barrier
; __device__ __forceinline__ unsigned pk2(float lo, float hi) { unsigned r; asm("v_cvt_pk_bf16_f32 %0, %1, %2" : "=v"(r) : "v"(lo), "v"(hi)); return r; }
;     __device__ __forceinline__ void operator()(const Acc& acc, const Unit& u, int wr, int wc, int fr, int fq) const {
;         const int col0 = u.pn * BM + wc * 32 + 8 * fq;
; #pragma unroll
;         for (int m = 0; m < 4; ++m) { const int ka = wr * 64 + m * 16 + fr; const float2 st = tw[ka]; const float2 t0 = tw[ka * (col0 & 127)];
; #pragma unroll
;             for (int bj = 0; bj < 2; ++bj) { const int q = col0 + bj * HALF, n = q >> 7, l1 = q & 127;
;                 bf16_t* dst = Yp + ((size_t)(ka * 1024 + n) * 2) * 128 + l1;
;                 float2 t = t0;
;                 unsigned ow[4], pw[4];
; #pragma unroll
;                 for (int nn = 0; nn < 2; ++nn) {
;                     float yr[4], yi[4];
; #pragma unroll
;                     for (int e = 0; e < 4; ++e) { const float a = acc[0][bj][m][nn][e], b = acc[1][bj][m][nn][e];
;                         yr[e] = a * t.x + b * t.y; yi[e] = b * t.x - a * t.y;
;                         const float tx = t.x * st.x - t.y * st.y, ty = t.x * st.y + t.y * st.x; t.x = tx; t.y = ty; }
;                     ow[2 * nn] = pk2(yr[0], yr[1]); ow[2 * nn + 1] = pk2(yr[2], yr[3]);
;                     pw[2 * nn] = pk2(yi[0], yi[1]); pw[2 * nn + 1] = pk2(yi[2], yi[3]); }
;                 *(u32x4*)dst = (u32x4){ow[0], ow[1], ow[2], ow[3]}; *(u32x4*)(dst + 128) = (u32x4){pw[0], pw[1], pw[2], pw[3]};
;                 __builtin_amdgcn_sched_barrier(0); } }
.Lgx_d_pre:
	global_load_dwordx2 v[158:159], v[136:137], off
	global_load_dwordx2 v[156:157], v[138:139], off
	v_mov_b32_e32 v160, v126
	v_mov_b32_e32 v161, v122
	s_lshl_b32 s9, s30, 1
	v_add_u32_e32 v154, s9, v171
	v_ashrrev_i32_e32 v155, 31, v154
	v_lshlrev_b64 v[154:155], 9, v[154:155]
	s_waitcnt vmcnt(0)
	v_pk_mul_f32 v[160:161], v[160:161], v[156:157]
	s_nop 0
	v_add_f32_e32 v176, v160, v161
	v_mov_b32_e32 v160, v122
	v_mov_b32_e32 v161, v126
	v_pk_mul_f32 v[160:161], v[160:161], v[156:157]
	v_pk_mul_f32 v[162:163], v[158:159], v[156:157] op_sel:[1,0] op_sel_hi:[0,1]
	v_sub_f32_e32 v177, v160, v161
	v_pk_mul_f32 v[160:161], v[158:159], v[156:157]
	v_mov_b32_e32 v165, v162
	v_mov_b32_e32 v164, v160
	v_mov_b32_e32 v162, v161
	v_pk_add_f32 v[166:167], v[164:165], v[162:163] neg_lo:[0,1] neg_hi:[0,1]
	v_pk_add_f32 v[162:163], v[164:165], v[162:163]
	v_mov_b32_e32 v160, v166
	v_mov_b32_e32 v161, v163
	v_mov_b32_e32 v122, v127
	v_mov_b32_e32 v126, v123
	v_pk_mul_f32 v[164:165], v[122:123], v[160:161]
	v_pk_mul_f32 v[122:123], v[126:127], v[160:161]
	v_add_f32_e32 v178, v164, v165
	v_sub_f32_e32 v179, v122, v123
	v_pk_mul_f32 v[122:123], v[158:159], v[162:163] op_sel:[1,1] op_sel_hi:[0,1]
	v_pk_fma_f32 v[162:163], v[158:159], v[166:167], v[122:123] neg_lo:[0,0,1] neg_hi:[0,0,1]
	v_pk_fma_f32 v[122:123], v[158:159], v[166:167], v[122:123] op_sel_hi:[1,0,1]
	s_nop 0
	v_mov_b32_e32 v163, v123
	v_mov_b32_e32 v122, v128
	v_mov_b32_e32 v123, v124
	v_pk_mul_f32 v[122:123], v[122:123], v[162:163]
	v_pk_mul_f32 v[126:127], v[158:159], v[162:163] op_sel:[1,0] op_sel_hi:[0,1]
	v_add_f32_e32 v180, v122, v123
	v_mov_b32_e32 v122, v124
	v_mov_b32_e32 v123, v128
	v_pk_mul_f32 v[122:123], v[122:123], v[162:163]
	v_mov_b32_e32 v165, v126
	v_sub_f32_e32 v181, v122, v123
	v_pk_mul_f32 v[122:123], v[158:159], v[162:163]
	v_mov_b32_e32 v124, v129
	v_mov_b32_e32 v164, v122
	v_mov_b32_e32 v126, v123
	v_pk_add_f32 v[168:169], v[164:165], v[126:127] neg_lo:[0,1] neg_hi:[0,1]
	v_pk_add_f32 v[166:167], v[164:165], v[126:127]
	v_mov_b32_e32 v164, v168
	v_mov_b32_e32 v165, v167
	v_pk_mul_f32 v[122:123], v[124:125], v[164:165]
	v_mov_b32_e32 v128, v125
	v_add_f32_e32 v124, v122, v123
	v_pk_mul_f32 v[122:123], v[128:129], v[164:165]
	v_cvt_pk_bf16_f32 v126, v177, v179
	s_nop 0
	v_sub_f32_e32 v125, v122, v123
	v_cvt_pk_bf16_f32 v123, v180, v124
	v_cvt_pk_bf16_f32 v127, v181, v125
	v_pk_mul_f32 v[124:125], v[158:159], v[166:167] op_sel:[1,1] op_sel_hi:[0,1]
	v_pk_fma_f32 v[166:167], v[158:159], v[168:169], v[124:125] neg_lo:[0,0,1] neg_hi:[0,0,1]
	v_pk_fma_f32 v[124:125], v[158:159], v[168:169], v[124:125] op_sel_hi:[1,0,1]
	v_cvt_pk_bf16_f32 v122, v176, v178
	s_nop 0
	v_mov_b32_e32 v167, v125
	v_mov_b32_e32 v124, v118
	v_mov_b32_e32 v125, v114
	v_pk_mul_f32 v[124:125], v[124:125], v[166:167]
	v_pk_mul_f32 v[128:129], v[158:159], v[166:167] op_sel:[1,0] op_sel_hi:[0,1]
	v_add_f32_e32 v178, v124, v125
	v_mov_b32_e32 v124, v114
	v_mov_b32_e32 v125, v118
	v_pk_mul_f32 v[124:125], v[124:125], v[166:167]
	v_mov_b32_e32 v169, v128
	v_sub_f32_e32 v179, v124, v125
	v_pk_mul_f32 v[124:125], v[158:159], v[166:167]
	v_mov_b32_e32 v114, v119
	v_mov_b32_e32 v168, v124
	v_mov_b32_e32 v128, v125
	v_pk_add_f32 v[124:125], v[168:169], v[128:129] neg_lo:[0,1] neg_hi:[0,1]
	v_pk_add_f32 v[128:129], v[168:169], v[128:129]
	v_mov_b32_e32 v168, v124
	v_mov_b32_e32 v169, v129
	v_mov_b32_e32 v118, v115
	v_pk_mul_f32 v[176:177], v[114:115], v[168:169]
	v_pk_mul_f32 v[114:115], v[118:119], v[168:169]
	v_add_f32_e32 v180, v176, v177
	v_sub_f32_e32 v181, v114, v115
	v_pk_mul_f32 v[114:115], v[158:159], v[128:129] op_sel:[1,1] op_sel_hi:[0,1]
	v_pk_fma_f32 v[118:119], v[158:159], v[124:125], v[114:115] op_sel_hi:[1,0,1] neg_lo:[0,0,1] neg_hi:[0,0,1]
	v_pk_fma_f32 v[124:125], v[158:159], v[124:125], v[114:115] op_sel_hi:[1,0,1]
	v_mov_b32_e32 v114, v118
	v_mov_b32_e32 v115, v125
	v_mov_b32_e32 v128, v120
	v_mov_b32_e32 v129, v116
	v_pk_mul_f32 v[124:125], v[158:159], v[124:125] op_sel:[1,1] op_sel_hi:[0,1]
	v_pk_mul_f32 v[128:129], v[128:129], v[114:115]
	v_pk_fma_f32 v[176:177], v[158:159], v[118:119], v[124:125] neg_lo:[0,0,1] neg_hi:[0,0,1]
	v_pk_fma_f32 v[118:119], v[158:159], v[118:119], v[124:125] op_sel_hi:[1,0,1]
	v_add_f32_e32 v182, v128, v129
	v_mov_b32_e32 v128, v116
	v_mov_b32_e32 v129, v120
	v_mov_b32_e32 v177, v119
	v_mov_b32_e32 v116, v121
	v_mov_b32_e32 v120, v117
	v_pk_mul_f32 v[128:129], v[128:129], v[114:115]
	v_pk_mul_f32 v[118:119], v[116:117], v[176:177]
	v_pk_mul_f32 v[116:117], v[120:121], v[176:177]
	v_sub_f32_e32 v129, v128, v129
	v_sub_f32_e32 v116, v116, v117
	v_add_f32_e32 v118, v118, v119
	v_cvt_pk_bf16_f32 v124, v178, v180
	v_cvt_pk_bf16_f32 v125, v182, v118
	v_cvt_pk_bf16_f32 v129, v129, v116
	v_lshl_add_u64 v[116:117], v[140:141], 0, v[154:155]
	v_cvt_pk_bf16_f32 v128, v179, v181
	global_store_dwordx4 v[116:117], v[122:125], off
	global_store_dwordx4 v[116:117], v[126:129], off offset:256
	v_mov_b32_e32 v118, v110
	v_mov_b32_e32 v119, v102
	v_pk_mul_f32 v[118:119], v[118:119], v[156:157]
	s_or_b32 s8, s9, 1
	v_add_f32_e32 v120, v118, v119
	v_mov_b32_e32 v118, v102
	v_mov_b32_e32 v119, v110
	v_pk_mul_f32 v[118:119], v[118:119], v[156:157]
	v_mov_b32_e32 v102, v111
	v_mov_b32_e32 v110, v103
	v_sub_f32_e32 v121, v118, v119
	v_pk_mul_f32 v[118:119], v[102:103], v[160:161]
	v_pk_mul_f32 v[102:103], v[110:111], v[160:161]
	v_add_f32_e32 v118, v118, v119
	v_sub_f32_e32 v110, v102, v103
	v_mov_b32_e32 v102, v112
	v_mov_b32_e32 v103, v104
	v_pk_mul_f32 v[102:103], v[102:103], v[162:163]
	v_add_u32_e32 v116, s8, v171
	v_add_f32_e32 v111, v102, v103
	v_mov_b32_e32 v102, v104
; __device__ __forceinline__ unsigned pk2(float lo, float hi) { unsigned r; asm("v_cvt_pk_bf16_f32 %0, %1, %2" : "=v"(r) : "v"(lo), "v"(hi)); return r; }
;     __device__ __forceinline__ void operator()(const Acc& acc, const Unit& u, int wr, int wc, int fr, int fq) const {
;         const int col0 = u.pn * BM + wc * 32 + 8 * fq;
; #pragma unroll
;         for (int m = 0; m < 4; ++m) { const int ka = wr * 64 + m * 16 + fr; const float2 st = tw[ka]; const float2 t0 = tw[ka * (col0 & 127)];
; #pragma unroll
;             for (int bj = 0; bj < 2; ++bj) { const int q = col0 + bj * HALF, n = q >> 7, l1 = q & 127;
;                 bf16_t* dst = Yp + ((size_t)(ka * 1024 + n) * 2) * 128 + l1;
;                 float2 t = t0;
;                 unsigned ow[4], pw[4];
; #pragma unroll
;                 for (int nn = 0; nn < 2; ++nn) {
;                     float yr[4], yi[4];
; #pragma unroll
;                     for (int e = 0; e < 4; ++e) { const float a = acc[0][bj][m][nn][e], b = acc[1][bj][m][nn][e];
;                         yr[e] = a * t.x + b * t.y; yi[e] = b * t.x - a * t.y;
;                         const float tx = t.x * st.x - t.y * st.y, ty = t.x * st.y + t.y * st.x; t.x = tx; t.y = ty; }
;                     ow[2 * nn] = pk2(yr[0], yr[1]); ow[2 * nn + 1] = pk2(yr[2], yr[3]);
;                     pw[2 * nn] = pk2(yi[0], yi[1]); pw[2 * nn + 1] = pk2(yi[2], yi[3]); }
;                 *(u32x4*)dst = (u32x4){ow[0], ow[1], ow[2], ow[3]}; *(u32x4*)(dst + 128) = (u32x4){pw[0], pw[1], pw[2], pw[3]};
;                 __builtin_amdgcn_sched_barrier(0); } }
	v_mov_b32_e32 v103, v112
	v_pk_mul_f32 v[102:103], v[102:103], v[162:163]
	v_mov_b32_e32 v104, v113
	v_sub_f32_e32 v119, v102, v103
	v_pk_mul_f32 v[102:103], v[104:105], v[164:165]
	v_mov_b32_e32 v112, v105
	v_add_f32_e32 v104, v102, v103
	v_pk_mul_f32 v[102:103], v[112:113], v[164:165]
	v_ashrrev_i32_e32 v117, 31, v116
	v_sub_f32_e32 v105, v102, v103
	v_cvt_pk_bf16_f32 v103, v111, v104
	v_cvt_pk_bf16_f32 v111, v119, v105
	v_mov_b32_e32 v104, v106
	v_mov_b32_e32 v105, v98
	v_pk_mul_f32 v[104:105], v[104:105], v[166:167]
	v_lshlrev_b64 v[116:117], 9, v[116:117]
	v_add_f32_e32 v112, v104, v105
	v_mov_b32_e32 v104, v98
	v_mov_b32_e32 v105, v106
	v_pk_mul_f32 v[104:105], v[104:105], v[166:167]
	v_mov_b32_e32 v98, v107
	v_mov_b32_e32 v106, v99
	v_sub_f32_e32 v113, v104, v105
	v_pk_mul_f32 v[104:105], v[98:99], v[168:169]
	v_pk_mul_f32 v[98:99], v[106:107], v[168:169]
	v_add_f32_e32 v104, v104, v105
	v_sub_f32_e32 v106, v98, v99
	v_mov_b32_e32 v98, v108
	v_mov_b32_e32 v99, v100
	v_pk_mul_f32 v[98:99], v[98:99], v[114:115]
	v_cvt_pk_bf16_f32 v102, v120, v118
	v_cvt_pk_bf16_f32 v104, v112, v104
	v_cvt_pk_bf16_f32 v112, v113, v106
	v_cvt_pk_bf16_f32 v110, v121, v110
	s_nop 0
	v_add_f32_e32 v105, v98, v99
	v_mov_b32_e32 v98, v100
	v_mov_b32_e32 v99, v108
	v_pk_mul_f32 v[98:99], v[98:99], v[114:115]
	v_mov_b32_e32 v100, v109
	v_sub_f32_e32 v107, v98, v99
	v_pk_mul_f32 v[98:99], v[100:101], v[176:177]
	v_mov_b32_e32 v108, v101
	v_add_f32_e32 v100, v98, v99
	v_pk_mul_f32 v[98:99], v[108:109], v[176:177]
	v_cvt_pk_bf16_f32 v105, v105, v100
	s_nop 0
	v_sub_f32_e32 v98, v98, v99
	v_cvt_pk_bf16_f32 v113, v107, v98
	v_lshl_add_u64 v[98:99], v[140:141], 0, v[116:117]
	global_store_dwordx4 v[98:99], v[102:105], off
	global_store_dwordx4 v[98:99], v[110:113], off offset:256
	global_load_dwordx2 v[102:103], v[142:143], off
	s_nop 0
	global_load_dwordx2 v[100:101], v[144:145], off
	v_mov_b32_e32 v104, v94
	v_mov_b32_e32 v105, v90
	v_add_u32_e32 v98, s9, v172
	v_ashrrev_i32_e32 v99, 31, v98
	v_lshlrev_b64 v[98:99], 9, v[98:99]
	s_waitcnt vmcnt(0)
	v_pk_mul_f32 v[104:105], v[104:105], v[100:101]
	s_nop 0
	v_add_f32_e32 v114, v104, v105
	v_mov_b32_e32 v104, v90
	v_mov_b32_e32 v105, v94
	v_pk_mul_f32 v[104:105], v[104:105], v[100:101]
	v_pk_mul_f32 v[106:107], v[102:103], v[100:101] op_sel:[1,0] op_sel_hi:[0,1]
	v_sub_f32_e32 v115, v104, v105
	v_pk_mul_f32 v[104:105], v[102:103], v[100:101]
	v_mov_b32_e32 v109, v106
	v_mov_b32_e32 v108, v104
	v_mov_b32_e32 v106, v105
	v_pk_add_f32 v[110:111], v[108:109], v[106:107] neg_lo:[0,1] neg_hi:[0,1]
	v_pk_add_f32 v[106:107], v[108:109], v[106:107]
	v_mov_b32_e32 v104, v110
	v_mov_b32_e32 v105, v107
	v_mov_b32_e32 v90, v95
	v_mov_b32_e32 v94, v91
	v_pk_mul_f32 v[108:109], v[90:91], v[104:105]
	v_pk_mul_f32 v[90:91], v[94:95], v[104:105]
	v_add_f32_e32 v116, v108, v109
	v_sub_f32_e32 v117, v90, v91
	v_pk_mul_f32 v[90:91], v[102:103], v[106:107] op_sel:[1,1] op_sel_hi:[0,1]
	v_pk_fma_f32 v[106:107], v[102:103], v[110:111], v[90:91] neg_lo:[0,0,1] neg_hi:[0,0,1]
	v_pk_fma_f32 v[90:91], v[102:103], v[110:111], v[90:91] op_sel_hi:[1,0,1]
	s_nop 0
	v_mov_b32_e32 v107, v91
	v_mov_b32_e32 v90, v96
	v_mov_b32_e32 v91, v92
	v_pk_mul_f32 v[90:91], v[90:91], v[106:107]
	v_pk_mul_f32 v[94:95], v[102:103], v[106:107] op_sel:[1,0] op_sel_hi:[0,1]
	v_add_f32_e32 v118, v90, v91
	v_mov_b32_e32 v90, v92
	v_mov_b32_e32 v91, v96
	v_pk_mul_f32 v[90:91], v[90:91], v[106:107]
	v_mov_b32_e32 v109, v94
	v_sub_f32_e32 v119, v90, v91
	v_pk_mul_f32 v[90:91], v[102:103], v[106:107]
	v_mov_b32_e32 v92, v97
	v_mov_b32_e32 v108, v90
	v_mov_b32_e32 v94, v91
	v_pk_add_f32 v[112:113], v[108:109], v[94:95] neg_lo:[0,1] neg_hi:[0,1]
	v_pk_add_f32 v[110:111], v[108:109], v[94:95]
	v_mov_b32_e32 v108, v112
	v_mov_b32_e32 v109, v111
	v_pk_mul_f32 v[90:91], v[92:93], v[108:109]
	v_mov_b32_e32 v96, v93
	v_add_f32_e32 v92, v90, v91
	v_pk_mul_f32 v[90:91], v[96:97], v[108:109]
	v_cvt_pk_bf16_f32 v94, v115, v117
	s_nop 0
	v_sub_f32_e32 v93, v90, v91
	v_cvt_pk_bf16_f32 v91, v118, v92
	v_cvt_pk_bf16_f32 v95, v119, v93
	v_pk_mul_f32 v[92:93], v[102:103], v[110:111] op_sel:[1,1] op_sel_hi:[0,1]
	v_pk_fma_f32 v[110:111], v[102:103], v[112:113], v[92:93] neg_lo:[0,0,1] neg_hi:[0,0,1]
	v_pk_fma_f32 v[92:93], v[102:103], v[112:113], v[92:93] op_sel_hi:[1,0,1]
	v_cvt_pk_bf16_f32 v90, v114, v116
	s_nop 0
	v_mov_b32_e32 v111, v93
	v_mov_b32_e32 v92, v86
	v_mov_b32_e32 v93, v82
	v_pk_mul_f32 v[92:93], v[92:93], v[110:111]
	v_pk_mul_f32 v[96:97], v[102:103], v[110:111] op_sel:[1,0] op_sel_hi:[0,1]
	v_add_f32_e32 v116, v92, v93
	v_mov_b32_e32 v92, v82
	v_mov_b32_e32 v93, v86
	v_pk_mul_f32 v[92:93], v[92:93], v[110:111]
	v_mov_b32_e32 v113, v96
	v_sub_f32_e32 v117, v92, v93
	v_pk_mul_f32 v[92:93], v[102:103], v[110:111]
	v_mov_b32_e32 v82, v87
	v_mov_b32_e32 v112, v92
	v_mov_b32_e32 v96, v93
	v_pk_add_f32 v[92:93], v[112:113], v[96:97] neg_lo:[0,1] neg_hi:[0,1]
	v_pk_add_f32 v[96:97], v[112:113], v[96:97]
	v_mov_b32_e32 v112, v92
	v_mov_b32_e32 v113, v97
	v_mov_b32_e32 v86, v83
	v_pk_mul_f32 v[114:115], v[82:83], v[112:113]
	v_pk_mul_f32 v[82:83], v[86:87], v[112:113]
	v_add_f32_e32 v118, v114, v115
	v_sub_f32_e32 v119, v82, v83
	v_pk_mul_f32 v[82:83], v[102:103], v[96:97] op_sel:[1,1] op_sel_hi:[0,1]
	v_pk_fma_f32 v[86:87], v[102:103], v[92:93], v[82:83] op_sel_hi:[1,0,1] neg_lo:[0,0,1] neg_hi:[0,0,1]
	v_pk_fma_f32 v[92:93], v[102:103], v[92:93], v[82:83] op_sel_hi:[1,0,1]
	v_mov_b32_e32 v82, v86
	v_mov_b32_e32 v83, v93
	v_mov_b32_e32 v96, v88
	v_mov_b32_e32 v97, v84
	v_pk_mul_f32 v[92:93], v[102:103], v[92:93] op_sel:[1,1] op_sel_hi:[0,1]
	v_pk_mul_f32 v[96:97], v[96:97], v[82:83]
; __device__ __forceinline__ unsigned pk2(float lo, float hi) { unsigned r; asm("v_cvt_pk_bf16_f32 %0, %1, %2" : "=v"(r) : "v"(lo), "v"(hi)); return r; }
;     __device__ __forceinline__ void operator()(const Acc& acc, const Unit& u, int wr, int wc, int fr, int fq) const {
;         const int col0 = u.pn * BM + wc * 32 + 8 * fq;
; #pragma unroll
;         for (int m = 0; m < 4; ++m) { const int ka = wr * 64 + m * 16 + fr; const float2 st = tw[ka]; const float2 t0 = tw[ka * (col0 & 127)];
; #pragma unroll
;             for (int bj = 0; bj < 2; ++bj) { const int q = col0 + bj * HALF, n = q >> 7, l1 = q & 127;
;                 bf16_t* dst = Yp + ((size_t)(ka * 1024 + n) * 2) * 128 + l1;
;                 float2 t = t0;
;                 unsigned ow[4], pw[4];
; #pragma unroll
;                 for (int nn = 0; nn < 2; ++nn) {
;                     float yr[4], yi[4];
; #pragma unroll
;                     for (int e = 0; e < 4; ++e) { const float a = acc[0][bj][m][nn][e], b = acc[1][bj][m][nn][e];
;                         yr[e] = a * t.x + b * t.y; yi[e] = b * t.x - a * t.y;
;                         const float tx = t.x * st.x - t.y * st.y, ty = t.x * st.y + t.y * st.x; t.x = tx; t.y = ty; }
;                     ow[2 * nn] = pk2(yr[0], yr[1]); ow[2 * nn + 1] = pk2(yr[2], yr[3]);
;                     pw[2 * nn] = pk2(yi[0], yi[1]); pw[2 * nn + 1] = pk2(yi[2], yi[3]); }
;                 *(u32x4*)dst = (u32x4){ow[0], ow[1], ow[2], ow[3]}; *(u32x4*)(dst + 128) = (u32x4){pw[0], pw[1], pw[2], pw[3]};
;                 __builtin_amdgcn_sched_barrier(0); } }
	v_pk_fma_f32 v[114:115], v[102:103], v[86:87], v[92:93] neg_lo:[0,0,1] neg_hi:[0,0,1]
	v_pk_fma_f32 v[86:87], v[102:103], v[86:87], v[92:93] op_sel_hi:[1,0,1]
	v_add_f32_e32 v120, v96, v97
	v_mov_b32_e32 v96, v84
	v_mov_b32_e32 v97, v88
	v_mov_b32_e32 v115, v87
	v_mov_b32_e32 v84, v89
	v_mov_b32_e32 v88, v85
	v_pk_mul_f32 v[96:97], v[96:97], v[82:83]
	v_pk_mul_f32 v[86:87], v[84:85], v[114:115]
	v_pk_mul_f32 v[84:85], v[88:89], v[114:115]
	v_sub_f32_e32 v97, v96, v97
	v_sub_f32_e32 v84, v84, v85
	v_add_f32_e32 v86, v86, v87
	v_cvt_pk_bf16_f32 v92, v116, v118
	v_cvt_pk_bf16_f32 v93, v120, v86
	v_cvt_pk_bf16_f32 v97, v97, v84
	v_lshl_add_u64 v[84:85], v[140:141], 0, v[98:99]
	v_cvt_pk_bf16_f32 v96, v117, v119
	global_store_dwordx4 v[84:85], v[90:93], off
	global_store_dwordx4 v[84:85], v[94:97], off offset:256
	v_mov_b32_e32 v86, v78
	v_mov_b32_e32 v87, v70
	v_pk_mul_f32 v[86:87], v[86:87], v[100:101]
	v_add_u32_e32 v84, s8, v172
	v_add_f32_e32 v88, v86, v87
	v_mov_b32_e32 v86, v70
	v_mov_b32_e32 v87, v78
	v_pk_mul_f32 v[86:87], v[86:87], v[100:101]
	v_mov_b32_e32 v70, v79
	v_mov_b32_e32 v78, v71
	v_sub_f32_e32 v89, v86, v87
	v_pk_mul_f32 v[86:87], v[70:71], v[104:105]
	v_pk_mul_f32 v[70:71], v[78:79], v[104:105]
	v_add_f32_e32 v86, v86, v87
	v_sub_f32_e32 v78, v70, v71
	v_mov_b32_e32 v70, v80
	v_mov_b32_e32 v71, v72
	v_pk_mul_f32 v[70:71], v[70:71], v[106:107]
	v_ashrrev_i32_e32 v85, 31, v84
	v_add_f32_e32 v79, v70, v71
	v_mov_b32_e32 v70, v72
	v_mov_b32_e32 v71, v80
	v_pk_mul_f32 v[70:71], v[70:71], v[106:107]
	v_mov_b32_e32 v72, v81
	v_sub_f32_e32 v87, v70, v71
	v_pk_mul_f32 v[70:71], v[72:73], v[108:109]
	v_mov_b32_e32 v80, v73
	v_add_f32_e32 v72, v70, v71
	v_pk_mul_f32 v[70:71], v[80:81], v[108:109]
	v_lshlrev_b64 v[84:85], 9, v[84:85]
	v_sub_f32_e32 v73, v70, v71
	v_cvt_pk_bf16_f32 v71, v79, v72
	v_cvt_pk_bf16_f32 v79, v87, v73
	v_mov_b32_e32 v72, v74
	v_mov_b32_e32 v73, v66
	v_pk_mul_f32 v[72:73], v[72:73], v[110:111]
	v_cvt_pk_bf16_f32 v70, v88, v86
	v_cvt_pk_bf16_f32 v78, v89, v78
	s_nop 0
	v_add_f32_e32 v80, v72, v73
	v_mov_b32_e32 v72, v66
	v_mov_b32_e32 v73, v74
	v_pk_mul_f32 v[72:73], v[72:73], v[110:111]
	v_mov_b32_e32 v66, v75
	v_mov_b32_e32 v74, v67
	v_sub_f32_e32 v81, v72, v73
	v_pk_mul_f32 v[72:73], v[66:67], v[112:113]
	v_pk_mul_f32 v[66:67], v[74:75], v[112:113]
	v_add_f32_e32 v72, v72, v73
	v_sub_f32_e32 v74, v66, v67
	v_mov_b32_e32 v66, v76
	v_mov_b32_e32 v67, v68
	v_pk_mul_f32 v[66:67], v[66:67], v[82:83]
	v_cvt_pk_bf16_f32 v72, v80, v72
	v_cvt_pk_bf16_f32 v80, v81, v74
	s_nop 0
	v_add_f32_e32 v73, v66, v67
	v_mov_b32_e32 v66, v68
	v_mov_b32_e32 v67, v76
	v_pk_mul_f32 v[66:67], v[66:67], v[82:83]
	v_mov_b32_e32 v68, v77
	v_sub_f32_e32 v75, v66, v67
	v_pk_mul_f32 v[66:67], v[68:69], v[114:115]
	v_mov_b32_e32 v76, v69
	v_add_f32_e32 v68, v66, v67
	v_pk_mul_f32 v[66:67], v[76:77], v[114:115]
	v_cvt_pk_bf16_f32 v73, v73, v68
	s_nop 0
	v_sub_f32_e32 v66, v66, v67
	v_cvt_pk_bf16_f32 v81, v75, v66
	v_lshl_add_u64 v[66:67], v[140:141], 0, v[84:85]
	global_store_dwordx4 v[66:67], v[70:73], off
	global_store_dwordx4 v[66:67], v[78:81], off offset:256
	global_load_dwordx2 v[70:71], v[146:147], off
	s_nop 0
	global_load_dwordx2 v[68:69], v[148:149], off
	v_mov_b32_e32 v72, v62
	v_mov_b32_e32 v73, v58
	v_add_u32_e32 v66, s9, v173
	v_ashrrev_i32_e32 v67, 31, v66
	v_lshlrev_b64 v[66:67], 9, v[66:67]
	s_waitcnt vmcnt(0)
	v_pk_mul_f32 v[72:73], v[72:73], v[68:69]
	s_nop 0
	v_add_f32_e32 v82, v72, v73
	v_mov_b32_e32 v72, v58
	v_mov_b32_e32 v73, v62
	v_pk_mul_f32 v[72:73], v[72:73], v[68:69]
	v_pk_mul_f32 v[74:75], v[70:71], v[68:69] op_sel:[1,0] op_sel_hi:[0,1]
	v_sub_f32_e32 v83, v72, v73
	v_pk_mul_f32 v[72:73], v[70:71], v[68:69]
	v_mov_b32_e32 v77, v74
	v_mov_b32_e32 v76, v72
	v_mov_b32_e32 v74, v73
	v_pk_add_f32 v[78:79], v[76:77], v[74:75] neg_lo:[0,1] neg_hi:[0,1]
	v_pk_add_f32 v[74:75], v[76:77], v[74:75]
	v_mov_b32_e32 v72, v78
	v_mov_b32_e32 v73, v75
	v_mov_b32_e32 v58, v63
	v_mov_b32_e32 v62, v59
	v_pk_mul_f32 v[76:77], v[58:59], v[72:73]
	v_pk_mul_f32 v[58:59], v[62:63], v[72:73]
	v_add_f32_e32 v84, v76, v77
	v_sub_f32_e32 v85, v58, v59
	v_pk_mul_f32 v[58:59], v[70:71], v[74:75] op_sel:[1,1] op_sel_hi:[0,1]
	v_pk_fma_f32 v[74:75], v[70:71], v[78:79], v[58:59] neg_lo:[0,0,1] neg_hi:[0,0,1]
	v_pk_fma_f32 v[58:59], v[70:71], v[78:79], v[58:59] op_sel_hi:[1,0,1]
	s_nop 0
	v_mov_b32_e32 v75, v59
	v_mov_b32_e32 v58, v64
	v_mov_b32_e32 v59, v60
	v_pk_mul_f32 v[58:59], v[58:59], v[74:75]
	v_pk_mul_f32 v[62:63], v[70:71], v[74:75] op_sel:[1,0] op_sel_hi:[0,1]
	v_add_f32_e32 v86, v58, v59
	v_mov_b32_e32 v58, v60
	v_mov_b32_e32 v59, v64
	v_pk_mul_f32 v[58:59], v[58:59], v[74:75]
	v_mov_b32_e32 v77, v62
	v_sub_f32_e32 v87, v58, v59
	v_pk_mul_f32 v[58:59], v[70:71], v[74:75]
	v_mov_b32_e32 v60, v65
	v_mov_b32_e32 v76, v58
	v_mov_b32_e32 v62, v59
	v_pk_add_f32 v[80:81], v[76:77], v[62:63] neg_lo:[0,1] neg_hi:[0,1]
	v_pk_add_f32 v[78:79], v[76:77], v[62:63]
	v_mov_b32_e32 v76, v80
	v_mov_b32_e32 v77, v79
	v_pk_mul_f32 v[58:59], v[60:61], v[76:77]
	v_mov_b32_e32 v64, v61
	v_add_f32_e32 v60, v58, v59
	v_pk_mul_f32 v[58:59], v[64:65], v[76:77]
	v_cvt_pk_bf16_f32 v62, v83, v85
	s_nop 0
	v_sub_f32_e32 v61, v58, v59
	v_cvt_pk_bf16_f32 v59, v86, v60
	v_cvt_pk_bf16_f32 v63, v87, v61
	v_pk_mul_f32 v[60:61], v[70:71], v[78:79] op_sel:[1,1] op_sel_hi:[0,1]
	v_pk_fma_f32 v[78:79], v[70:71], v[80:81], v[60:61] neg_lo:[0,0,1] neg_hi:[0,0,1]
	v_pk_fma_f32 v[60:61], v[70:71], v[80:81], v[60:61] op_sel_hi:[1,0,1]
	v_cvt_pk_bf16_f32 v58, v82, v84
	s_nop 0
	v_mov_b32_e32 v79, v61
	v_mov_b32_e32 v60, v54
	v_mov_b32_e32 v61, v50
	v_pk_mul_f32 v[60:61], v[60:61], v[78:79]
; __device__ __forceinline__ unsigned pk2(float lo, float hi) { unsigned r; asm("v_cvt_pk_bf16_f32 %0, %1, %2" : "=v"(r) : "v"(lo), "v"(hi)); return r; }
;     __device__ __forceinline__ void operator()(const Acc& acc, const Unit& u, int wr, int wc, int fr, int fq) const {
;         const int col0 = u.pn * BM + wc * 32 + 8 * fq;
; #pragma unroll
;         for (int m = 0; m < 4; ++m) { const int ka = wr * 64 + m * 16 + fr; const float2 st = tw[ka]; const float2 t0 = tw[ka * (col0 & 127)];
; #pragma unroll
;             for (int bj = 0; bj < 2; ++bj) { const int q = col0 + bj * HALF, n = q >> 7, l1 = q & 127;
;                 bf16_t* dst = Yp + ((size_t)(ka * 1024 + n) * 2) * 128 + l1;
;                 float2 t = t0;
;                 unsigned ow[4], pw[4];
; #pragma unroll
;                 for (int nn = 0; nn < 2; ++nn) {
;                     float yr[4], yi[4];
; #pragma unroll
;                     for (int e = 0; e < 4; ++e) { const float a = acc[0][bj][m][nn][e], b = acc[1][bj][m][nn][e];
;                         yr[e] = a * t.x + b * t.y; yi[e] = b * t.x - a * t.y;
;                         const float tx = t.x * st.x - t.y * st.y, ty = t.x * st.y + t.y * st.x; t.x = tx; t.y = ty; }
;                     ow[2 * nn] = pk2(yr[0], yr[1]); ow[2 * nn + 1] = pk2(yr[2], yr[3]);
;                     pw[2 * nn] = pk2(yi[0], yi[1]); pw[2 * nn + 1] = pk2(yi[2], yi[3]); }
;                 *(u32x4*)dst = (u32x4){ow[0], ow[1], ow[2], ow[3]}; *(u32x4*)(dst + 128) = (u32x4){pw[0], pw[1], pw[2], pw[3]};
;                 __builtin_amdgcn_sched_barrier(0); } }
	v_pk_mul_f32 v[64:65], v[70:71], v[78:79] op_sel:[1,0] op_sel_hi:[0,1]
	v_add_f32_e32 v84, v60, v61
	v_mov_b32_e32 v60, v50
	v_mov_b32_e32 v61, v54
	v_pk_mul_f32 v[60:61], v[60:61], v[78:79]
	v_mov_b32_e32 v81, v64
	v_sub_f32_e32 v85, v60, v61
	v_pk_mul_f32 v[60:61], v[70:71], v[78:79]
	v_mov_b32_e32 v50, v55
	v_mov_b32_e32 v80, v60
	v_mov_b32_e32 v64, v61
	v_pk_add_f32 v[60:61], v[80:81], v[64:65] neg_lo:[0,1] neg_hi:[0,1]
	v_pk_add_f32 v[64:65], v[80:81], v[64:65]
	v_mov_b32_e32 v80, v60
	v_mov_b32_e32 v81, v65
	v_mov_b32_e32 v54, v51
	v_pk_mul_f32 v[82:83], v[50:51], v[80:81]
	v_pk_mul_f32 v[50:51], v[54:55], v[80:81]
	v_add_f32_e32 v86, v82, v83
	v_sub_f32_e32 v87, v50, v51
	v_pk_mul_f32 v[50:51], v[70:71], v[64:65] op_sel:[1,1] op_sel_hi:[0,1]
	v_pk_fma_f32 v[54:55], v[70:71], v[60:61], v[50:51] op_sel_hi:[1,0,1] neg_lo:[0,0,1] neg_hi:[0,0,1]
	v_pk_fma_f32 v[60:61], v[70:71], v[60:61], v[50:51] op_sel_hi:[1,0,1]
	v_mov_b32_e32 v50, v54
	v_mov_b32_e32 v51, v61
	v_mov_b32_e32 v64, v56
	v_mov_b32_e32 v65, v52
	v_pk_mul_f32 v[60:61], v[70:71], v[60:61] op_sel:[1,1] op_sel_hi:[0,1]
	v_pk_mul_f32 v[64:65], v[64:65], v[50:51]
	v_pk_fma_f32 v[82:83], v[70:71], v[54:55], v[60:61] neg_lo:[0,0,1] neg_hi:[0,0,1]
	v_pk_fma_f32 v[54:55], v[70:71], v[54:55], v[60:61] op_sel_hi:[1,0,1]
	v_add_f32_e32 v88, v64, v65
	v_mov_b32_e32 v64, v52
	v_mov_b32_e32 v65, v56
	v_mov_b32_e32 v83, v55
	v_mov_b32_e32 v52, v57
	v_mov_b32_e32 v56, v53
	v_pk_mul_f32 v[64:65], v[64:65], v[50:51]
	v_pk_mul_f32 v[54:55], v[52:53], v[82:83]
	v_pk_mul_f32 v[52:53], v[56:57], v[82:83]
	v_sub_f32_e32 v65, v64, v65
	v_sub_f32_e32 v52, v52, v53
	v_add_f32_e32 v54, v54, v55
	v_cvt_pk_bf16_f32 v60, v84, v86
	v_cvt_pk_bf16_f32 v61, v88, v54
	v_cvt_pk_bf16_f32 v65, v65, v52
	v_lshl_add_u64 v[52:53], v[140:141], 0, v[66:67]
	v_cvt_pk_bf16_f32 v64, v85, v87
	global_store_dwordx4 v[52:53], v[58:61], off
	global_store_dwordx4 v[52:53], v[62:65], off offset:256
	v_mov_b32_e32 v54, v46
	v_mov_b32_e32 v55, v38
	v_pk_mul_f32 v[54:55], v[54:55], v[68:69]
	v_add_u32_e32 v52, s8, v173
	v_add_f32_e32 v56, v54, v55
	v_mov_b32_e32 v54, v38
	v_mov_b32_e32 v55, v46
	v_pk_mul_f32 v[54:55], v[54:55], v[68:69]
	v_mov_b32_e32 v38, v47
	v_mov_b32_e32 v46, v39
	v_sub_f32_e32 v57, v54, v55
	v_pk_mul_f32 v[54:55], v[38:39], v[72:73]
	v_pk_mul_f32 v[38:39], v[46:47], v[72:73]
	v_add_f32_e32 v54, v54, v55
	v_sub_f32_e32 v46, v38, v39
	v_mov_b32_e32 v38, v48
	v_mov_b32_e32 v39, v40
	v_pk_mul_f32 v[38:39], v[38:39], v[74:75]
	v_ashrrev_i32_e32 v53, 31, v52
	v_add_f32_e32 v47, v38, v39
	v_mov_b32_e32 v38, v40
	v_mov_b32_e32 v39, v48
	v_pk_mul_f32 v[38:39], v[38:39], v[74:75]
	v_mov_b32_e32 v40, v49
	v_sub_f32_e32 v55, v38, v39
	v_pk_mul_f32 v[38:39], v[40:41], v[76:77]
	v_mov_b32_e32 v48, v41
	v_add_f32_e32 v40, v38, v39
	v_pk_mul_f32 v[38:39], v[48:49], v[76:77]
	v_lshlrev_b64 v[52:53], 9, v[52:53]
	v_sub_f32_e32 v41, v38, v39
	v_cvt_pk_bf16_f32 v39, v47, v40
	v_cvt_pk_bf16_f32 v47, v55, v41
	v_mov_b32_e32 v40, v42
	v_mov_b32_e32 v41, v34
	v_pk_mul_f32 v[40:41], v[40:41], v[78:79]
	v_cvt_pk_bf16_f32 v38, v56, v54
	v_cvt_pk_bf16_f32 v46, v57, v46
	s_nop 0
	v_add_f32_e32 v48, v40, v41
	v_mov_b32_e32 v40, v34
	v_mov_b32_e32 v41, v42
	v_pk_mul_f32 v[40:41], v[40:41], v[78:79]
	v_mov_b32_e32 v34, v43
	v_mov_b32_e32 v42, v35
	v_sub_f32_e32 v49, v40, v41
	v_pk_mul_f32 v[40:41], v[34:35], v[80:81]
	v_pk_mul_f32 v[34:35], v[42:43], v[80:81]
	v_add_f32_e32 v40, v40, v41
	v_sub_f32_e32 v42, v34, v35
	v_mov_b32_e32 v34, v44
	v_mov_b32_e32 v35, v36
	v_pk_mul_f32 v[34:35], v[34:35], v[50:51]
	v_cvt_pk_bf16_f32 v40, v48, v40
	v_cvt_pk_bf16_f32 v48, v49, v42
	s_nop 0
	v_add_f32_e32 v41, v34, v35
	v_mov_b32_e32 v34, v36
	v_mov_b32_e32 v35, v44
	v_pk_mul_f32 v[34:35], v[34:35], v[50:51]
	v_mov_b32_e32 v36, v45
	v_sub_f32_e32 v43, v34, v35
	v_pk_mul_f32 v[34:35], v[36:37], v[82:83]
	v_mov_b32_e32 v44, v37
	v_add_f32_e32 v36, v34, v35
	v_pk_mul_f32 v[34:35], v[44:45], v[82:83]
	v_cvt_pk_bf16_f32 v41, v41, v36
	s_nop 0
	v_sub_f32_e32 v34, v34, v35
	v_cvt_pk_bf16_f32 v49, v43, v34
	v_lshl_add_u64 v[34:35], v[140:141], 0, v[52:53]
	global_store_dwordx4 v[34:35], v[38:41], off
	global_store_dwordx4 v[34:35], v[46:49], off offset:256
	global_load_dwordx2 v[38:39], v[150:151], off
	s_nop 0
	global_load_dwordx2 v[36:37], v[152:153], off
	v_mov_b32_e32 v40, v30
	v_mov_b32_e32 v41, v26
	v_add_u32_e32 v34, s9, v174
	v_ashrrev_i32_e32 v35, 31, v34
	v_lshlrev_b64 v[34:35], 9, v[34:35]
	s_waitcnt vmcnt(0)
; __device__ __forceinline__ unsigned pk2(float lo, float hi) { unsigned r; asm("v_cvt_pk_bf16_f32 %0, %1, %2" : "=v"(r) : "v"(lo), "v"(hi)); return r; }
; #define PG8_WAIT_V(n) asm volatile("s_waitcnt vmcnt(" #n ")" ::: "memory")
; #define PG8_BAR __builtin_amdgcn_s_barrier()
; template <class Epi, class Sched>
; __device__ __forceinline__ void gemm_phase(LAS unsigned char* lds, const int K, const int lda, const int ldb, const Sched& S, const Epi& E) {
;     ...
;         if (!has_next) break;
; #pragma unroll
;         for (int a = 0; a < 2; ++a)
; #pragma unroll
;             for (int b = 0; b < 2; ++b)
; #pragma unroll
;                 for (int m = 0; m < 4; ++m)
; #pragma unroll
;                     for (int n = 0; n < 2; ++n) acc[a][b][m][n] = (f32x4){0.f, 0.f, 0.f, 0.f};
;         cur = nxt; cA = nA; cB = nB; ++ui;
;     }
;     PG8_WAIT_V(0);
;     if (wr == 0) PG8_BAR;
;     __device__ __forceinline__ void operator()(const Acc& acc, const Unit& u, int wr, int wc, int fr, int fq) const {
;         const int col0 = u.pn * BM + wc * 32 + 8 * fq;
; #pragma unroll
;         for (int m = 0; m < 4; ++m) { const int ka = wr * 64 + m * 16 + fr; const float2 st = tw[ka]; const float2 t0 = tw[ka * (col0 & 127)];
; #pragma unroll
;             for (int bj = 0; bj < 2; ++bj) { const int q = col0 + bj * HALF, n = q >> 7, l1 = q & 127;
;                 bf16_t* dst = Yp + ((size_t)(ka * 1024 + n) * 2) * 128 + l1;
;                 float2 t = t0;
;                 unsigned ow[4], pw[4];
; #pragma unroll
;                 for (int nn = 0; nn < 2; ++nn) {
;                     float yr[4], yi[4];
; #pragma unroll
;                     for (int e = 0; e < 4; ++e) { const float a = acc[0][bj][m][nn][e], b = acc[1][bj][m][nn][e];
;                         yr[e] = a * t.x + b * t.y; yi[e] = b * t.x - a * t.y;
;                         const float tx = t.x * st.x - t.y * st.y, ty = t.x * st.y + t.y * st.x; t.x = tx; t.y = ty; }
;                     ow[2 * nn] = pk2(yr[0], yr[1]); ow[2 * nn + 1] = pk2(yr[2], yr[3]);
;                     pw[2 * nn] = pk2(yi[0], yi[1]); pw[2 * nn + 1] = pk2(yi[2], yi[3]); }
;                 *(u32x4*)dst = (u32x4){ow[0], ow[1], ow[2], ow[3]}; *(u32x4*)(dst + 128) = (u32x4){pw[0], pw[1], pw[2], pw[3]};
;                 __builtin_amdgcn_sched_barrier(0); } }
	v_pk_mul_f32 v[40:41], v[40:41], v[36:37]
	s_nop 0
	v_add_f32_e32 v50, v40, v41
	v_mov_b32_e32 v40, v26
	v_mov_b32_e32 v41, v30
	v_pk_mul_f32 v[40:41], v[40:41], v[36:37]
	v_pk_mul_f32 v[42:43], v[38:39], v[36:37] op_sel:[1,0] op_sel_hi:[0,1]
	v_sub_f32_e32 v51, v40, v41
	v_pk_mul_f32 v[40:41], v[38:39], v[36:37]
	v_mov_b32_e32 v45, v42
	v_mov_b32_e32 v44, v40
	v_mov_b32_e32 v42, v41
	v_pk_add_f32 v[46:47], v[44:45], v[42:43] neg_lo:[0,1] neg_hi:[0,1]
	v_pk_add_f32 v[42:43], v[44:45], v[42:43]
	v_mov_b32_e32 v40, v46
	v_mov_b32_e32 v41, v43
	v_mov_b32_e32 v26, v31
	v_mov_b32_e32 v30, v27
	v_pk_mul_f32 v[44:45], v[26:27], v[40:41]
	v_pk_mul_f32 v[26:27], v[30:31], v[40:41]
	v_add_f32_e32 v52, v44, v45
	v_sub_f32_e32 v53, v26, v27
	v_pk_mul_f32 v[26:27], v[38:39], v[42:43] op_sel:[1,1] op_sel_hi:[0,1]
	v_pk_fma_f32 v[42:43], v[38:39], v[46:47], v[26:27] neg_lo:[0,0,1] neg_hi:[0,0,1]
	v_pk_fma_f32 v[26:27], v[38:39], v[46:47], v[26:27] op_sel_hi:[1,0,1]
	s_nop 0
	v_mov_b32_e32 v43, v27
	v_mov_b32_e32 v26, v32
	v_mov_b32_e32 v27, v28
	v_pk_mul_f32 v[26:27], v[26:27], v[42:43]
	v_pk_mul_f32 v[30:31], v[38:39], v[42:43] op_sel:[1,0] op_sel_hi:[0,1]
	v_add_f32_e32 v54, v26, v27
	v_mov_b32_e32 v26, v28
	v_mov_b32_e32 v27, v32
	v_pk_mul_f32 v[26:27], v[26:27], v[42:43]
	v_mov_b32_e32 v45, v30
	v_sub_f32_e32 v55, v26, v27
	v_pk_mul_f32 v[26:27], v[38:39], v[42:43]
	v_mov_b32_e32 v28, v33
	v_mov_b32_e32 v44, v26
	v_mov_b32_e32 v30, v27
	v_pk_add_f32 v[48:49], v[44:45], v[30:31] neg_lo:[0,1] neg_hi:[0,1]
	v_pk_add_f32 v[46:47], v[44:45], v[30:31]
	v_mov_b32_e32 v44, v48
	v_mov_b32_e32 v45, v47
	v_pk_mul_f32 v[26:27], v[28:29], v[44:45]
	v_mov_b32_e32 v32, v29
	v_add_f32_e32 v28, v26, v27
	v_pk_mul_f32 v[26:27], v[32:33], v[44:45]
	v_cvt_pk_bf16_f32 v30, v51, v53
	s_nop 0
	v_sub_f32_e32 v29, v26, v27
	v_cvt_pk_bf16_f32 v27, v54, v28
	v_cvt_pk_bf16_f32 v31, v55, v29
	v_pk_mul_f32 v[28:29], v[38:39], v[46:47] op_sel:[1,1] op_sel_hi:[0,1]
	v_pk_fma_f32 v[46:47], v[38:39], v[48:49], v[28:29] neg_lo:[0,0,1] neg_hi:[0,0,1]
	v_pk_fma_f32 v[28:29], v[38:39], v[48:49], v[28:29] op_sel_hi:[1,0,1]
	v_cvt_pk_bf16_f32 v26, v50, v52
	s_nop 0
	v_mov_b32_e32 v47, v29
	v_mov_b32_e32 v28, v22
	v_mov_b32_e32 v29, v18
	v_pk_mul_f32 v[28:29], v[28:29], v[46:47]
	v_pk_mul_f32 v[32:33], v[38:39], v[46:47] op_sel:[1,0] op_sel_hi:[0,1]
	v_add_f32_e32 v52, v28, v29
	v_mov_b32_e32 v28, v18
	v_mov_b32_e32 v29, v22
	v_pk_mul_f32 v[28:29], v[28:29], v[46:47]
	v_mov_b32_e32 v49, v32
	v_sub_f32_e32 v53, v28, v29
	v_pk_mul_f32 v[28:29], v[38:39], v[46:47]
	v_mov_b32_e32 v18, v23
	v_mov_b32_e32 v48, v28
	v_mov_b32_e32 v32, v29
	v_pk_add_f32 v[28:29], v[48:49], v[32:33] neg_lo:[0,1] neg_hi:[0,1]
	v_pk_add_f32 v[32:33], v[48:49], v[32:33]
	v_mov_b32_e32 v48, v28
	v_mov_b32_e32 v49, v33
	v_mov_b32_e32 v22, v19
	v_pk_mul_f32 v[50:51], v[18:19], v[48:49]
	v_pk_mul_f32 v[18:19], v[22:23], v[48:49]
	v_add_f32_e32 v54, v50, v51
	v_sub_f32_e32 v55, v18, v19
	v_pk_mul_f32 v[18:19], v[38:39], v[32:33] op_sel:[1,1] op_sel_hi:[0,1]
	v_pk_fma_f32 v[22:23], v[38:39], v[28:29], v[18:19] op_sel_hi:[1,0,1] neg_lo:[0,0,1] neg_hi:[0,0,1]
	v_pk_fma_f32 v[28:29], v[38:39], v[28:29], v[18:19] op_sel_hi:[1,0,1]
	v_mov_b32_e32 v18, v22
	v_mov_b32_e32 v19, v29
	v_mov_b32_e32 v32, v24
	v_mov_b32_e32 v33, v20
	v_pk_mul_f32 v[28:29], v[38:39], v[28:29] op_sel:[1,1] op_sel_hi:[0,1]
	v_pk_mul_f32 v[32:33], v[32:33], v[18:19]
	v_pk_fma_f32 v[50:51], v[38:39], v[22:23], v[28:29] neg_lo:[0,0,1] neg_hi:[0,0,1]
	v_pk_fma_f32 v[22:23], v[38:39], v[22:23], v[28:29] op_sel_hi:[1,0,1]
	v_add_f32_e32 v56, v32, v33
	v_mov_b32_e32 v32, v20
	v_mov_b32_e32 v33, v24
	v_mov_b32_e32 v51, v23
	v_mov_b32_e32 v20, v25
	v_mov_b32_e32 v24, v21
	v_pk_mul_f32 v[32:33], v[32:33], v[18:19]
	v_pk_mul_f32 v[22:23], v[20:21], v[50:51]
	v_pk_mul_f32 v[20:21], v[24:25], v[50:51]
	v_sub_f32_e32 v33, v32, v33
	v_sub_f32_e32 v20, v20, v21
	v_add_f32_e32 v22, v22, v23
	v_cvt_pk_bf16_f32 v28, v52, v54
	v_cvt_pk_bf16_f32 v29, v56, v22
	v_cvt_pk_bf16_f32 v33, v33, v20
	v_lshl_add_u64 v[20:21], v[140:141], 0, v[34:35]
	v_cvt_pk_bf16_f32 v32, v53, v55
	global_store_dwordx4 v[20:21], v[26:29], off
	global_store_dwordx4 v[20:21], v[30:33], off offset:256
	v_mov_b32_e32 v22, v14
	v_mov_b32_e32 v23, v6
	v_pk_mul_f32 v[22:23], v[22:23], v[36:37]
	v_add_u32_e32 v20, s8, v174
	v_add_f32_e32 v24, v22, v23
	v_mov_b32_e32 v22, v6
	v_mov_b32_e32 v23, v14
	v_pk_mul_f32 v[22:23], v[22:23], v[36:37]
	v_mov_b32_e32 v6, v15
	v_mov_b32_e32 v14, v7
	v_sub_f32_e32 v25, v22, v23
	v_pk_mul_f32 v[22:23], v[6:7], v[40:41]
	v_pk_mul_f32 v[6:7], v[14:15], v[40:41]
	v_add_f32_e32 v22, v22, v23
	v_sub_f32_e32 v14, v6, v7
	v_mov_b32_e32 v6, v16
	v_mov_b32_e32 v7, v8
	v_pk_mul_f32 v[6:7], v[6:7], v[42:43]
	v_ashrrev_i32_e32 v21, 31, v20
	v_add_f32_e32 v15, v6, v7
	v_mov_b32_e32 v6, v8
	v_mov_b32_e32 v7, v16
	v_pk_mul_f32 v[6:7], v[6:7], v[42:43]
	v_mov_b32_e32 v8, v17
	v_sub_f32_e32 v23, v6, v7
	v_pk_mul_f32 v[6:7], v[8:9], v[44:45]
	v_mov_b32_e32 v16, v9
	v_add_f32_e32 v8, v6, v7
	v_pk_mul_f32 v[6:7], v[16:17], v[44:45]
	v_lshlrev_b64 v[20:21], 9, v[20:21]
	v_sub_f32_e32 v9, v6, v7
	v_cvt_pk_bf16_f32 v7, v15, v8
	v_cvt_pk_bf16_f32 v15, v23, v9
	v_mov_b32_e32 v8, v10
	v_mov_b32_e32 v9, v2
	v_pk_mul_f32 v[8:9], v[8:9], v[46:47]
	v_cvt_pk_bf16_f32 v6, v24, v22
	v_cvt_pk_bf16_f32 v14, v25, v14
	s_nop 0
	v_add_f32_e32 v16, v8, v9
	v_mov_b32_e32 v8, v2
	v_mov_b32_e32 v9, v10
	v_pk_mul_f32 v[8:9], v[8:9], v[46:47]
	v_mov_b32_e32 v2, v11
	v_mov_b32_e32 v10, v3
	v_sub_f32_e32 v17, v8, v9
	v_pk_mul_f32 v[8:9], v[2:3], v[48:49]
	v_pk_mul_f32 v[2:3], v[10:11], v[48:49]
	v_add_f32_e32 v8, v8, v9
	v_sub_f32_e32 v10, v2, v3
	v_mov_b32_e32 v2, v12
	v_mov_b32_e32 v3, v4
	v_pk_mul_f32 v[2:3], v[2:3], v[18:19]
	v_cvt_pk_bf16_f32 v8, v16, v8
	v_cvt_pk_bf16_f32 v16, v17, v10
	s_nop 0
	v_add_f32_e32 v9, v2, v3
	v_mov_b32_e32 v2, v4
	v_mov_b32_e32 v3, v12
	v_pk_mul_f32 v[2:3], v[2:3], v[18:19]
	v_mov_b32_e32 v4, v13
	v_sub_f32_e32 v11, v2, v3
	v_pk_mul_f32 v[2:3], v[4:5], v[50:51]
	v_mov_b32_e32 v12, v5
	v_add_f32_e32 v4, v2, v3
	v_pk_mul_f32 v[2:3], v[12:13], v[50:51]
	v_cvt_pk_bf16_f32 v9, v9, v4
	s_nop 0
	v_sub_f32_e32 v2, v2, v3
	v_cvt_pk_bf16_f32 v17, v11, v2
	v_lshl_add_u64 v[2:3], v[140:141], 0, v[20:21]
	global_store_dwordx4 v[2:3], v[6:9], off
	global_store_dwordx4 v[2:3], v[14:17], off offset:256
	s_and_b64 vcc, exec, s[0:1]
	s_mov_b32 s30, s60
	s_mov_b64 s[10:11], s[6:7]
	s_mov_b64 s[8:9], s[4:5]
	s_cbranch_vccnz .Lgx_d_exit
	s_cmpk_gt_u32 s39, 0xff
	s_cbranch_scc0 .LBB0_948
	s_barrier
	s_branch .LBB0_948
.Lgx_d_exit:
	s_waitcnt vmcnt(0)
	v_readlane_b32 s60, v253, 19
	s_cmpk_gt_u32 s39, 0xff
	v_readlane_b32 s61, v253, 20
	s_movk_i32 s48, 0x7000
	s_mov_b32 s47, s94

; template <class Epi, class Sched>
; __device__ __forceinline__ void gemm_phase(LAS unsigned char* lds, const int K, const int lda, const int ldb, const Sched& S, const Epi& E) {
;     ...
; #pragma unroll
;         for (int a = 0; a < 2; ++a)
; #pragma unroll
;             for (int b = 0; b < 2; ++b)
; #pragma unroll
;                 for (int m = 0; m < 4; ++m)
; #pragma unroll
;                     for (int n = 0; n < 2; ++n) acc[a][b][m][n] = (f32x4){0.f, 0.f, 0.f, 0.f};
;         cur = nxt; cA = nA; cB = nB; ++ui;
.LBB0_968:
	s_add_u32 s14, s14, 0x40080
	s_addc_u32 s15, s15, 0
	s_add_u32 s1, s16, 0x100
	v_mov_b32_e32 v2, 0
	s_addc_u32 s7, s17, 0
	s_mov_b32 s9, -2
	v_mov_b32_e32 v3, v2
	v_mov_b64_e32 v[4:5], 0
	v_mov_b64_e32 v[6:7], 0
	v_mov_b64_e32 v[8:9], 0
	v_mov_b64_e32 v[18:19], 0
	v_mov_b64_e32 v[20:21], 0
	v_mov_b64_e32 v[22:23], 0
	v_mov_b64_e32 v[24:25], 0
	v_mov_b64_e32 v[34:35], 0
	v_mov_b64_e32 v[36:37], 0
	v_mov_b64_e32 v[38:39], 0
	v_mov_b64_e32 v[40:41], 0
	v_mov_b64_e32 v[50:51], 0
	v_mov_b64_e32 v[52:53], 0
	v_mov_b64_e32 v[54:55], 0
	v_mov_b64_e32 v[56:57], 0
	v_mov_b64_e32 v[10:11], 0
	v_mov_b64_e32 v[12:13], 0
	v_mov_b64_e32 v[14:15], 0
	v_mov_b64_e32 v[16:17], 0
	v_mov_b64_e32 v[26:27], 0
	v_mov_b64_e32 v[28:29], 0
	v_mov_b64_e32 v[30:31], 0
	v_mov_b64_e32 v[32:33], 0
	v_mov_b64_e32 v[42:43], 0
	v_mov_b64_e32 v[44:45], 0
	v_mov_b64_e32 v[46:47], 0
	v_mov_b64_e32 v[48:49], 0
	v_mov_b64_e32 v[58:59], 0
	v_mov_b64_e32 v[60:61], 0
	v_mov_b64_e32 v[62:63], 0
	v_mov_b64_e32 v[64:65], 0
	v_mov_b64_e32 v[66:67], 0
	v_mov_b64_e32 v[68:69], 0
	v_mov_b64_e32 v[70:71], 0
	v_mov_b64_e32 v[72:73], 0
	v_mov_b64_e32 v[82:83], 0
	v_mov_b64_e32 v[84:85], 0
	v_mov_b64_e32 v[86:87], 0
	v_mov_b64_e32 v[88:89], 0
	v_mov_b64_e32 v[98:99], 0
	v_mov_b64_e32 v[100:101], 0
	v_mov_b64_e32 v[102:103], 0
	v_mov_b64_e32 v[104:105], 0
	v_mov_b64_e32 v[114:115], 0
	v_mov_b64_e32 v[116:117], 0
	v_mov_b64_e32 v[118:119], 0
	v_mov_b64_e32 v[120:121], 0
	v_mov_b64_e32 v[74:75], 0
	v_mov_b64_e32 v[76:77], 0
	v_mov_b64_e32 v[78:79], 0
	v_mov_b64_e32 v[80:81], 0
	v_mov_b64_e32 v[90:91], 0
	v_mov_b64_e32 v[92:93], 0
	v_mov_b64_e32 v[94:95], 0
	v_mov_b64_e32 v[96:97], 0
	v_mov_b64_e32 v[106:107], 0
	v_mov_b64_e32 v[108:109], 0
	v_mov_b64_e32 v[110:111], 0
	v_mov_b64_e32 v[112:113], 0
	v_mov_b64_e32 v[122:123], 0
	v_mov_b64_e32 v[124:125], 0
	v_mov_b64_e32 v[126:127], 0
	v_mov_b64_e32 v[128:129], 0
